# v44 + flat->global stores/atomics in GEMM epilogues + nt on G1e/G1o/G3 output stores
# speedup vs baseline: 1.0138x; 1.0042x over previous
; __device__ __forceinline__ float ss2f(unsigned long long v) { return (float)v * (1.0f / 16777216.0f); }
; __device__ __forceinline__ f32x2 gelu_pk(f32x2 v) {
;     const f32x2 av = __builtin_elementwise_abs(v), d = av * 0.2316418882f + 1.0f;
;     f32x2 t; t.x = __builtin_amdgcn_rcpf(d.x); t.y = __builtin_amdgcn_rcpf(d.y);
;     f32x2 q = t * 0.5307027145f + (-0.7265760135f); q = q * t + 0.7107068705f; q = q * t + (-0.142248368f); q = q * t + 0.127414796f; q = q * t;
;     const f32x2 s = (v * v) * (-0.72134752044f);
;     f32x2 e; e.x = __builtin_amdgcn_exp2f(s.x); e.y = __builtin_amdgcn_exp2f(s.y);
;     const f32x2 m = v * (q * e), r = v - m;
;     f32x2 o; o.x = v.x < 0.f ? m.x : r.x; o.y = v.y < 0.f ? m.y : r.y; return o;
; __device__ __forceinline__ void rstd8(float (&r)[8], const PreSS& p, int fr) {
;     const float a = __builtin_amdgcn_rsqf(ss2f(p.v0) * (1.0f / 1024.0f) + RMS_EPS), b = __builtin_amdgcn_rsqf(ss2f(p.v1) * (1.0f / 1024.0f) + RMS_EPS);
; #pragma unroll
;     for (int k = 0; k < 8; ++k) r[k] = __shfl((k & 1) ? b : a, fr + 16 * (k >> 1));
; }
.LBB0_57:
	s_waitcnt vmcnt(8)
	v_ffbh_u32_e32 v154, v153
	v_min_u32_e32 v154, 32, v154
	v_lshlrev_b64 v[152:153], v154, v[152:153]
	v_min_u32_e32 v152, 1, v152
	v_or_b32_e32 v152, v153, v152
	v_cvt_f32_u32_e32 v152, v152
	v_sub_u32_e32 v153, 32, v154
	s_mov_b32 s8, 0x3e6d3388
	s_cmp_gt_i32 s4, 3
	v_ldexp_f32 v152, v152, v153
	v_ffbh_u32_e32 v153, v147
	v_min_u32_e32 v153, 32, v153
	v_lshlrev_b64 v[146:147], v153, v[146:147]
	v_min_u32_e32 v146, 1, v146
	v_or_b32_e32 v146, v147, v146
	v_cvt_f32_u32_e32 v146, v146
	v_mul_f32_e32 v152, 0x33800000, v152
	v_fmamk_f32 v152, v152, 0x3a800000, v233
	v_rsq_f32_e32 v152, v152
	v_sub_u32_e32 v147, 32, v153
	v_ldexp_f32 v146, v146, v147
	v_and_b32_e32 v147, 64, v236
	v_or_b32_e32 v153, v147, v145
	v_lshlrev_b32_e32 v153, 2, v153
	ds_bpermute_b32 v168, v153, v152
	v_mul_f32_e32 v146, 0x33800000, v146
	v_fmamk_f32 v146, v146, 0x3a800000, v233
	v_rsq_f32_e32 v146, v146
	s_mov_b32 s12, 0xbf3a00e3
	s_waitcnt lgkmcnt(0)
	v_pk_mul_f32 v[124:125], v[124:125], v[168:169] op_sel_hi:[1,0]
	v_pk_mul_f32 v[170:171], v[120:121], v[168:169] op_sel_hi:[1,0]
	v_and_b32_e32 v121, 0x7fffffff, v125
	v_and_b32_e32 v120, 0x7fffffff, v124
	v_pk_fma_f32 v[120:121], v[120:121], s[8:9], 1.0 op_sel_hi:[1,0,0]
	v_lshl_or_b32 v162, s4, 8, v159
	v_rcp_f32_e32 v172, v120
	v_rcp_f32_e32 v173, v121
	s_cselect_b64 s[64:65], -1, 0
	s_cmp_lt_i32 s4, 4
	v_mov_b64_e32 v[120:121], s[12:13]
	s_mov_b32 s10, 0x3f07dc22
	v_pk_mul_f32 v[176:177], v[124:125], v[124:125]
	s_mov_b32 s4, 0xbf38aa3b
	v_pk_fma_f32 v[174:175], v[172:173], s[10:11], v[120:121] op_sel_hi:[1,0,0]
	s_mov_b32 s14, 0x3f35f0e3
	v_pk_mul_f32 v[176:177], v[176:177], s[4:5] op_sel_hi:[1,0]
	v_pk_fma_f32 v[174:175], v[172:173], v[174:175], s[14:15] op_sel_hi:[1,1,0]
	s_mov_b32 s36, 0xbe11a98e
	v_exp_f32_e32 v176, v176
	v_exp_f32_e32 v177, v177
	ds_bpermute_b32 v166, v153, v146
	ds_bpermute_b32 v164, v153, v152 offset:64
	ds_bpermute_b32 v160, v153, v146 offset:64
	ds_bpermute_b32 v158, v153, v152 offset:128
	ds_bpermute_b32 v156, v153, v146 offset:128
	ds_bpermute_b32 v154, v153, v152 offset:192
	ds_bpermute_b32 v146, v153, v146 offset:192
	v_xor_b32_e32 v152, 16, v236
	v_add_u32_e32 v153, 64, v147
	v_pk_fma_f32 v[174:175], v[172:173], v[174:175], s[36:37] op_sel_hi:[1,1,0]
	s_mov_b32 s66, 0x3e027906
	v_cmp_lt_i32_e32 vcc, v152, v153
	v_pk_fma_f32 v[174:175], v[172:173], v[174:175], s[66:67] op_sel_hi:[1,1,0]
	v_pk_mul_f32 v[126:127], v[126:127], v[168:169] op_sel_hi:[1,0]
	v_cndmask_b32_e32 v147, v236, v152, vcc
	v_xor_b32_e32 v152, 32, v236
	v_pk_mul_f32 v[172:173], v[172:173], v[174:175]
	v_cmp_lt_i32_e32 vcc, v152, v153
	v_pk_mul_f32 v[172:173], v[176:177], v[172:173]
	v_pk_mul_f32 v[174:175], v[126:127], v[126:127]
	v_cndmask_b32_e32 v152, v236, v152, vcc
	v_pk_mul_f32 v[176:177], v[124:125], v[172:173]
	v_pk_fma_f32 v[172:173], v[124:125], v[172:173], v[124:125] neg_lo:[1,0,0] neg_hi:[1,0,0]
	v_cmp_gt_f32_e32 vcc, 0, v124
	v_pk_mul_f32 v[174:175], v[174:175], s[4:5] op_sel_hi:[1,0]
	v_pk_mul_f32 v[122:123], v[122:123], v[168:169] op_sel_hi:[1,0]
	v_cndmask_b32_e32 v124, v172, v176, vcc
	v_cmp_gt_f32_e32 vcc, 0, v125
	v_and_b32_e32 v172, 0x7fffffff, v126
	v_exp_f32_e32 v174, v174
	v_cndmask_b32_e32 v125, v173, v177, vcc
	v_and_b32_e32 v173, 0x7fffffff, v127
	v_pk_fma_f32 v[172:173], v[172:173], s[8:9], 1.0 op_sel_hi:[1,0,0]
	v_exp_f32_e32 v175, v175
	v_rcp_f32_e32 v172, v172
	v_rcp_f32_e32 v173, v173
	v_cmp_gt_f32_e32 vcc, 0, v126
	v_lshlrev_b32_e32 v165, 2, v152
	v_lshlrev_b64 v[152:153], 12, v[142:143]
	v_pk_fma_f32 v[176:177], v[172:173], s[10:11], v[120:121] op_sel_hi:[1,0,0]
	v_ashrrev_i32_e32 v163, 31, v162
	v_pk_fma_f32 v[176:177], v[172:173], v[176:177], s[14:15] op_sel_hi:[1,1,0]
	v_lshl_add_u64 v[152:153], s[30:31], 0, v[152:153]
	v_pk_fma_f32 v[176:177], v[172:173], v[176:177], s[36:37] op_sel_hi:[1,1,0]
	v_lshl_add_u64 v[152:153], v[162:163], 1, v[152:153]
	v_pk_fma_f32 v[176:177], v[172:173], v[176:177], s[66:67] op_sel_hi:[1,1,0]
	v_lshlrev_b32_e32 v147, 2, v147
	v_pk_mul_f32 v[172:173], v[172:173], v[176:177]
	v_pk_mul_f32 v[176:177], v[170:171], v[170:171]
	v_pk_mul_f32 v[172:173], v[174:175], v[172:173]
	v_pk_mul_f32 v[176:177], v[176:177], s[4:5] op_sel_hi:[1,0]
	v_pk_mul_f32 v[174:175], v[126:127], v[172:173]
	v_pk_fma_f32 v[172:173], v[126:127], v[172:173], v[126:127] neg_lo:[1,0,0] neg_hi:[1,0,0]
	v_exp_f32_e32 v176, v176
	v_cndmask_b32_e32 v126, v172, v174, vcc
	v_cmp_gt_f32_e32 vcc, 0, v127
	v_and_b32_e32 v172, 0x7fffffff, v170
	v_exp_f32_e32 v177, v177
	v_cndmask_b32_e32 v127, v173, v175, vcc
	v_and_b32_e32 v173, 0x7fffffff, v171
	v_pk_fma_f32 v[172:173], v[172:173], s[8:9], 1.0 op_sel_hi:[1,0,0]
	v_cmp_gt_f32_e32 vcc, 0, v170
	v_rcp_f32_e32 v172, v172
	v_rcp_f32_e32 v173, v173
	v_readlane_b32 s76, v255, 14
	v_readlane_b32 s77, v255, 15
	v_pk_fma_f32 v[174:175], v[172:173], s[10:11], v[120:121] op_sel_hi:[1,0,0]
	s_nop 0
	v_pk_fma_f32 v[174:175], v[172:173], v[174:175], s[14:15] op_sel_hi:[1,1,0]
	s_nop 0
	v_pk_fma_f32 v[174:175], v[172:173], v[174:175], s[36:37] op_sel_hi:[1,1,0]
	s_nop 0
	v_pk_fma_f32 v[174:175], v[172:173], v[174:175], s[66:67] op_sel_hi:[1,1,0]
	s_nop 0
	v_pk_mul_f32 v[172:173], v[172:173], v[174:175]
	v_pk_mul_f32 v[174:175], v[122:123], v[122:123]
	v_pk_mul_f32 v[172:173], v[176:177], v[172:173]
	s_nop 0
	v_pk_mul_f32 v[176:177], v[170:171], v[172:173]
	v_pk_fma_f32 v[172:173], v[170:171], v[172:173], v[170:171] neg_lo:[1,0,0] neg_hi:[1,0,0]
	v_and_b32_e32 v170, 0x7fffffff, v122
	v_cndmask_b32_e32 v167, v172, v176, vcc
	v_cmp_gt_f32_e32 vcc, 0, v171
	v_and_b32_e32 v171, 0x7fffffff, v123
	v_pk_fma_f32 v[170:171], v[170:171], s[8:9], 1.0 op_sel_hi:[1,0,0]
; __device__ __forceinline__ u32x4 pack8(f32x4 v0, f32x4 v1) { u32x4 w; w.x = cvt_pk_bf16(v0[0], v0[1]); w.y = cvt_pk_bf16(v0[2], v0[3]); w.z = cvt_pk_bf16(v1[0], v1[1]); w.w = cvt_pk_bf16(v1[2], v1[3]); return w; }
; __device__ __forceinline__ f32x2 gelu_pk(f32x2 v) {
;     const f32x2 av = __builtin_elementwise_abs(v), d = av * 0.2316418882f + 1.0f;
;     f32x2 t; t.x = __builtin_amdgcn_rcpf(d.x); t.y = __builtin_amdgcn_rcpf(d.y);
;     f32x2 q = t * 0.5307027145f + (-0.7265760135f); q = q * t + 0.7107068705f; q = q * t + (-0.142248368f); q = q * t + 0.127414796f; q = q * t;
;     const f32x2 s = (v * v) * (-0.72134752044f);
;     f32x2 e; e.x = __builtin_amdgcn_exp2f(s.x); e.y = __builtin_amdgcn_exp2f(s.y);
;     const f32x2 m = v * (q * e), r = v - m;
;     f32x2 o; o.x = v.x < 0.f ? m.x : r.x; o.y = v.y < 0.f ? m.y : r.y; return o;
;     __device__ __forceinline__ void operator()(const f32x4 (&acc)[2][2][4][2], const Unit& u, int wr, int wc, int fr, int fq, const Pre& pre) const {
;     ...
;                 for (int bj = 0; bj < 2; ++bj) { f32x4 v0 = acc[ai][bj][m][0] * r, v1 = acc[ai][bj][m][1] * r;
;                     f32x2 a = gelu_pk((f32x2){v0[0], v0[1]}), b = gelu_pk((f32x2){v0[2], v0[3]}), c = gelu_pk((f32x2){v1[0], v1[1]}), d = gelu_pk((f32x2){v1[2], v1[3]});
;                     v0 = (f32x4){a.x, a.y, b.x, b.y}; v1 = (f32x4){c.x, c.y, d.x, d.y};
;                     sq += (v0[0] * v0[0] + v0[1] * v0[1]) + (v0[2] * v0[2] + v0[3] * v0[3]) + (v1[0] * v1[0] + v1[1] * v1[1]) + (v1[2] * v1[2] + v1[3] * v1[3]);
;                     *(u32x4*)(rowp + bj * HALF) = pack8(v0, v1); }
	v_cndmask_b32_e32 v169, v173, v177, vcc
	v_rcp_f32_e32 v170, v170
	v_rcp_f32_e32 v171, v171
	v_cmp_gt_f32_e32 vcc, 0, v122
	v_pk_mul_f32 v[116:117], v[116:117], v[168:169] op_sel_hi:[1,0]
	v_pk_mul_f32 v[118:119], v[118:119], v[168:169] op_sel_hi:[1,0]
	v_pk_fma_f32 v[172:173], v[170:171], s[10:11], v[120:121] op_sel_hi:[1,0,0]
	v_pk_mul_f32 v[114:115], v[114:115], v[168:169] op_sel_hi:[1,0]
	v_pk_fma_f32 v[172:173], v[170:171], v[172:173], s[14:15] op_sel_hi:[1,1,0]
	s_nop 0
	v_pk_fma_f32 v[172:173], v[170:171], v[172:173], s[36:37] op_sel_hi:[1,1,0]
	s_nop 0
	v_pk_fma_f32 v[172:173], v[170:171], v[172:173], s[66:67] op_sel_hi:[1,1,0]
	s_nop 0
	v_pk_mul_f32 v[170:171], v[170:171], v[172:173]
	v_pk_mul_f32 v[172:173], v[174:175], s[4:5] op_sel_hi:[1,0]
	v_pk_mul_f32 v[174:175], v[116:117], v[116:117]
	v_exp_f32_e32 v172, v172
	v_exp_f32_e32 v173, v173
	v_pk_mul_f32 v[174:175], v[174:175], s[4:5] op_sel_hi:[1,0]
	v_pk_mul_f32 v[170:171], v[172:173], v[170:171]
	s_nop 0
	v_pk_mul_f32 v[172:173], v[122:123], v[170:171]
	v_pk_fma_f32 v[170:171], v[122:123], v[170:171], v[122:123] neg_lo:[1,0,0] neg_hi:[1,0,0]
	v_exp_f32_e32 v174, v174
	v_cndmask_b32_e32 v122, v170, v172, vcc
	v_cmp_gt_f32_e32 vcc, 0, v123
	v_cvt_pk_bf16_f32 v170, v124, v125
	v_exp_f32_e32 v175, v175
	s_nop 0
	v_cndmask_b32_e32 v123, v171, v173, vcc
	v_cvt_pk_bf16_f32 v171, v126, v127
	v_cvt_pk_bf16_f32 v172, v167, v169
	v_cvt_pk_bf16_f32 v173, v122, v123
	global_store_dwordx4 v[152:153], v[170:173], off nt
	v_cmp_gt_f32_e32 vcc, 0, v116
	s_nop 0
	v_pk_mul_f32 v[170:171], v[112:113], v[168:169] op_sel_hi:[1,0]
	v_and_b32_e32 v113, 0x7fffffff, v117
	v_and_b32_e32 v112, 0x7fffffff, v116
	v_pk_fma_f32 v[112:113], v[112:113], s[8:9], 1.0 op_sel_hi:[1,0,0]
	s_nop 0
	v_rcp_f32_e32 v112, v112
	v_rcp_f32_e32 v113, v113
	s_nop 0
	v_pk_fma_f32 v[172:173], v[112:113], s[10:11], v[120:121] op_sel_hi:[1,0,0]
	s_nop 0
	v_pk_fma_f32 v[172:173], v[112:113], v[172:173], s[14:15] op_sel_hi:[1,1,0]
	s_nop 0
	v_pk_fma_f32 v[172:173], v[112:113], v[172:173], s[36:37] op_sel_hi:[1,1,0]
	s_nop 0
	v_pk_fma_f32 v[172:173], v[112:113], v[172:173], s[66:67] op_sel_hi:[1,1,0]
	s_nop 0
	v_pk_mul_f32 v[112:113], v[112:113], v[172:173]
	v_pk_mul_f32 v[172:173], v[118:119], v[118:119]
	v_pk_mul_f32 v[112:113], v[174:175], v[112:113]
	v_pk_mul_f32 v[172:173], v[172:173], s[4:5] op_sel_hi:[1,0]
	v_pk_mul_f32 v[174:175], v[116:117], v[112:113]
	v_pk_fma_f32 v[112:113], v[116:117], v[112:113], v[116:117] neg_lo:[1,0,0] neg_hi:[1,0,0]
	v_and_b32_e32 v116, 0x7fffffff, v118
	v_cndmask_b32_e32 v112, v112, v174, vcc
	v_cmp_gt_f32_e32 vcc, 0, v117
	v_and_b32_e32 v117, 0x7fffffff, v119
	v_pk_fma_f32 v[116:117], v[116:117], s[8:9], 1.0 op_sel_hi:[1,0,0]
	v_cndmask_b32_e32 v113, v113, v175, vcc
	v_rcp_f32_e32 v116, v116
	v_rcp_f32_e32 v117, v117
	v_exp_f32_e32 v172, v172
	v_exp_f32_e32 v173, v173
	v_cmp_gt_f32_e32 vcc, 0, v118
	v_pk_fma_f32 v[174:175], v[116:117], s[10:11], v[120:121] op_sel_hi:[1,0,0]
	s_nop 0
	v_pk_fma_f32 v[174:175], v[116:117], v[174:175], s[14:15] op_sel_hi:[1,1,0]
	s_nop 0
	v_pk_fma_f32 v[174:175], v[116:117], v[174:175], s[36:37] op_sel_hi:[1,1,0]
	s_nop 0
	v_pk_fma_f32 v[174:175], v[116:117], v[174:175], s[66:67] op_sel_hi:[1,1,0]
	s_nop 0
	v_pk_mul_f32 v[116:117], v[116:117], v[174:175]
	v_pk_mul_f32 v[174:175], v[170:171], v[170:171]
	v_pk_mul_f32 v[116:117], v[172:173], v[116:117]
	v_pk_mul_f32 v[174:175], v[174:175], s[4:5] op_sel_hi:[1,0]
	v_pk_mul_f32 v[172:173], v[118:119], v[116:117]
	v_pk_fma_f32 v[116:117], v[118:119], v[116:117], v[118:119] neg_lo:[1,0,0] neg_hi:[1,0,0]
	v_and_b32_e32 v118, 0x7fffffff, v170
	v_cndmask_b32_e32 v116, v116, v172, vcc
	v_cmp_gt_f32_e32 vcc, 0, v119
	v_and_b32_e32 v119, 0x7fffffff, v171
	v_pk_fma_f32 v[118:119], v[118:119], s[8:9], 1.0 op_sel_hi:[1,0,0]
	v_cndmask_b32_e32 v117, v117, v173, vcc
	v_rcp_f32_e32 v118, v118
	v_rcp_f32_e32 v119, v119
	v_exp_f32_e32 v174, v174
	v_exp_f32_e32 v175, v175
	v_cmp_gt_f32_e32 vcc, 0, v170
	v_pk_fma_f32 v[172:173], v[118:119], s[10:11], v[120:121] op_sel_hi:[1,0,0]
	s_nop 0
	v_pk_fma_f32 v[172:173], v[118:119], v[172:173], s[14:15] op_sel_hi:[1,1,0]
	s_nop 0
	v_pk_fma_f32 v[172:173], v[118:119], v[172:173], s[36:37] op_sel_hi:[1,1,0]
	s_nop 0
	v_pk_fma_f32 v[172:173], v[118:119], v[172:173], s[66:67] op_sel_hi:[1,1,0]
	s_nop 0
	v_pk_mul_f32 v[118:119], v[118:119], v[172:173]
	v_pk_mul_f32 v[172:173], v[114:115], v[114:115]
	v_pk_mul_f32 v[118:119], v[174:175], v[118:119]
	s_nop 0
	v_pk_mul_f32 v[174:175], v[170:171], v[118:119]
	v_pk_fma_f32 v[118:119], v[170:171], v[118:119], v[170:171] neg_lo:[1,0,0] neg_hi:[1,0,0]
	v_and_b32_e32 v170, 0x7fffffff, v114
	v_cndmask_b32_e32 v118, v118, v174, vcc
	v_cmp_gt_f32_e32 vcc, 0, v171
	v_and_b32_e32 v171, 0x7fffffff, v115
	v_pk_fma_f32 v[170:171], v[170:171], s[8:9], 1.0 op_sel_hi:[1,0,0]
	v_cndmask_b32_e32 v119, v119, v175, vcc
	v_rcp_f32_e32 v170, v170
	v_rcp_f32_e32 v171, v171
	v_cmp_gt_f32_e32 vcc, 0, v114
	v_pk_fma_f32 v[120:121], v[170:171], s[10:11], v[120:121] op_sel_hi:[1,0,0]
	s_nop 0
	v_pk_fma_f32 v[120:121], v[170:171], v[120:121], s[14:15] op_sel_hi:[1,1,0]
	s_nop 0
	v_pk_fma_f32 v[120:121], v[170:171], v[120:121], s[36:37] op_sel_hi:[1,1,0]
	s_nop 0
	v_pk_fma_f32 v[120:121], v[170:171], v[120:121], s[66:67] op_sel_hi:[1,1,0]
	s_nop 0
	v_pk_mul_f32 v[120:121], v[170:171], v[120:121]
	v_pk_mul_f32 v[170:171], v[172:173], s[4:5] op_sel_hi:[1,0]
	s_nop 0
	v_exp_f32_e32 v170, v170
	v_exp_f32_e32 v171, v171
	s_nop 0
	v_pk_mul_f32 v[120:121], v[170:171], v[120:121]
	s_nop 0
	v_pk_mul_f32 v[170:171], v[114:115], v[120:121]
	v_pk_fma_f32 v[120:121], v[114:115], v[120:121], v[114:115] neg_lo:[1,0,0] neg_hi:[1,0,0]
	s_nop 0
	v_cndmask_b32_e32 v114, v120, v170, vcc
	v_cmp_gt_f32_e32 vcc, 0, v115
	v_cvt_pk_bf16_f32 v170, v112, v113
	s_nop 1
	v_cndmask_b32_e32 v115, v121, v171, vcc
	v_cvt_pk_bf16_f32 v171, v116, v117
	v_cvt_pk_bf16_f32 v172, v118, v119
	v_cvt_pk_bf16_f32 v173, v114, v115
	global_store_dwordx4 v[152:153], v[170:173], off offset:256 nt
	s_cbranch_scc1 .LBB0_61
; __device__ __forceinline__ unsigned long long f2ss(float v) { return (unsigned long long)(v * 16777216.0f); }
; __device__ __forceinline__ u32x4 pack8(f32x4 v0, f32x4 v1) { u32x4 w; w.x = cvt_pk_bf16(v0[0], v0[1]); w.y = cvt_pk_bf16(v0[2], v0[3]); w.z = cvt_pk_bf16(v1[0], v1[1]); w.w = cvt_pk_bf16(v1[2], v1[3]); return w; }
;     __device__ __forceinline__ void operator()(const f32x4 (&acc)[2][2][4][2], const Unit& u, int wr, int wc, int fr, int fq, const Pre& pre) const {
;     ...
;                     sq += (v0[0] * v0[0] + v0[1] * v0[1]) + (v0[2] * v0[2] + v0[3] * v0[3]) + (v1[0] * v1[0] + v1[1] * v1[1]) + (v1[2] * v1[2] + v1[3] * v1[3]);
;                     *(u32x4*)(rowp + bj * HALF) = pack8(v0, v1); }
;                 if (isv) { sq += __shfl_xor(sq, 16); sq += __shfl_xor(sq, 32); if (fq == 0) atomicAdd(vss + row, f2ss(sq)); } }
	v_mul_f32_e32 v120, v123, v123
	v_mul_f32_e32 v113, v113, v113
	v_fmac_f32_e32 v120, v122, v122
	v_mul_f32_e32 v121, v125, v125
	v_mul_f32_e32 v122, v127, v127
	v_fmac_f32_e32 v113, v112, v112
	v_mul_f32_e32 v112, v117, v117
	v_fmac_f32_e32 v121, v124, v124
	v_fmac_f32_e32 v122, v126, v126
	v_fmac_f32_e32 v112, v116, v116
	v_add_f32_e32 v121, v121, v122
	v_mul_f32_e32 v122, v169, v169
	v_add_f32_e32 v112, v113, v112
	v_mul_f32_e32 v113, v119, v119
	v_fmac_f32_e32 v122, v167, v167
	v_mul_f32_e32 v115, v115, v115
	v_fmac_f32_e32 v113, v118, v118
	v_add_f32_e32 v121, v122, v121
	v_fmac_f32_e32 v115, v114, v114
	v_add_f32_e32 v112, v113, v112
	v_add_f32_e32 v120, v120, v121
	v_add_f32_e32 v112, v115, v112
	v_add_f32_e32 v112, v120, v112
	ds_bpermute_b32 v113, v147, v112
	s_waitcnt lgkmcnt(0)
	v_add_f32_e32 v112, v112, v113
	ds_bpermute_b32 v113, v165, v112
	s_and_saveexec_b64 s[26:27], s[40:41]
	s_cbranch_execz .LBB0_60
	s_waitcnt lgkmcnt(0)
	v_add_f32_e32 v112, v112, v113
	v_mul_f32_e32 v112, 0x4b800000, v112
	v_trunc_f32_e32 v112, v112
	v_mul_f32_e32 v113, 0x2f800000, v112
	v_floor_f32_e32 v113, v113
	v_fmac_f32_e32 v112, 0xcf800000, v113
	v_cvt_u32_f32_e32 v112, v112
	v_cvt_u32_f32_e32 v113, v113
	v_lshl_add_u64 v[114:115], v[142:143], 3, s[52:53]
	global_atomic_add_x2 v[114:115], v[112:113], off

; __device__ __forceinline__ u32x4 pack8(f32x4 v0, f32x4 v1) { u32x4 w; w.x = cvt_pk_bf16(v0[0], v0[1]); w.y = cvt_pk_bf16(v0[2], v0[3]); w.z = cvt_pk_bf16(v1[0], v1[1]); w.w = cvt_pk_bf16(v1[2], v1[3]); return w; }
; __device__ __forceinline__ f32x2 gelu_pk(f32x2 v) {
;     const f32x2 av = __builtin_elementwise_abs(v), d = av * 0.2316418882f + 1.0f;
;     f32x2 t; t.x = __builtin_amdgcn_rcpf(d.x); t.y = __builtin_amdgcn_rcpf(d.y);
;     f32x2 q = t * 0.5307027145f + (-0.7265760135f); q = q * t + 0.7107068705f; q = q * t + (-0.142248368f); q = q * t + 0.127414796f; q = q * t;
;     const f32x2 s = (v * v) * (-0.72134752044f);
;     f32x2 e; e.x = __builtin_amdgcn_exp2f(s.x); e.y = __builtin_amdgcn_exp2f(s.y);
;     const f32x2 m = v * (q * e), r = v - m;
;     f32x2 o; o.x = v.x < 0.f ? m.x : r.x; o.y = v.y < 0.f ? m.y : r.y; return o;
;     __device__ __forceinline__ void operator()(const f32x4 (&acc)[2][2][4][2], const Unit& u, int wr, int wc, int fr, int fq, const Pre& pre) const {
;     ...
;             for (int m = 0; m < 4; ++m) { const int row = row0 + ai * HALF + m * 16; const float r = rs8[ai * 4 + m];
;                 bf16_t* rowp = O + (size_t)row * 2048 + col0; float sq = 0.f;
; #pragma unroll
;                 for (int bj = 0; bj < 2; ++bj) { f32x4 v0 = acc[ai][bj][m][0] * r, v1 = acc[ai][bj][m][1] * r;
;                     f32x2 a = gelu_pk((f32x2){v0[0], v0[1]}), b = gelu_pk((f32x2){v0[2], v0[3]}), c = gelu_pk((f32x2){v1[0], v1[1]}), d = gelu_pk((f32x2){v1[2], v1[3]});
;                     v0 = (f32x4){a.x, a.y, b.x, b.y}; v1 = (f32x4){c.x, c.y, d.x, d.y};
;                     sq += (v0[0] * v0[0] + v0[1] * v0[1]) + (v0[2] * v0[2] + v0[3] * v0[3]) + (v1[0] * v1[0] + v1[1] * v1[1]) + (v1[2] * v1[2] + v1[3] * v1[3]);
;                     *(u32x4*)(rowp + bj * HALF) = pack8(v0, v1); }
.LBB0_61:
	s_waitcnt lgkmcnt(0)
	v_pk_mul_f32 v[108:109], v[108:109], v[166:167] op_sel_hi:[1,0]
	v_pk_mul_f32 v[114:115], v[104:105], v[166:167] op_sel_hi:[1,0]
	v_and_b32_e32 v105, 0x7fffffff, v109
	v_and_b32_e32 v104, 0x7fffffff, v108
	v_pk_fma_f32 v[104:105], v[104:105], s[8:9], 1.0 op_sel_hi:[1,0,0]
	v_pk_mul_f32 v[120:121], v[108:109], v[108:109]
	v_rcp_f32_e32 v116, v104
	v_rcp_f32_e32 v117, v105
	v_mov_b64_e32 v[104:105], s[12:13]
	v_pk_mul_f32 v[120:121], v[120:121], s[4:5] op_sel_hi:[1,0]
	v_cmp_gt_f32_e32 vcc, 0, v108
	v_pk_fma_f32 v[118:119], v[116:117], s[10:11], v[104:105] op_sel_hi:[1,0,0]
	v_exp_f32_e32 v120, v120
	v_pk_fma_f32 v[118:119], v[116:117], v[118:119], s[14:15] op_sel_hi:[1,1,0]
	v_exp_f32_e32 v121, v121
	v_pk_fma_f32 v[118:119], v[116:117], v[118:119], s[36:37] op_sel_hi:[1,1,0]
	v_pk_mul_f32 v[110:111], v[110:111], v[166:167] op_sel_hi:[1,0]
	v_pk_fma_f32 v[118:119], v[116:117], v[118:119], s[66:67] op_sel_hi:[1,1,0]
	v_pk_mul_f32 v[106:107], v[106:107], v[166:167] op_sel_hi:[1,0]
	v_pk_mul_f32 v[116:117], v[116:117], v[118:119]
	v_pk_mul_f32 v[118:119], v[110:111], v[110:111]
	v_pk_mul_f32 v[116:117], v[120:121], v[116:117]
	v_pk_mul_f32 v[118:119], v[118:119], s[4:5] op_sel_hi:[1,0]
	v_pk_mul_f32 v[120:121], v[108:109], v[116:117]
	v_pk_fma_f32 v[116:117], v[108:109], v[116:117], v[108:109] neg_lo:[1,0,0] neg_hi:[1,0,0]
	v_exp_f32_e32 v118, v118
	v_cndmask_b32_e32 v108, v116, v120, vcc
	v_cmp_gt_f32_e32 vcc, 0, v109
	v_and_b32_e32 v116, 0x7fffffff, v110
	v_exp_f32_e32 v119, v119
	v_cndmask_b32_e32 v109, v117, v121, vcc
	v_and_b32_e32 v117, 0x7fffffff, v111
	v_pk_fma_f32 v[116:117], v[116:117], s[8:9], 1.0 op_sel_hi:[1,0,0]
	v_cmp_gt_f32_e32 vcc, 0, v110
	v_rcp_f32_e32 v116, v116
	v_rcp_f32_e32 v117, v117
	v_or_b32_e32 v112, 16, v142
	v_ashrrev_i32_e32 v113, 31, v112
	v_lshlrev_b64 v[112:113], 12, v[112:113]
	v_pk_fma_f32 v[120:121], v[116:117], s[10:11], v[104:105] op_sel_hi:[1,0,0]
	v_lshl_add_u64 v[112:113], s[30:31], 0, v[112:113]
	v_pk_fma_f32 v[120:121], v[116:117], v[120:121], s[14:15] op_sel_hi:[1,1,0]
	v_lshl_add_u64 v[112:113], v[162:163], 1, v[112:113]
	v_pk_fma_f32 v[120:121], v[116:117], v[120:121], s[36:37] op_sel_hi:[1,1,0]
	v_pk_mul_f32 v[100:101], v[100:101], v[166:167] op_sel_hi:[1,0]
	v_pk_fma_f32 v[120:121], v[116:117], v[120:121], s[66:67] op_sel_hi:[1,1,0]
	v_pk_mul_f32 v[102:103], v[102:103], v[166:167] op_sel_hi:[1,0]
	v_pk_mul_f32 v[116:117], v[116:117], v[120:121]
	v_pk_mul_f32 v[120:121], v[114:115], v[114:115]
	v_pk_mul_f32 v[116:117], v[118:119], v[116:117]
	v_pk_mul_f32 v[120:121], v[120:121], s[4:5] op_sel_hi:[1,0]
	v_pk_mul_f32 v[118:119], v[110:111], v[116:117]
	v_pk_fma_f32 v[116:117], v[110:111], v[116:117], v[110:111] neg_lo:[1,0,0] neg_hi:[1,0,0]
	v_exp_f32_e32 v120, v120
	v_cndmask_b32_e32 v110, v116, v118, vcc
	v_cmp_gt_f32_e32 vcc, 0, v111
	v_and_b32_e32 v116, 0x7fffffff, v114
	v_exp_f32_e32 v121, v121
	v_cndmask_b32_e32 v111, v117, v119, vcc
	v_and_b32_e32 v117, 0x7fffffff, v115
	v_pk_fma_f32 v[116:117], v[116:117], s[8:9], 1.0 op_sel_hi:[1,0,0]
	v_cmp_gt_f32_e32 vcc, 0, v114
	v_rcp_f32_e32 v116, v116
	v_rcp_f32_e32 v117, v117
	v_pk_mul_f32 v[98:99], v[98:99], v[166:167] op_sel_hi:[1,0]
	v_pk_fma_f32 v[118:119], v[116:117], s[10:11], v[104:105] op_sel_hi:[1,0,0]
	s_nop 0
	v_pk_fma_f32 v[118:119], v[116:117], v[118:119], s[14:15] op_sel_hi:[1,1,0]
	s_nop 0
	v_pk_fma_f32 v[118:119], v[116:117], v[118:119], s[36:37] op_sel_hi:[1,1,0]
	s_nop 0
	v_pk_fma_f32 v[118:119], v[116:117], v[118:119], s[66:67] op_sel_hi:[1,1,0]
	s_nop 0
	v_pk_mul_f32 v[116:117], v[116:117], v[118:119]
	v_pk_mul_f32 v[118:119], v[106:107], v[106:107]
	v_pk_mul_f32 v[116:117], v[120:121], v[116:117]
	v_pk_mul_f32 v[118:119], v[118:119], s[4:5] op_sel_hi:[1,0]
	v_pk_mul_f32 v[120:121], v[114:115], v[116:117]
	v_pk_fma_f32 v[116:117], v[114:115], v[116:117], v[114:115] neg_lo:[1,0,0] neg_hi:[1,0,0]
	v_exp_f32_e32 v118, v118
	v_cndmask_b32_e32 v114, v116, v120, vcc
	v_cmp_gt_f32_e32 vcc, 0, v115
	v_and_b32_e32 v116, 0x7fffffff, v106
	v_exp_f32_e32 v119, v119
	v_cndmask_b32_e32 v115, v117, v121, vcc
	v_and_b32_e32 v117, 0x7fffffff, v107
	v_pk_fma_f32 v[116:117], v[116:117], s[8:9], 1.0 op_sel_hi:[1,0,0]
	v_cmp_gt_f32_e32 vcc, 0, v106
	v_rcp_f32_e32 v116, v116
	v_rcp_f32_e32 v117, v117
	s_nop 0
	v_pk_fma_f32 v[120:121], v[116:117], s[10:11], v[104:105] op_sel_hi:[1,0,0]
	s_nop 0
	v_pk_fma_f32 v[120:121], v[116:117], v[120:121], s[14:15] op_sel_hi:[1,1,0]
	s_nop 0
	v_pk_fma_f32 v[120:121], v[116:117], v[120:121], s[36:37] op_sel_hi:[1,1,0]
	s_nop 0
	v_pk_fma_f32 v[120:121], v[116:117], v[120:121], s[66:67] op_sel_hi:[1,1,0]
	s_nop 0
	v_pk_mul_f32 v[116:117], v[116:117], v[120:121]
	v_pk_mul_f32 v[120:121], v[100:101], v[100:101]
	v_pk_mul_f32 v[116:117], v[118:119], v[116:117]
	v_pk_mul_f32 v[120:121], v[120:121], s[4:5] op_sel_hi:[1,0]
	v_pk_mul_f32 v[118:119], v[106:107], v[116:117]
	v_pk_fma_f32 v[116:117], v[106:107], v[116:117], v[106:107] neg_lo:[1,0,0] neg_hi:[1,0,0]
	v_exp_f32_e32 v120, v120
	v_cndmask_b32_e32 v106, v116, v118, vcc
	v_cmp_gt_f32_e32 vcc, 0, v107
	v_cvt_pk_bf16_f32 v116, v108, v109
	v_exp_f32_e32 v121, v121
	s_nop 0
	v_cndmask_b32_e32 v107, v117, v119, vcc
	v_cvt_pk_bf16_f32 v117, v110, v111
	v_cvt_pk_bf16_f32 v118, v114, v115
	v_cvt_pk_bf16_f32 v119, v106, v107
	global_store_dwordx4 v[112:113], v[116:119], off nt
	v_cmp_gt_f32_e32 vcc, 0, v100
	s_nop 0
	v_pk_mul_f32 v[116:117], v[96:97], v[166:167] op_sel_hi:[1,0]
	v_and_b32_e32 v97, 0x7fffffff, v101
	v_and_b32_e32 v96, 0x7fffffff, v100
	v_pk_fma_f32 v[96:97], v[96:97], s[8:9], 1.0 op_sel_hi:[1,0,0]
	s_nop 0
; __device__ __forceinline__ unsigned long long f2ss(float v) { return (unsigned long long)(v * 16777216.0f); }
; __device__ __forceinline__ u32x4 pack8(f32x4 v0, f32x4 v1) { u32x4 w; w.x = cvt_pk_bf16(v0[0], v0[1]); w.y = cvt_pk_bf16(v0[2], v0[3]); w.z = cvt_pk_bf16(v1[0], v1[1]); w.w = cvt_pk_bf16(v1[2], v1[3]); return w; }
; __device__ __forceinline__ f32x2 gelu_pk(f32x2 v) {
;     const f32x2 av = __builtin_elementwise_abs(v), d = av * 0.2316418882f + 1.0f;
;     f32x2 t; t.x = __builtin_amdgcn_rcpf(d.x); t.y = __builtin_amdgcn_rcpf(d.y);
;     f32x2 q = t * 0.5307027145f + (-0.7265760135f); q = q * t + 0.7107068705f; q = q * t + (-0.142248368f); q = q * t + 0.127414796f; q = q * t;
;     const f32x2 s = (v * v) * (-0.72134752044f);
;     f32x2 e; e.x = __builtin_amdgcn_exp2f(s.x); e.y = __builtin_amdgcn_exp2f(s.y);
;     const f32x2 m = v * (q * e), r = v - m;
;     f32x2 o; o.x = v.x < 0.f ? m.x : r.x; o.y = v.y < 0.f ? m.y : r.y; return o;
;     __device__ __forceinline__ void operator()(const f32x4 (&acc)[2][2][4][2], const Unit& u, int wr, int wc, int fr, int fq, const Pre& pre) const {
;     ...
;                 for (int bj = 0; bj < 2; ++bj) { f32x4 v0 = acc[ai][bj][m][0] * r, v1 = acc[ai][bj][m][1] * r;
;                     f32x2 a = gelu_pk((f32x2){v0[0], v0[1]}), b = gelu_pk((f32x2){v0[2], v0[3]}), c = gelu_pk((f32x2){v1[0], v1[1]}), d = gelu_pk((f32x2){v1[2], v1[3]});
;                     v0 = (f32x4){a.x, a.y, b.x, b.y}; v1 = (f32x4){c.x, c.y, d.x, d.y};
;                     sq += (v0[0] * v0[0] + v0[1] * v0[1]) + (v0[2] * v0[2] + v0[3] * v0[3]) + (v1[0] * v1[0] + v1[1] * v1[1]) + (v1[2] * v1[2] + v1[3] * v1[3]);
;                     *(u32x4*)(rowp + bj * HALF) = pack8(v0, v1); }
;                 if (isv) { sq += __shfl_xor(sq, 16); sq += __shfl_xor(sq, 32); if (fq == 0) atomicAdd(vss + row, f2ss(sq)); } }
	v_rcp_f32_e32 v96, v96
	v_rcp_f32_e32 v97, v97
	s_nop 0
	v_pk_fma_f32 v[118:119], v[96:97], s[10:11], v[104:105] op_sel_hi:[1,0,0]
	s_nop 0
	v_pk_fma_f32 v[118:119], v[96:97], v[118:119], s[14:15] op_sel_hi:[1,1,0]
	s_nop 0
	v_pk_fma_f32 v[118:119], v[96:97], v[118:119], s[36:37] op_sel_hi:[1,1,0]
	s_nop 0
	v_pk_fma_f32 v[118:119], v[96:97], v[118:119], s[66:67] op_sel_hi:[1,1,0]
	s_nop 0
	v_pk_mul_f32 v[96:97], v[96:97], v[118:119]
	v_pk_mul_f32 v[118:119], v[102:103], v[102:103]
	v_pk_mul_f32 v[96:97], v[120:121], v[96:97]
	v_pk_mul_f32 v[118:119], v[118:119], s[4:5] op_sel_hi:[1,0]
	v_pk_mul_f32 v[120:121], v[100:101], v[96:97]
	v_pk_fma_f32 v[96:97], v[100:101], v[96:97], v[100:101] neg_lo:[1,0,0] neg_hi:[1,0,0]
	v_and_b32_e32 v100, 0x7fffffff, v102
	v_cndmask_b32_e32 v96, v96, v120, vcc
	v_cmp_gt_f32_e32 vcc, 0, v101
	v_and_b32_e32 v101, 0x7fffffff, v103
	v_pk_fma_f32 v[100:101], v[100:101], s[8:9], 1.0 op_sel_hi:[1,0,0]
	v_cndmask_b32_e32 v97, v97, v121, vcc
	v_rcp_f32_e32 v100, v100
	v_rcp_f32_e32 v101, v101
	v_exp_f32_e32 v118, v118
	v_exp_f32_e32 v119, v119
	v_cmp_gt_f32_e32 vcc, 0, v102
	v_pk_fma_f32 v[120:121], v[100:101], s[10:11], v[104:105] op_sel_hi:[1,0,0]
	s_nop 0
	v_pk_fma_f32 v[120:121], v[100:101], v[120:121], s[14:15] op_sel_hi:[1,1,0]
	s_nop 0
	v_pk_fma_f32 v[120:121], v[100:101], v[120:121], s[36:37] op_sel_hi:[1,1,0]
	s_nop 0
	v_pk_fma_f32 v[120:121], v[100:101], v[120:121], s[66:67] op_sel_hi:[1,1,0]
	s_nop 0
	v_pk_mul_f32 v[100:101], v[100:101], v[120:121]
	v_pk_mul_f32 v[120:121], v[116:117], v[116:117]
	v_pk_mul_f32 v[100:101], v[118:119], v[100:101]
	v_pk_mul_f32 v[120:121], v[120:121], s[4:5] op_sel_hi:[1,0]
	v_pk_mul_f32 v[118:119], v[102:103], v[100:101]
	v_pk_fma_f32 v[100:101], v[102:103], v[100:101], v[102:103] neg_lo:[1,0,0] neg_hi:[1,0,0]
	v_and_b32_e32 v102, 0x7fffffff, v116
	v_cndmask_b32_e32 v100, v100, v118, vcc
	v_cmp_gt_f32_e32 vcc, 0, v103
	v_and_b32_e32 v103, 0x7fffffff, v117
	v_pk_fma_f32 v[102:103], v[102:103], s[8:9], 1.0 op_sel_hi:[1,0,0]
	v_cndmask_b32_e32 v101, v101, v119, vcc
	v_rcp_f32_e32 v102, v102
	v_rcp_f32_e32 v103, v103
	v_exp_f32_e32 v120, v120
	v_exp_f32_e32 v121, v121
	v_cmp_gt_f32_e32 vcc, 0, v116
	v_pk_fma_f32 v[118:119], v[102:103], s[10:11], v[104:105] op_sel_hi:[1,0,0]
	s_nop 0
	v_pk_fma_f32 v[118:119], v[102:103], v[118:119], s[14:15] op_sel_hi:[1,1,0]
	s_nop 0
	v_pk_fma_f32 v[118:119], v[102:103], v[118:119], s[36:37] op_sel_hi:[1,1,0]
	s_nop 0
	v_pk_fma_f32 v[118:119], v[102:103], v[118:119], s[66:67] op_sel_hi:[1,1,0]
	s_nop 0
	v_pk_mul_f32 v[102:103], v[102:103], v[118:119]
	v_pk_mul_f32 v[118:119], v[98:99], v[98:99]
	v_pk_mul_f32 v[102:103], v[120:121], v[102:103]
	s_nop 0
	v_pk_mul_f32 v[120:121], v[116:117], v[102:103]
	v_pk_fma_f32 v[102:103], v[116:117], v[102:103], v[116:117] neg_lo:[1,0,0] neg_hi:[1,0,0]
	v_and_b32_e32 v116, 0x7fffffff, v98
	v_cndmask_b32_e32 v102, v102, v120, vcc
	v_cmp_gt_f32_e32 vcc, 0, v117
	v_and_b32_e32 v117, 0x7fffffff, v99
	v_pk_fma_f32 v[116:117], v[116:117], s[8:9], 1.0 op_sel_hi:[1,0,0]
	v_cndmask_b32_e32 v103, v103, v121, vcc
	v_rcp_f32_e32 v116, v116
	v_rcp_f32_e32 v117, v117
	v_cmp_gt_f32_e32 vcc, 0, v98
	v_pk_fma_f32 v[104:105], v[116:117], s[10:11], v[104:105] op_sel_hi:[1,0,0]
	s_nop 0
	v_pk_fma_f32 v[104:105], v[116:117], v[104:105], s[14:15] op_sel_hi:[1,1,0]
	s_nop 0
	v_pk_fma_f32 v[104:105], v[116:117], v[104:105], s[36:37] op_sel_hi:[1,1,0]
	s_nop 0
	v_pk_fma_f32 v[104:105], v[116:117], v[104:105], s[66:67] op_sel_hi:[1,1,0]
	s_nop 0
	v_pk_mul_f32 v[104:105], v[116:117], v[104:105]
	v_pk_mul_f32 v[116:117], v[118:119], s[4:5] op_sel_hi:[1,0]
	s_nop 0
	v_exp_f32_e32 v116, v116
	v_exp_f32_e32 v117, v117
	s_nop 0
	v_pk_mul_f32 v[104:105], v[116:117], v[104:105]
	s_nop 0
	v_pk_mul_f32 v[116:117], v[98:99], v[104:105]
	v_pk_fma_f32 v[104:105], v[98:99], v[104:105], v[98:99] neg_lo:[1,0,0] neg_hi:[1,0,0]
	s_nop 0
	v_cndmask_b32_e32 v98, v104, v116, vcc
	v_cmp_gt_f32_e32 vcc, 0, v99
	v_cndmask_b32_e64 v104, 0, 1, s[64:65]
	v_cmp_ne_u32_e64 s[44:45], 1, v104
	v_cndmask_b32_e32 v99, v105, v117, vcc
	s_andn2_b64 vcc, exec, s[64:65]
	v_cvt_pk_bf16_f32 v116, v96, v97
	v_cvt_pk_bf16_f32 v117, v100, v101
	v_cvt_pk_bf16_f32 v118, v102, v103
	v_cvt_pk_bf16_f32 v119, v98, v99
	global_store_dwordx4 v[112:113], v[116:119], off offset:256 nt
	s_cbranch_vccnz .LBB0_65
	v_mul_f32_e32 v104, v107, v107
	v_mul_f32_e32 v97, v97, v97
	v_fmac_f32_e32 v104, v106, v106
	v_mul_f32_e32 v105, v109, v109
	v_mul_f32_e32 v106, v111, v111
	v_fmac_f32_e32 v97, v96, v96
	v_mul_f32_e32 v96, v101, v101
	v_fmac_f32_e32 v105, v108, v108
	v_fmac_f32_e32 v106, v110, v110
	v_fmac_f32_e32 v96, v100, v100
	v_add_f32_e32 v105, v105, v106
	v_mul_f32_e32 v106, v115, v115
	v_add_f32_e32 v96, v97, v96
	v_mul_f32_e32 v97, v103, v103
	v_fmac_f32_e32 v106, v114, v114
	v_mul_f32_e32 v99, v99, v99
	v_fmac_f32_e32 v97, v102, v102
	v_add_f32_e32 v105, v106, v105
	v_fmac_f32_e32 v99, v98, v98
	v_add_f32_e32 v96, v97, v96
	v_add_f32_e32 v104, v104, v105
	v_add_f32_e32 v96, v99, v96
	v_add_f32_e32 v96, v104, v96
	ds_bpermute_b32 v97, v147, v96
	s_waitcnt lgkmcnt(0)
	v_add_f32_e32 v96, v96, v97
	ds_bpermute_b32 v97, v165, v96
	s_and_saveexec_b64 s[26:27], s[40:41]
	s_cbranch_execz .LBB0_64
	s_waitcnt lgkmcnt(0)
	v_add_f32_e32 v96, v96, v97
	v_mul_f32_e32 v96, 0x4b800000, v96
	v_trunc_f32_e32 v96, v96
	v_mul_f32_e32 v97, 0x2f800000, v96
	v_floor_f32_e32 v97, v97
	v_fmac_f32_e32 v96, 0xcf800000, v97
	v_cvt_u32_f32_e32 v96, v96
	v_cvt_u32_f32_e32 v97, v97
	v_lshl_add_u64 v[98:99], v[142:143], 3, s[52:53]
	global_atomic_add_x2 v[98:99], v[96:97], off offset:128

; __device__ __forceinline__ u32x4 pack8(f32x4 v0, f32x4 v1) { u32x4 w; w.x = cvt_pk_bf16(v0[0], v0[1]); w.y = cvt_pk_bf16(v0[2], v0[3]); w.z = cvt_pk_bf16(v1[0], v1[1]); w.w = cvt_pk_bf16(v1[2], v1[3]); return w; }
; __device__ __forceinline__ f32x2 gelu_pk(f32x2 v) {
;     const f32x2 av = __builtin_elementwise_abs(v), d = av * 0.2316418882f + 1.0f;
;     f32x2 t; t.x = __builtin_amdgcn_rcpf(d.x); t.y = __builtin_amdgcn_rcpf(d.y);
;     f32x2 q = t * 0.5307027145f + (-0.7265760135f); q = q * t + 0.7107068705f; q = q * t + (-0.142248368f); q = q * t + 0.127414796f; q = q * t;
;     const f32x2 s = (v * v) * (-0.72134752044f);
;     f32x2 e; e.x = __builtin_amdgcn_exp2f(s.x); e.y = __builtin_amdgcn_exp2f(s.y);
;     const f32x2 m = v * (q * e), r = v - m;
;     f32x2 o; o.x = v.x < 0.f ? m.x : r.x; o.y = v.y < 0.f ? m.y : r.y; return o;
;     __device__ __forceinline__ void operator()(const f32x4 (&acc)[2][2][4][2], const Unit& u, int wr, int wc, int fr, int fq, const Pre& pre) const {
;     ...
;             for (int m = 0; m < 4; ++m) { const int row = row0 + ai * HALF + m * 16; const float r = rs8[ai * 4 + m];
;                 bf16_t* rowp = O + (size_t)row * 2048 + col0; float sq = 0.f;
; #pragma unroll
;                 for (int bj = 0; bj < 2; ++bj) { f32x4 v0 = acc[ai][bj][m][0] * r, v1 = acc[ai][bj][m][1] * r;
;                     f32x2 a = gelu_pk((f32x2){v0[0], v0[1]}), b = gelu_pk((f32x2){v0[2], v0[3]}), c = gelu_pk((f32x2){v1[0], v1[1]}), d = gelu_pk((f32x2){v1[2], v1[3]});
;                     v0 = (f32x4){a.x, a.y, b.x, b.y}; v1 = (f32x4){c.x, c.y, d.x, d.y};
;                     sq += (v0[0] * v0[0] + v0[1] * v0[1]) + (v0[2] * v0[2] + v0[3] * v0[3]) + (v1[0] * v1[0] + v1[1] * v1[1]) + (v1[2] * v1[2] + v1[3] * v1[3]);
;                     *(u32x4*)(rowp + bj * HALF) = pack8(v0, v1); }
.LBB0_65:
	v_pk_mul_f32 v[92:93], v[92:93], v[164:165] op_sel_hi:[1,0]
	v_pk_mul_f32 v[98:99], v[88:89], v[164:165] op_sel_hi:[1,0]
	v_and_b32_e32 v89, 0x7fffffff, v93
	v_and_b32_e32 v88, 0x7fffffff, v92
	v_pk_fma_f32 v[88:89], v[88:89], s[8:9], 1.0 op_sel_hi:[1,0,0]
	v_pk_mul_f32 v[104:105], v[92:93], v[92:93]
	v_rcp_f32_e32 v100, v88
	v_rcp_f32_e32 v101, v89
	v_mov_b64_e32 v[88:89], s[12:13]
	v_pk_mul_f32 v[104:105], v[104:105], s[4:5] op_sel_hi:[1,0]
	v_cmp_gt_f32_e32 vcc, 0, v92
	v_pk_fma_f32 v[102:103], v[100:101], s[10:11], v[88:89] op_sel_hi:[1,0,0]
	v_exp_f32_e32 v104, v104
	v_pk_fma_f32 v[102:103], v[100:101], v[102:103], s[14:15] op_sel_hi:[1,1,0]
	v_exp_f32_e32 v105, v105
	v_pk_fma_f32 v[102:103], v[100:101], v[102:103], s[36:37] op_sel_hi:[1,1,0]
	v_pk_mul_f32 v[94:95], v[94:95], v[164:165] op_sel_hi:[1,0]
	v_pk_fma_f32 v[102:103], v[100:101], v[102:103], s[66:67] op_sel_hi:[1,1,0]
	v_pk_mul_f32 v[90:91], v[90:91], v[164:165] op_sel_hi:[1,0]
	v_pk_mul_f32 v[100:101], v[100:101], v[102:103]
	v_pk_mul_f32 v[102:103], v[94:95], v[94:95]
	v_pk_mul_f32 v[100:101], v[104:105], v[100:101]
	v_pk_mul_f32 v[102:103], v[102:103], s[4:5] op_sel_hi:[1,0]
	v_pk_mul_f32 v[104:105], v[92:93], v[100:101]
	v_pk_fma_f32 v[100:101], v[92:93], v[100:101], v[92:93] neg_lo:[1,0,0] neg_hi:[1,0,0]
	v_exp_f32_e32 v102, v102
	v_cndmask_b32_e32 v92, v100, v104, vcc
	v_cmp_gt_f32_e32 vcc, 0, v93
	v_and_b32_e32 v100, 0x7fffffff, v94
	v_exp_f32_e32 v103, v103
	v_cndmask_b32_e32 v93, v101, v105, vcc
	v_and_b32_e32 v101, 0x7fffffff, v95
	v_pk_fma_f32 v[100:101], v[100:101], s[8:9], 1.0 op_sel_hi:[1,0,0]
	v_cmp_gt_f32_e32 vcc, 0, v94
	v_rcp_f32_e32 v100, v100
	v_rcp_f32_e32 v101, v101
	v_or_b32_e32 v96, 32, v142
	s_waitcnt lgkmcnt(0)
	v_ashrrev_i32_e32 v97, 31, v96
	v_lshlrev_b64 v[96:97], 12, v[96:97]
	v_pk_fma_f32 v[104:105], v[100:101], s[10:11], v[88:89] op_sel_hi:[1,0,0]
	v_lshl_add_u64 v[96:97], s[30:31], 0, v[96:97]
	v_pk_fma_f32 v[104:105], v[100:101], v[104:105], s[14:15] op_sel_hi:[1,1,0]
	v_lshl_add_u64 v[96:97], v[162:163], 1, v[96:97]
	v_pk_fma_f32 v[104:105], v[100:101], v[104:105], s[36:37] op_sel_hi:[1,1,0]
	v_pk_mul_f32 v[84:85], v[84:85], v[164:165] op_sel_hi:[1,0]
	v_pk_fma_f32 v[104:105], v[100:101], v[104:105], s[66:67] op_sel_hi:[1,1,0]
	v_pk_mul_f32 v[86:87], v[86:87], v[164:165] op_sel_hi:[1,0]
	v_pk_mul_f32 v[100:101], v[100:101], v[104:105]
	v_pk_mul_f32 v[104:105], v[98:99], v[98:99]
	v_pk_mul_f32 v[100:101], v[102:103], v[100:101]
	v_pk_mul_f32 v[104:105], v[104:105], s[4:5] op_sel_hi:[1,0]
	v_pk_mul_f32 v[102:103], v[94:95], v[100:101]
	v_pk_fma_f32 v[100:101], v[94:95], v[100:101], v[94:95] neg_lo:[1,0,0] neg_hi:[1,0,0]
	v_exp_f32_e32 v104, v104
	v_cndmask_b32_e32 v94, v100, v102, vcc
	v_cmp_gt_f32_e32 vcc, 0, v95
	v_and_b32_e32 v100, 0x7fffffff, v98
	v_exp_f32_e32 v105, v105
	v_cndmask_b32_e32 v95, v101, v103, vcc
	v_and_b32_e32 v101, 0x7fffffff, v99
	v_pk_fma_f32 v[100:101], v[100:101], s[8:9], 1.0 op_sel_hi:[1,0,0]
	v_cmp_gt_f32_e32 vcc, 0, v98
	v_rcp_f32_e32 v100, v100
	v_rcp_f32_e32 v101, v101
	v_pk_mul_f32 v[82:83], v[82:83], v[164:165] op_sel_hi:[1,0]
	v_pk_fma_f32 v[102:103], v[100:101], s[10:11], v[88:89] op_sel_hi:[1,0,0]
	s_nop 0
	v_pk_fma_f32 v[102:103], v[100:101], v[102:103], s[14:15] op_sel_hi:[1,1,0]
	s_nop 0
	v_pk_fma_f32 v[102:103], v[100:101], v[102:103], s[36:37] op_sel_hi:[1,1,0]
	s_nop 0
	v_pk_fma_f32 v[102:103], v[100:101], v[102:103], s[66:67] op_sel_hi:[1,1,0]
	s_nop 0
	v_pk_mul_f32 v[100:101], v[100:101], v[102:103]
	v_pk_mul_f32 v[102:103], v[90:91], v[90:91]
	v_pk_mul_f32 v[100:101], v[104:105], v[100:101]
	v_pk_mul_f32 v[102:103], v[102:103], s[4:5] op_sel_hi:[1,0]
	v_pk_mul_f32 v[104:105], v[98:99], v[100:101]
	v_pk_fma_f32 v[100:101], v[98:99], v[100:101], v[98:99] neg_lo:[1,0,0] neg_hi:[1,0,0]
	v_exp_f32_e32 v102, v102
	v_cndmask_b32_e32 v98, v100, v104, vcc
	v_cmp_gt_f32_e32 vcc, 0, v99
	v_and_b32_e32 v100, 0x7fffffff, v90
	v_exp_f32_e32 v103, v103
	v_cndmask_b32_e32 v99, v101, v105, vcc
	v_and_b32_e32 v101, 0x7fffffff, v91
	v_pk_fma_f32 v[100:101], v[100:101], s[8:9], 1.0 op_sel_hi:[1,0,0]
	v_cmp_gt_f32_e32 vcc, 0, v90
	v_rcp_f32_e32 v100, v100
	v_rcp_f32_e32 v101, v101
	s_nop 0
	v_pk_fma_f32 v[104:105], v[100:101], s[10:11], v[88:89] op_sel_hi:[1,0,0]
	s_nop 0
	v_pk_fma_f32 v[104:105], v[100:101], v[104:105], s[14:15] op_sel_hi:[1,1,0]
	s_nop 0
	v_pk_fma_f32 v[104:105], v[100:101], v[104:105], s[36:37] op_sel_hi:[1,1,0]
	s_nop 0
	v_pk_fma_f32 v[104:105], v[100:101], v[104:105], s[66:67] op_sel_hi:[1,1,0]
	s_nop 0
	v_pk_mul_f32 v[100:101], v[100:101], v[104:105]
	v_pk_mul_f32 v[104:105], v[84:85], v[84:85]
	v_pk_mul_f32 v[100:101], v[102:103], v[100:101]
	v_pk_mul_f32 v[104:105], v[104:105], s[4:5] op_sel_hi:[1,0]
	v_pk_mul_f32 v[102:103], v[90:91], v[100:101]
	v_pk_fma_f32 v[100:101], v[90:91], v[100:101], v[90:91] neg_lo:[1,0,0] neg_hi:[1,0,0]
	v_exp_f32_e32 v104, v104
	v_cndmask_b32_e32 v90, v100, v102, vcc
	v_cmp_gt_f32_e32 vcc, 0, v91
	v_cvt_pk_bf16_f32 v100, v92, v93
	v_exp_f32_e32 v105, v105
	s_nop 0
	v_cndmask_b32_e32 v91, v101, v103, vcc
	v_cvt_pk_bf16_f32 v101, v94, v95
	v_cvt_pk_bf16_f32 v102, v98, v99
	v_cvt_pk_bf16_f32 v103, v90, v91
	global_store_dwordx4 v[96:97], v[100:103], off nt
	v_cmp_gt_f32_e32 vcc, 0, v84
	s_nop 0
	v_pk_mul_f32 v[100:101], v[80:81], v[164:165] op_sel_hi:[1,0]
	v_and_b32_e32 v81, 0x7fffffff, v85
	v_and_b32_e32 v80, 0x7fffffff, v84
; __device__ __forceinline__ unsigned long long f2ss(float v) { return (unsigned long long)(v * 16777216.0f); }
; __device__ __forceinline__ u32x4 pack8(f32x4 v0, f32x4 v1) { u32x4 w; w.x = cvt_pk_bf16(v0[0], v0[1]); w.y = cvt_pk_bf16(v0[2], v0[3]); w.z = cvt_pk_bf16(v1[0], v1[1]); w.w = cvt_pk_bf16(v1[2], v1[3]); return w; }
; __device__ __forceinline__ f32x2 gelu_pk(f32x2 v) {
;     const f32x2 av = __builtin_elementwise_abs(v), d = av * 0.2316418882f + 1.0f;
;     f32x2 t; t.x = __builtin_amdgcn_rcpf(d.x); t.y = __builtin_amdgcn_rcpf(d.y);
;     f32x2 q = t * 0.5307027145f + (-0.7265760135f); q = q * t + 0.7107068705f; q = q * t + (-0.142248368f); q = q * t + 0.127414796f; q = q * t;
;     const f32x2 s = (v * v) * (-0.72134752044f);
;     f32x2 e; e.x = __builtin_amdgcn_exp2f(s.x); e.y = __builtin_amdgcn_exp2f(s.y);
;     const f32x2 m = v * (q * e), r = v - m;
;     f32x2 o; o.x = v.x < 0.f ? m.x : r.x; o.y = v.y < 0.f ? m.y : r.y; return o;
;     __device__ __forceinline__ void operator()(const f32x4 (&acc)[2][2][4][2], const Unit& u, int wr, int wc, int fr, int fq, const Pre& pre) const {
;     ...
;                 for (int bj = 0; bj < 2; ++bj) { f32x4 v0 = acc[ai][bj][m][0] * r, v1 = acc[ai][bj][m][1] * r;
;                     f32x2 a = gelu_pk((f32x2){v0[0], v0[1]}), b = gelu_pk((f32x2){v0[2], v0[3]}), c = gelu_pk((f32x2){v1[0], v1[1]}), d = gelu_pk((f32x2){v1[2], v1[3]});
;                     v0 = (f32x4){a.x, a.y, b.x, b.y}; v1 = (f32x4){c.x, c.y, d.x, d.y};
;                     sq += (v0[0] * v0[0] + v0[1] * v0[1]) + (v0[2] * v0[2] + v0[3] * v0[3]) + (v1[0] * v1[0] + v1[1] * v1[1]) + (v1[2] * v1[2] + v1[3] * v1[3]);
;                     *(u32x4*)(rowp + bj * HALF) = pack8(v0, v1); }
;                 if (isv) { sq += __shfl_xor(sq, 16); sq += __shfl_xor(sq, 32); if (fq == 0) atomicAdd(vss + row, f2ss(sq)); } }
	v_pk_fma_f32 v[80:81], v[80:81], s[8:9], 1.0 op_sel_hi:[1,0,0]
	s_nop 0
	v_rcp_f32_e32 v80, v80
	v_rcp_f32_e32 v81, v81
	s_nop 0
	v_pk_fma_f32 v[102:103], v[80:81], s[10:11], v[88:89] op_sel_hi:[1,0,0]
	s_nop 0
	v_pk_fma_f32 v[102:103], v[80:81], v[102:103], s[14:15] op_sel_hi:[1,1,0]
	s_nop 0
	v_pk_fma_f32 v[102:103], v[80:81], v[102:103], s[36:37] op_sel_hi:[1,1,0]
	s_nop 0
	v_pk_fma_f32 v[102:103], v[80:81], v[102:103], s[66:67] op_sel_hi:[1,1,0]
	s_nop 0
	v_pk_mul_f32 v[80:81], v[80:81], v[102:103]
	v_pk_mul_f32 v[102:103], v[86:87], v[86:87]
	v_pk_mul_f32 v[80:81], v[104:105], v[80:81]
	v_pk_mul_f32 v[102:103], v[102:103], s[4:5] op_sel_hi:[1,0]
	v_pk_mul_f32 v[104:105], v[84:85], v[80:81]
	v_pk_fma_f32 v[80:81], v[84:85], v[80:81], v[84:85] neg_lo:[1,0,0] neg_hi:[1,0,0]
	v_and_b32_e32 v84, 0x7fffffff, v86
	v_cndmask_b32_e32 v80, v80, v104, vcc
	v_cmp_gt_f32_e32 vcc, 0, v85
	v_and_b32_e32 v85, 0x7fffffff, v87
	v_pk_fma_f32 v[84:85], v[84:85], s[8:9], 1.0 op_sel_hi:[1,0,0]
	v_cndmask_b32_e32 v81, v81, v105, vcc
	v_rcp_f32_e32 v84, v84
	v_rcp_f32_e32 v85, v85
	v_exp_f32_e32 v102, v102
	v_exp_f32_e32 v103, v103
	v_cmp_gt_f32_e32 vcc, 0, v86
	v_pk_fma_f32 v[104:105], v[84:85], s[10:11], v[88:89] op_sel_hi:[1,0,0]
	s_nop 0
	v_pk_fma_f32 v[104:105], v[84:85], v[104:105], s[14:15] op_sel_hi:[1,1,0]
	s_nop 0
	v_pk_fma_f32 v[104:105], v[84:85], v[104:105], s[36:37] op_sel_hi:[1,1,0]
	s_nop 0
	v_pk_fma_f32 v[104:105], v[84:85], v[104:105], s[66:67] op_sel_hi:[1,1,0]
	s_nop 0
	v_pk_mul_f32 v[84:85], v[84:85], v[104:105]
	v_pk_mul_f32 v[104:105], v[100:101], v[100:101]
	v_pk_mul_f32 v[84:85], v[102:103], v[84:85]
	v_pk_mul_f32 v[104:105], v[104:105], s[4:5] op_sel_hi:[1,0]
	v_pk_mul_f32 v[102:103], v[86:87], v[84:85]
	v_pk_fma_f32 v[84:85], v[86:87], v[84:85], v[86:87] neg_lo:[1,0,0] neg_hi:[1,0,0]
	v_and_b32_e32 v86, 0x7fffffff, v100
	v_cndmask_b32_e32 v84, v84, v102, vcc
	v_cmp_gt_f32_e32 vcc, 0, v87
	v_and_b32_e32 v87, 0x7fffffff, v101
	v_pk_fma_f32 v[86:87], v[86:87], s[8:9], 1.0 op_sel_hi:[1,0,0]
	v_cndmask_b32_e32 v85, v85, v103, vcc
	v_rcp_f32_e32 v86, v86
	v_rcp_f32_e32 v87, v87
	v_exp_f32_e32 v104, v104
	v_exp_f32_e32 v105, v105
	v_cmp_gt_f32_e32 vcc, 0, v100
	v_pk_fma_f32 v[102:103], v[86:87], s[10:11], v[88:89] op_sel_hi:[1,0,0]
	s_nop 0
	v_pk_fma_f32 v[102:103], v[86:87], v[102:103], s[14:15] op_sel_hi:[1,1,0]
	s_nop 0
	v_pk_fma_f32 v[102:103], v[86:87], v[102:103], s[36:37] op_sel_hi:[1,1,0]
	s_nop 0
	v_pk_fma_f32 v[102:103], v[86:87], v[102:103], s[66:67] op_sel_hi:[1,1,0]
	s_nop 0
	v_pk_mul_f32 v[86:87], v[86:87], v[102:103]
	v_pk_mul_f32 v[102:103], v[82:83], v[82:83]
	v_pk_mul_f32 v[86:87], v[104:105], v[86:87]
	s_nop 0
	v_pk_mul_f32 v[104:105], v[100:101], v[86:87]
	v_pk_fma_f32 v[86:87], v[100:101], v[86:87], v[100:101] neg_lo:[1,0,0] neg_hi:[1,0,0]
	v_and_b32_e32 v100, 0x7fffffff, v82
	v_cndmask_b32_e32 v86, v86, v104, vcc
	v_cmp_gt_f32_e32 vcc, 0, v101
	v_and_b32_e32 v101, 0x7fffffff, v83
	v_pk_fma_f32 v[100:101], v[100:101], s[8:9], 1.0 op_sel_hi:[1,0,0]
	v_cndmask_b32_e32 v87, v87, v105, vcc
	v_rcp_f32_e32 v100, v100
	v_rcp_f32_e32 v101, v101
	v_cmp_gt_f32_e32 vcc, 0, v82
	v_pk_fma_f32 v[88:89], v[100:101], s[10:11], v[88:89] op_sel_hi:[1,0,0]
	s_nop 0
	v_pk_fma_f32 v[88:89], v[100:101], v[88:89], s[14:15] op_sel_hi:[1,1,0]
	s_nop 0
	v_pk_fma_f32 v[88:89], v[100:101], v[88:89], s[36:37] op_sel_hi:[1,1,0]
	s_nop 0
	v_pk_fma_f32 v[88:89], v[100:101], v[88:89], s[66:67] op_sel_hi:[1,1,0]
	s_nop 0
	v_pk_mul_f32 v[88:89], v[100:101], v[88:89]
	v_pk_mul_f32 v[100:101], v[102:103], s[4:5] op_sel_hi:[1,0]
	s_nop 0
	v_exp_f32_e32 v100, v100
	v_exp_f32_e32 v101, v101
	s_nop 0
	v_pk_mul_f32 v[88:89], v[100:101], v[88:89]
	s_nop 0
	v_pk_mul_f32 v[100:101], v[82:83], v[88:89]
	v_pk_fma_f32 v[88:89], v[82:83], v[88:89], v[82:83] neg_lo:[1,0,0] neg_hi:[1,0,0]
	s_nop 0
	v_cndmask_b32_e32 v82, v88, v100, vcc
	v_cmp_gt_f32_e32 vcc, 0, v83
	v_cvt_pk_bf16_f32 v100, v80, v81
	s_nop 1
	v_cndmask_b32_e32 v83, v89, v101, vcc
	s_and_b64 vcc, exec, s[44:45]
	v_cvt_pk_bf16_f32 v101, v84, v85
	v_cvt_pk_bf16_f32 v102, v86, v87
	v_cvt_pk_bf16_f32 v103, v82, v83
	global_store_dwordx4 v[96:97], v[100:103], off offset:256 nt
	s_cbranch_vccnz .LBB0_69
	v_mul_f32_e32 v88, v91, v91
	v_mul_f32_e32 v81, v81, v81
	v_fmac_f32_e32 v88, v90, v90
	v_mul_f32_e32 v89, v93, v93
	v_mul_f32_e32 v90, v95, v95
	v_fmac_f32_e32 v81, v80, v80
	v_mul_f32_e32 v80, v85, v85
	v_fmac_f32_e32 v89, v92, v92
	v_fmac_f32_e32 v90, v94, v94
	v_fmac_f32_e32 v80, v84, v84
	v_add_f32_e32 v89, v89, v90
	v_mul_f32_e32 v90, v99, v99
	v_add_f32_e32 v80, v81, v80
	v_mul_f32_e32 v81, v87, v87
	v_fmac_f32_e32 v90, v98, v98
	v_mul_f32_e32 v83, v83, v83
	v_fmac_f32_e32 v81, v86, v86
	v_add_f32_e32 v89, v90, v89
	v_fmac_f32_e32 v83, v82, v82
	v_add_f32_e32 v80, v81, v80
	v_add_f32_e32 v88, v88, v89
	v_add_f32_e32 v80, v83, v80
	v_add_f32_e32 v80, v88, v80
	ds_bpermute_b32 v81, v147, v80
	s_waitcnt lgkmcnt(0)
	v_add_f32_e32 v80, v80, v81
	ds_bpermute_b32 v81, v165, v80
	s_and_saveexec_b64 s[26:27], s[40:41]
	s_cbranch_execz .LBB0_68
	s_waitcnt lgkmcnt(0)
	v_add_f32_e32 v80, v80, v81
	v_mul_f32_e32 v80, 0x4b800000, v80
	v_trunc_f32_e32 v80, v80
	v_mul_f32_e32 v81, 0x2f800000, v80
	v_floor_f32_e32 v81, v81
	v_fmac_f32_e32 v80, 0xcf800000, v81
	v_cvt_u32_f32_e32 v80, v80
	v_cvt_u32_f32_e32 v81, v81
	v_lshl_add_u64 v[82:83], v[142:143], 3, s[52:53]
	global_atomic_add_x2 v[82:83], v[80:81], off offset:256

; __device__ __forceinline__ u32x4 pack8(f32x4 v0, f32x4 v1) { u32x4 w; w.x = cvt_pk_bf16(v0[0], v0[1]); w.y = cvt_pk_bf16(v0[2], v0[3]); w.z = cvt_pk_bf16(v1[0], v1[1]); w.w = cvt_pk_bf16(v1[2], v1[3]); return w; }
; __device__ __forceinline__ f32x2 gelu_pk(f32x2 v) {
;     const f32x2 av = __builtin_elementwise_abs(v), d = av * 0.2316418882f + 1.0f;
;     f32x2 t; t.x = __builtin_amdgcn_rcpf(d.x); t.y = __builtin_amdgcn_rcpf(d.y);
;     f32x2 q = t * 0.5307027145f + (-0.7265760135f); q = q * t + 0.7107068705f; q = q * t + (-0.142248368f); q = q * t + 0.127414796f; q = q * t;
;     const f32x2 s = (v * v) * (-0.72134752044f);
;     f32x2 e; e.x = __builtin_amdgcn_exp2f(s.x); e.y = __builtin_amdgcn_exp2f(s.y);
;     const f32x2 m = v * (q * e), r = v - m;
;     f32x2 o; o.x = v.x < 0.f ? m.x : r.x; o.y = v.y < 0.f ? m.y : r.y; return o;
;     __device__ __forceinline__ void operator()(const f32x4 (&acc)[2][2][4][2], const Unit& u, int wr, int wc, int fr, int fq, const Pre& pre) const {
;     ...
;             for (int m = 0; m < 4; ++m) { const int row = row0 + ai * HALF + m * 16; const float r = rs8[ai * 4 + m];
;                 bf16_t* rowp = O + (size_t)row * 2048 + col0; float sq = 0.f;
; #pragma unroll
;                 for (int bj = 0; bj < 2; ++bj) { f32x4 v0 = acc[ai][bj][m][0] * r, v1 = acc[ai][bj][m][1] * r;
;                     f32x2 a = gelu_pk((f32x2){v0[0], v0[1]}), b = gelu_pk((f32x2){v0[2], v0[3]}), c = gelu_pk((f32x2){v1[0], v1[1]}), d = gelu_pk((f32x2){v1[2], v1[3]});
;                     v0 = (f32x4){a.x, a.y, b.x, b.y}; v1 = (f32x4){c.x, c.y, d.x, d.y};
;                     sq += (v0[0] * v0[0] + v0[1] * v0[1]) + (v0[2] * v0[2] + v0[3] * v0[3]) + (v1[0] * v1[0] + v1[1] * v1[1]) + (v1[2] * v1[2] + v1[3] * v1[3]);
;                     *(u32x4*)(rowp + bj * HALF) = pack8(v0, v1); }
.LBB0_69:
	v_pk_mul_f32 v[76:77], v[76:77], v[160:161] op_sel_hi:[1,0]
	v_pk_mul_f32 v[82:83], v[72:73], v[160:161] op_sel_hi:[1,0]
	v_and_b32_e32 v73, 0x7fffffff, v77
	v_and_b32_e32 v72, 0x7fffffff, v76
	v_pk_fma_f32 v[72:73], v[72:73], s[8:9], 1.0 op_sel_hi:[1,0,0]
	v_pk_mul_f32 v[88:89], v[76:77], v[76:77]
	v_rcp_f32_e32 v84, v72
	v_rcp_f32_e32 v85, v73
	v_mov_b64_e32 v[72:73], s[12:13]
	v_pk_mul_f32 v[88:89], v[88:89], s[4:5] op_sel_hi:[1,0]
	v_cmp_gt_f32_e32 vcc, 0, v76
	v_pk_fma_f32 v[86:87], v[84:85], s[10:11], v[72:73] op_sel_hi:[1,0,0]
	v_exp_f32_e32 v88, v88
	v_pk_fma_f32 v[86:87], v[84:85], v[86:87], s[14:15] op_sel_hi:[1,1,0]
	v_exp_f32_e32 v89, v89
	v_pk_fma_f32 v[86:87], v[84:85], v[86:87], s[36:37] op_sel_hi:[1,1,0]
	v_pk_mul_f32 v[78:79], v[78:79], v[160:161] op_sel_hi:[1,0]
	v_pk_fma_f32 v[86:87], v[84:85], v[86:87], s[66:67] op_sel_hi:[1,1,0]
	v_pk_mul_f32 v[74:75], v[74:75], v[160:161] op_sel_hi:[1,0]
	v_pk_mul_f32 v[84:85], v[84:85], v[86:87]
	v_pk_mul_f32 v[86:87], v[78:79], v[78:79]
	v_pk_mul_f32 v[84:85], v[88:89], v[84:85]
	v_pk_mul_f32 v[86:87], v[86:87], s[4:5] op_sel_hi:[1,0]
	v_pk_mul_f32 v[88:89], v[76:77], v[84:85]
	v_pk_fma_f32 v[84:85], v[76:77], v[84:85], v[76:77] neg_lo:[1,0,0] neg_hi:[1,0,0]
	v_exp_f32_e32 v86, v86
	v_cndmask_b32_e32 v76, v84, v88, vcc
	v_cmp_gt_f32_e32 vcc, 0, v77
	v_and_b32_e32 v84, 0x7fffffff, v78
	v_exp_f32_e32 v87, v87
	v_cndmask_b32_e32 v77, v85, v89, vcc
	v_and_b32_e32 v85, 0x7fffffff, v79
	v_pk_fma_f32 v[84:85], v[84:85], s[8:9], 1.0 op_sel_hi:[1,0,0]
	v_cmp_gt_f32_e32 vcc, 0, v78
	v_rcp_f32_e32 v84, v84
	v_rcp_f32_e32 v85, v85
	v_or_b32_e32 v80, 48, v142
	s_waitcnt lgkmcnt(0)
	v_ashrrev_i32_e32 v81, 31, v80
	v_lshlrev_b64 v[80:81], 12, v[80:81]
	v_pk_fma_f32 v[88:89], v[84:85], s[10:11], v[72:73] op_sel_hi:[1,0,0]
	v_lshl_add_u64 v[80:81], s[30:31], 0, v[80:81]
	v_pk_fma_f32 v[88:89], v[84:85], v[88:89], s[14:15] op_sel_hi:[1,1,0]
	v_lshl_add_u64 v[80:81], v[162:163], 1, v[80:81]
	v_pk_fma_f32 v[88:89], v[84:85], v[88:89], s[36:37] op_sel_hi:[1,1,0]
	v_pk_mul_f32 v[68:69], v[68:69], v[160:161] op_sel_hi:[1,0]
	v_pk_fma_f32 v[88:89], v[84:85], v[88:89], s[66:67] op_sel_hi:[1,1,0]
	v_pk_mul_f32 v[70:71], v[70:71], v[160:161] op_sel_hi:[1,0]
	v_pk_mul_f32 v[84:85], v[84:85], v[88:89]
	v_pk_mul_f32 v[88:89], v[82:83], v[82:83]
	v_pk_mul_f32 v[84:85], v[86:87], v[84:85]
	v_pk_mul_f32 v[88:89], v[88:89], s[4:5] op_sel_hi:[1,0]
	v_pk_mul_f32 v[86:87], v[78:79], v[84:85]
	v_pk_fma_f32 v[84:85], v[78:79], v[84:85], v[78:79] neg_lo:[1,0,0] neg_hi:[1,0,0]
	v_exp_f32_e32 v88, v88
	v_cndmask_b32_e32 v78, v84, v86, vcc
	v_cmp_gt_f32_e32 vcc, 0, v79
	v_and_b32_e32 v84, 0x7fffffff, v82
	v_exp_f32_e32 v89, v89
	v_cndmask_b32_e32 v79, v85, v87, vcc
	v_and_b32_e32 v85, 0x7fffffff, v83
	v_pk_fma_f32 v[84:85], v[84:85], s[8:9], 1.0 op_sel_hi:[1,0,0]
	v_cmp_gt_f32_e32 vcc, 0, v82
	v_rcp_f32_e32 v84, v84
	v_rcp_f32_e32 v85, v85
	v_pk_mul_f32 v[66:67], v[66:67], v[160:161] op_sel_hi:[1,0]
	v_pk_fma_f32 v[86:87], v[84:85], s[10:11], v[72:73] op_sel_hi:[1,0,0]
	s_nop 0
	v_pk_fma_f32 v[86:87], v[84:85], v[86:87], s[14:15] op_sel_hi:[1,1,0]
	s_nop 0
	v_pk_fma_f32 v[86:87], v[84:85], v[86:87], s[36:37] op_sel_hi:[1,1,0]
	s_nop 0
	v_pk_fma_f32 v[86:87], v[84:85], v[86:87], s[66:67] op_sel_hi:[1,1,0]
	s_nop 0
	v_pk_mul_f32 v[84:85], v[84:85], v[86:87]
	v_pk_mul_f32 v[86:87], v[74:75], v[74:75]
	v_pk_mul_f32 v[84:85], v[88:89], v[84:85]
	v_pk_mul_f32 v[86:87], v[86:87], s[4:5] op_sel_hi:[1,0]
	v_pk_mul_f32 v[88:89], v[82:83], v[84:85]
	v_pk_fma_f32 v[84:85], v[82:83], v[84:85], v[82:83] neg_lo:[1,0,0] neg_hi:[1,0,0]
	v_exp_f32_e32 v86, v86
	v_cndmask_b32_e32 v82, v84, v88, vcc
	v_cmp_gt_f32_e32 vcc, 0, v83
	v_and_b32_e32 v84, 0x7fffffff, v74
	v_exp_f32_e32 v87, v87
	v_cndmask_b32_e32 v83, v85, v89, vcc
	v_and_b32_e32 v85, 0x7fffffff, v75
	v_pk_fma_f32 v[84:85], v[84:85], s[8:9], 1.0 op_sel_hi:[1,0,0]
	v_cmp_gt_f32_e32 vcc, 0, v74
	v_rcp_f32_e32 v84, v84
	v_rcp_f32_e32 v85, v85
	s_nop 0
	v_pk_fma_f32 v[88:89], v[84:85], s[10:11], v[72:73] op_sel_hi:[1,0,0]
	s_nop 0
	v_pk_fma_f32 v[88:89], v[84:85], v[88:89], s[14:15] op_sel_hi:[1,1,0]
	s_nop 0
	v_pk_fma_f32 v[88:89], v[84:85], v[88:89], s[36:37] op_sel_hi:[1,1,0]
	s_nop 0
	v_pk_fma_f32 v[88:89], v[84:85], v[88:89], s[66:67] op_sel_hi:[1,1,0]
	s_nop 0
	v_pk_mul_f32 v[84:85], v[84:85], v[88:89]
	v_pk_mul_f32 v[88:89], v[68:69], v[68:69]
	v_pk_mul_f32 v[84:85], v[86:87], v[84:85]
	v_pk_mul_f32 v[88:89], v[88:89], s[4:5] op_sel_hi:[1,0]
	v_pk_mul_f32 v[86:87], v[74:75], v[84:85]
	v_pk_fma_f32 v[84:85], v[74:75], v[84:85], v[74:75] neg_lo:[1,0,0] neg_hi:[1,0,0]
	v_exp_f32_e32 v88, v88
	v_cndmask_b32_e32 v74, v84, v86, vcc
	v_cmp_gt_f32_e32 vcc, 0, v75
	v_cvt_pk_bf16_f32 v84, v76, v77
	v_exp_f32_e32 v89, v89
	s_nop 0
	v_cndmask_b32_e32 v75, v85, v87, vcc
	v_cvt_pk_bf16_f32 v85, v78, v79
	v_cvt_pk_bf16_f32 v86, v82, v83
	v_cvt_pk_bf16_f32 v87, v74, v75
	global_store_dwordx4 v[80:81], v[84:87], off nt
	v_cmp_gt_f32_e32 vcc, 0, v68
	s_nop 0
	v_pk_mul_f32 v[84:85], v[64:65], v[160:161] op_sel_hi:[1,0]
	v_and_b32_e32 v65, 0x7fffffff, v69
	v_and_b32_e32 v64, 0x7fffffff, v68
	v_pk_fma_f32 v[64:65], v[64:65], s[8:9], 1.0 op_sel_hi:[1,0,0]
	s_nop 0
; __device__ __forceinline__ unsigned long long f2ss(float v) { return (unsigned long long)(v * 16777216.0f); }
; __device__ __forceinline__ u32x4 pack8(f32x4 v0, f32x4 v1) { u32x4 w; w.x = cvt_pk_bf16(v0[0], v0[1]); w.y = cvt_pk_bf16(v0[2], v0[3]); w.z = cvt_pk_bf16(v1[0], v1[1]); w.w = cvt_pk_bf16(v1[2], v1[3]); return w; }
; __device__ __forceinline__ f32x2 gelu_pk(f32x2 v) {
;     const f32x2 av = __builtin_elementwise_abs(v), d = av * 0.2316418882f + 1.0f;
;     f32x2 t; t.x = __builtin_amdgcn_rcpf(d.x); t.y = __builtin_amdgcn_rcpf(d.y);
;     f32x2 q = t * 0.5307027145f + (-0.7265760135f); q = q * t + 0.7107068705f; q = q * t + (-0.142248368f); q = q * t + 0.127414796f; q = q * t;
;     const f32x2 s = (v * v) * (-0.72134752044f);
;     f32x2 e; e.x = __builtin_amdgcn_exp2f(s.x); e.y = __builtin_amdgcn_exp2f(s.y);
;     const f32x2 m = v * (q * e), r = v - m;
;     f32x2 o; o.x = v.x < 0.f ? m.x : r.x; o.y = v.y < 0.f ? m.y : r.y; return o;
;     __device__ __forceinline__ void operator()(const f32x4 (&acc)[2][2][4][2], const Unit& u, int wr, int wc, int fr, int fq, const Pre& pre) const {
;     ...
;                 for (int bj = 0; bj < 2; ++bj) { f32x4 v0 = acc[ai][bj][m][0] * r, v1 = acc[ai][bj][m][1] * r;
;                     f32x2 a = gelu_pk((f32x2){v0[0], v0[1]}), b = gelu_pk((f32x2){v0[2], v0[3]}), c = gelu_pk((f32x2){v1[0], v1[1]}), d = gelu_pk((f32x2){v1[2], v1[3]});
;                     v0 = (f32x4){a.x, a.y, b.x, b.y}; v1 = (f32x4){c.x, c.y, d.x, d.y};
;                     sq += (v0[0] * v0[0] + v0[1] * v0[1]) + (v0[2] * v0[2] + v0[3] * v0[3]) + (v1[0] * v1[0] + v1[1] * v1[1]) + (v1[2] * v1[2] + v1[3] * v1[3]);
;                     *(u32x4*)(rowp + bj * HALF) = pack8(v0, v1); }
;                 if (isv) { sq += __shfl_xor(sq, 16); sq += __shfl_xor(sq, 32); if (fq == 0) atomicAdd(vss + row, f2ss(sq)); } }
	v_rcp_f32_e32 v64, v64
	v_rcp_f32_e32 v65, v65
	s_nop 0
	v_pk_fma_f32 v[86:87], v[64:65], s[10:11], v[72:73] op_sel_hi:[1,0,0]
	s_nop 0
	v_pk_fma_f32 v[86:87], v[64:65], v[86:87], s[14:15] op_sel_hi:[1,1,0]
	s_nop 0
	v_pk_fma_f32 v[86:87], v[64:65], v[86:87], s[36:37] op_sel_hi:[1,1,0]
	s_nop 0
	v_pk_fma_f32 v[86:87], v[64:65], v[86:87], s[66:67] op_sel_hi:[1,1,0]
	s_nop 0
	v_pk_mul_f32 v[64:65], v[64:65], v[86:87]
	v_pk_mul_f32 v[86:87], v[70:71], v[70:71]
	v_pk_mul_f32 v[64:65], v[88:89], v[64:65]
	v_pk_mul_f32 v[86:87], v[86:87], s[4:5] op_sel_hi:[1,0]
	v_pk_mul_f32 v[88:89], v[68:69], v[64:65]
	v_pk_fma_f32 v[64:65], v[68:69], v[64:65], v[68:69] neg_lo:[1,0,0] neg_hi:[1,0,0]
	v_and_b32_e32 v68, 0x7fffffff, v70
	v_cndmask_b32_e32 v64, v64, v88, vcc
	v_cmp_gt_f32_e32 vcc, 0, v69
	v_and_b32_e32 v69, 0x7fffffff, v71
	v_pk_fma_f32 v[68:69], v[68:69], s[8:9], 1.0 op_sel_hi:[1,0,0]
	v_cndmask_b32_e32 v65, v65, v89, vcc
	v_rcp_f32_e32 v68, v68
	v_rcp_f32_e32 v69, v69
	v_exp_f32_e32 v86, v86
	v_exp_f32_e32 v87, v87
	v_cmp_gt_f32_e32 vcc, 0, v70
	v_pk_fma_f32 v[88:89], v[68:69], s[10:11], v[72:73] op_sel_hi:[1,0,0]
	s_nop 0
	v_pk_fma_f32 v[88:89], v[68:69], v[88:89], s[14:15] op_sel_hi:[1,1,0]
	s_nop 0
	v_pk_fma_f32 v[88:89], v[68:69], v[88:89], s[36:37] op_sel_hi:[1,1,0]
	s_nop 0
	v_pk_fma_f32 v[88:89], v[68:69], v[88:89], s[66:67] op_sel_hi:[1,1,0]
	s_nop 0
	v_pk_mul_f32 v[68:69], v[68:69], v[88:89]
	v_pk_mul_f32 v[88:89], v[84:85], v[84:85]
	v_pk_mul_f32 v[68:69], v[86:87], v[68:69]
	v_pk_mul_f32 v[88:89], v[88:89], s[4:5] op_sel_hi:[1,0]
	v_pk_mul_f32 v[86:87], v[70:71], v[68:69]
	v_pk_fma_f32 v[68:69], v[70:71], v[68:69], v[70:71] neg_lo:[1,0,0] neg_hi:[1,0,0]
	v_and_b32_e32 v70, 0x7fffffff, v84
	v_cndmask_b32_e32 v68, v68, v86, vcc
	v_cmp_gt_f32_e32 vcc, 0, v71
	v_and_b32_e32 v71, 0x7fffffff, v85
	v_pk_fma_f32 v[70:71], v[70:71], s[8:9], 1.0 op_sel_hi:[1,0,0]
	v_cndmask_b32_e32 v69, v69, v87, vcc
	v_rcp_f32_e32 v70, v70
	v_rcp_f32_e32 v71, v71
	v_exp_f32_e32 v88, v88
	v_exp_f32_e32 v89, v89
	v_cmp_gt_f32_e32 vcc, 0, v84
	v_pk_fma_f32 v[86:87], v[70:71], s[10:11], v[72:73] op_sel_hi:[1,0,0]
	s_nop 0
	v_pk_fma_f32 v[86:87], v[70:71], v[86:87], s[14:15] op_sel_hi:[1,1,0]
	s_nop 0
	v_pk_fma_f32 v[86:87], v[70:71], v[86:87], s[36:37] op_sel_hi:[1,1,0]
	s_nop 0
	v_pk_fma_f32 v[86:87], v[70:71], v[86:87], s[66:67] op_sel_hi:[1,1,0]
	s_nop 0
	v_pk_mul_f32 v[70:71], v[70:71], v[86:87]
	v_pk_mul_f32 v[86:87], v[66:67], v[66:67]
	v_pk_mul_f32 v[70:71], v[88:89], v[70:71]
	s_nop 0
	v_pk_mul_f32 v[88:89], v[84:85], v[70:71]
	v_pk_fma_f32 v[70:71], v[84:85], v[70:71], v[84:85] neg_lo:[1,0,0] neg_hi:[1,0,0]
	v_and_b32_e32 v84, 0x7fffffff, v66
	v_cndmask_b32_e32 v70, v70, v88, vcc
	v_cmp_gt_f32_e32 vcc, 0, v85
	v_and_b32_e32 v85, 0x7fffffff, v67
	v_pk_fma_f32 v[84:85], v[84:85], s[8:9], 1.0 op_sel_hi:[1,0,0]
	v_cndmask_b32_e32 v71, v71, v89, vcc
	v_rcp_f32_e32 v84, v84
	v_rcp_f32_e32 v85, v85
	v_cmp_gt_f32_e32 vcc, 0, v66
	v_pk_fma_f32 v[72:73], v[84:85], s[10:11], v[72:73] op_sel_hi:[1,0,0]
	s_nop 0
	v_pk_fma_f32 v[72:73], v[84:85], v[72:73], s[14:15] op_sel_hi:[1,1,0]
	s_nop 0
	v_pk_fma_f32 v[72:73], v[84:85], v[72:73], s[36:37] op_sel_hi:[1,1,0]
	s_nop 0
	v_pk_fma_f32 v[72:73], v[84:85], v[72:73], s[66:67] op_sel_hi:[1,1,0]
	s_nop 0
	v_pk_mul_f32 v[72:73], v[84:85], v[72:73]
	v_pk_mul_f32 v[84:85], v[86:87], s[4:5] op_sel_hi:[1,0]
	s_nop 0
	v_exp_f32_e32 v84, v84
	v_exp_f32_e32 v85, v85
	s_nop 0
	v_pk_mul_f32 v[72:73], v[84:85], v[72:73]
	s_nop 0
	v_pk_mul_f32 v[84:85], v[66:67], v[72:73]
	v_pk_fma_f32 v[72:73], v[66:67], v[72:73], v[66:67] neg_lo:[1,0,0] neg_hi:[1,0,0]
	s_nop 0
	v_cndmask_b32_e32 v66, v72, v84, vcc
	v_cmp_gt_f32_e32 vcc, 0, v67
	v_cvt_pk_bf16_f32 v84, v64, v65
	s_nop 1
	v_cndmask_b32_e32 v67, v73, v85, vcc
	s_and_b64 vcc, exec, s[44:45]
	v_cvt_pk_bf16_f32 v85, v68, v69
	v_cvt_pk_bf16_f32 v86, v70, v71
	v_cvt_pk_bf16_f32 v87, v66, v67
	global_store_dwordx4 v[80:81], v[84:87], off offset:256 nt
	s_cbranch_vccnz .LBB0_73
	v_mul_f32_e32 v72, v75, v75
	v_mul_f32_e32 v65, v65, v65
	v_fmac_f32_e32 v72, v74, v74
	v_mul_f32_e32 v73, v77, v77
	v_mul_f32_e32 v74, v79, v79
	v_fmac_f32_e32 v65, v64, v64
	v_mul_f32_e32 v64, v69, v69
	v_fmac_f32_e32 v73, v76, v76
	v_fmac_f32_e32 v74, v78, v78
	v_fmac_f32_e32 v64, v68, v68
	v_add_f32_e32 v73, v73, v74
	v_mul_f32_e32 v74, v83, v83
	v_add_f32_e32 v64, v65, v64
	v_mul_f32_e32 v65, v71, v71
	v_fmac_f32_e32 v74, v82, v82
	v_mul_f32_e32 v67, v67, v67
	v_fmac_f32_e32 v65, v70, v70
	v_add_f32_e32 v73, v74, v73
	v_fmac_f32_e32 v67, v66, v66
	v_add_f32_e32 v64, v65, v64
	v_add_f32_e32 v72, v72, v73
	v_add_f32_e32 v64, v67, v64
	v_add_f32_e32 v64, v72, v64
	ds_bpermute_b32 v65, v147, v64
	s_waitcnt lgkmcnt(0)
	v_add_f32_e32 v64, v64, v65
	ds_bpermute_b32 v65, v165, v64
	s_and_saveexec_b64 s[26:27], s[40:41]
	s_cbranch_execz .LBB0_72
	s_waitcnt lgkmcnt(0)
	v_add_f32_e32 v64, v64, v65
	v_mul_f32_e32 v64, 0x4b800000, v64
	v_trunc_f32_e32 v64, v64
	v_mul_f32_e32 v65, 0x2f800000, v64
	v_floor_f32_e32 v65, v65
	v_fmac_f32_e32 v64, 0xcf800000, v65
	v_cvt_u32_f32_e32 v64, v64
	v_cvt_u32_f32_e32 v65, v65
	v_lshl_add_u64 v[66:67], v[142:143], 3, s[52:53]
	global_atomic_add_x2 v[66:67], v[64:65], off offset:384

; __device__ __forceinline__ u32x4 pack8(f32x4 v0, f32x4 v1) { u32x4 w; w.x = cvt_pk_bf16(v0[0], v0[1]); w.y = cvt_pk_bf16(v0[2], v0[3]); w.z = cvt_pk_bf16(v1[0], v1[1]); w.w = cvt_pk_bf16(v1[2], v1[3]); return w; }
; __device__ __forceinline__ f32x2 gelu_pk(f32x2 v) {
;     const f32x2 av = __builtin_elementwise_abs(v), d = av * 0.2316418882f + 1.0f;
;     f32x2 t; t.x = __builtin_amdgcn_rcpf(d.x); t.y = __builtin_amdgcn_rcpf(d.y);
;     f32x2 q = t * 0.5307027145f + (-0.7265760135f); q = q * t + 0.7107068705f; q = q * t + (-0.142248368f); q = q * t + 0.127414796f; q = q * t;
;     const f32x2 s = (v * v) * (-0.72134752044f);
;     f32x2 e; e.x = __builtin_amdgcn_exp2f(s.x); e.y = __builtin_amdgcn_exp2f(s.y);
;     const f32x2 m = v * (q * e), r = v - m;
;     f32x2 o; o.x = v.x < 0.f ? m.x : r.x; o.y = v.y < 0.f ? m.y : r.y; return o;
;     __device__ __forceinline__ void operator()(const f32x4 (&acc)[2][2][4][2], const Unit& u, int wr, int wc, int fr, int fq, const Pre& pre) const {
;     ...
;             for (int m = 0; m < 4; ++m) { const int row = row0 + ai * HALF + m * 16; const float r = rs8[ai * 4 + m];
;                 bf16_t* rowp = O + (size_t)row * 2048 + col0; float sq = 0.f;
; #pragma unroll
;                 for (int bj = 0; bj < 2; ++bj) { f32x4 v0 = acc[ai][bj][m][0] * r, v1 = acc[ai][bj][m][1] * r;
;                     f32x2 a = gelu_pk((f32x2){v0[0], v0[1]}), b = gelu_pk((f32x2){v0[2], v0[3]}), c = gelu_pk((f32x2){v1[0], v1[1]}), d = gelu_pk((f32x2){v1[2], v1[3]});
;                     v0 = (f32x4){a.x, a.y, b.x, b.y}; v1 = (f32x4){c.x, c.y, d.x, d.y};
;                     sq += (v0[0] * v0[0] + v0[1] * v0[1]) + (v0[2] * v0[2] + v0[3] * v0[3]) + (v1[0] * v1[0] + v1[1] * v1[1]) + (v1[2] * v1[2] + v1[3] * v1[3]);
;                     *(u32x4*)(rowp + bj * HALF) = pack8(v0, v1); }
.LBB0_73:
	v_pk_mul_f32 v[60:61], v[60:61], v[158:159] op_sel_hi:[1,0]
	v_pk_mul_f32 v[66:67], v[56:57], v[158:159] op_sel_hi:[1,0]
	v_and_b32_e32 v57, 0x7fffffff, v61
	v_and_b32_e32 v56, 0x7fffffff, v60
	v_pk_fma_f32 v[56:57], v[56:57], s[8:9], 1.0 op_sel_hi:[1,0,0]
	s_mov_b64 s[20:21], 0x80000
	v_rcp_f32_e32 v68, v56
	v_rcp_f32_e32 v69, v57
	s_waitcnt lgkmcnt(0)
	v_lshl_add_u64 v[64:65], v[152:153], 0, s[20:21]
	v_mov_b64_e32 v[56:57], s[12:13]
	v_pk_mul_f32 v[72:73], v[60:61], v[60:61]
	s_mov_b32 s20, 0xbf38aa3b
	v_pk_fma_f32 v[70:71], v[68:69], s[10:11], v[56:57] op_sel_hi:[1,0,0]
	v_pk_mul_f32 v[72:73], v[72:73], s[20:21] op_sel_hi:[1,0]
	v_pk_fma_f32 v[70:71], v[68:69], v[70:71], s[14:15] op_sel_hi:[1,1,0]
	v_exp_f32_e32 v72, v72
	v_exp_f32_e32 v73, v73
	v_pk_fma_f32 v[70:71], v[68:69], v[70:71], s[36:37] op_sel_hi:[1,1,0]
	v_cmp_gt_f32_e32 vcc, 0, v60
	v_pk_fma_f32 v[70:71], v[68:69], v[70:71], s[66:67] op_sel_hi:[1,1,0]
	v_pk_mul_f32 v[62:63], v[62:63], v[158:159] op_sel_hi:[1,0]
	v_pk_mul_f32 v[68:69], v[68:69], v[70:71]
	v_pk_mul_f32 v[70:71], v[62:63], v[62:63]
	v_pk_mul_f32 v[68:69], v[72:73], v[68:69]
	v_pk_mul_f32 v[70:71], v[70:71], s[20:21] op_sel_hi:[1,0]
	v_pk_mul_f32 v[72:73], v[60:61], v[68:69]
	v_pk_fma_f32 v[68:69], v[60:61], v[68:69], v[60:61] neg_lo:[1,0,0] neg_hi:[1,0,0]
	v_exp_f32_e32 v70, v70
	v_cndmask_b32_e32 v60, v68, v72, vcc
	v_cmp_gt_f32_e32 vcc, 0, v61
	v_and_b32_e32 v68, 0x7fffffff, v62
	v_exp_f32_e32 v71, v71
	v_cndmask_b32_e32 v61, v69, v73, vcc
	v_and_b32_e32 v69, 0x7fffffff, v63
	v_pk_fma_f32 v[68:69], v[68:69], s[8:9], 1.0 op_sel_hi:[1,0,0]
	v_cmp_gt_f32_e32 vcc, 0, v62
	v_rcp_f32_e32 v68, v68
	v_rcp_f32_e32 v69, v69
	v_pk_mul_f32 v[58:59], v[58:59], v[158:159] op_sel_hi:[1,0]
	s_mov_b32 s4, 0x80000
	v_pk_mul_f32 v[52:53], v[52:53], v[158:159] op_sel_hi:[1,0]
	v_pk_fma_f32 v[72:73], v[68:69], s[10:11], v[56:57] op_sel_hi:[1,0,0]
	v_pk_mul_f32 v[54:55], v[54:55], v[158:159] op_sel_hi:[1,0]
	v_pk_fma_f32 v[72:73], v[68:69], v[72:73], s[14:15] op_sel_hi:[1,1,0]
	v_pk_mul_f32 v[50:51], v[50:51], v[158:159] op_sel_hi:[1,0]
	v_pk_fma_f32 v[72:73], v[68:69], v[72:73], s[36:37] op_sel_hi:[1,1,0]
	s_nop 0
	v_pk_fma_f32 v[72:73], v[68:69], v[72:73], s[66:67] op_sel_hi:[1,1,0]
	s_nop 0
	v_pk_mul_f32 v[68:69], v[68:69], v[72:73]
	v_pk_mul_f32 v[72:73], v[66:67], v[66:67]
	v_pk_mul_f32 v[68:69], v[70:71], v[68:69]
	v_pk_mul_f32 v[72:73], v[72:73], s[20:21] op_sel_hi:[1,0]
	v_pk_mul_f32 v[70:71], v[62:63], v[68:69]
	v_pk_fma_f32 v[68:69], v[62:63], v[68:69], v[62:63] neg_lo:[1,0,0] neg_hi:[1,0,0]
	v_exp_f32_e32 v72, v72
	v_cndmask_b32_e32 v62, v68, v70, vcc
	v_cmp_gt_f32_e32 vcc, 0, v63
	v_and_b32_e32 v68, 0x7fffffff, v66
	v_exp_f32_e32 v73, v73
	v_cndmask_b32_e32 v63, v69, v71, vcc
	v_and_b32_e32 v69, 0x7fffffff, v67
	v_pk_fma_f32 v[68:69], v[68:69], s[8:9], 1.0 op_sel_hi:[1,0,0]
	v_cmp_gt_f32_e32 vcc, 0, v66
	v_rcp_f32_e32 v68, v68
	v_rcp_f32_e32 v69, v69
	s_nop 0
	v_pk_fma_f32 v[70:71], v[68:69], s[10:11], v[56:57] op_sel_hi:[1,0,0]
	s_nop 0
	v_pk_fma_f32 v[70:71], v[68:69], v[70:71], s[14:15] op_sel_hi:[1,1,0]
	s_nop 0
	v_pk_fma_f32 v[70:71], v[68:69], v[70:71], s[36:37] op_sel_hi:[1,1,0]
	s_nop 0
	v_pk_fma_f32 v[70:71], v[68:69], v[70:71], s[66:67] op_sel_hi:[1,1,0]
	s_nop 0
	v_pk_mul_f32 v[68:69], v[68:69], v[70:71]
	v_pk_mul_f32 v[70:71], v[58:59], v[58:59]
	v_pk_mul_f32 v[68:69], v[72:73], v[68:69]
	v_pk_mul_f32 v[70:71], v[70:71], s[20:21] op_sel_hi:[1,0]
	v_pk_mul_f32 v[72:73], v[66:67], v[68:69]
	v_pk_fma_f32 v[68:69], v[66:67], v[68:69], v[66:67] neg_lo:[1,0,0] neg_hi:[1,0,0]
	v_exp_f32_e32 v70, v70
	v_cndmask_b32_e32 v66, v68, v72, vcc
	v_cmp_gt_f32_e32 vcc, 0, v67
	v_and_b32_e32 v68, 0x7fffffff, v58
	v_exp_f32_e32 v71, v71
	v_cndmask_b32_e32 v67, v69, v73, vcc
	v_and_b32_e32 v69, 0x7fffffff, v59
	v_pk_fma_f32 v[68:69], v[68:69], s[8:9], 1.0 op_sel_hi:[1,0,0]
	v_cmp_gt_f32_e32 vcc, 0, v58
	v_rcp_f32_e32 v68, v68
	v_rcp_f32_e32 v69, v69
	s_nop 0
	v_pk_fma_f32 v[72:73], v[68:69], s[10:11], v[56:57] op_sel_hi:[1,0,0]
	s_nop 0
	v_pk_fma_f32 v[72:73], v[68:69], v[72:73], s[14:15] op_sel_hi:[1,1,0]
	s_nop 0
	v_pk_fma_f32 v[72:73], v[68:69], v[72:73], s[36:37] op_sel_hi:[1,1,0]
	s_nop 0
	v_pk_fma_f32 v[72:73], v[68:69], v[72:73], s[66:67] op_sel_hi:[1,1,0]
	s_nop 0
	v_pk_mul_f32 v[68:69], v[68:69], v[72:73]
	s_nop 0
	v_pk_mul_f32 v[68:69], v[70:71], v[68:69]
	s_nop 0
	v_pk_mul_f32 v[70:71], v[58:59], v[68:69]
	v_pk_fma_f32 v[68:69], v[58:59], v[68:69], v[58:59] neg_lo:[1,0,0] neg_hi:[1,0,0]
	s_nop 0
	v_cndmask_b32_e32 v58, v68, v70, vcc
	v_cmp_gt_f32_e32 vcc, 0, v59
	v_cvt_pk_bf16_f32 v68, v60, v61
	s_nop 1
	v_cndmask_b32_e32 v59, v69, v71, vcc
	v_add_co_u32_e32 v72, vcc, s4, v152
	v_cvt_pk_bf16_f32 v69, v62, v63
	v_cvt_pk_bf16_f32 v70, v66, v67
	v_cvt_pk_bf16_f32 v71, v58, v59
	s_nop 1
	v_addc_co_u32_e32 v73, vcc, 0, v153, vcc
	global_store_dwordx4 v[72:73], v[68:71], off nt
	v_pk_mul_f32 v[72:73], v[52:53], v[52:53]
	v_cmp_gt_f32_e32 vcc, 0, v52
	v_pk_mul_f32 v[68:69], v[48:49], v[158:159] op_sel_hi:[1,0]
	v_and_b32_e32 v49, 0x7fffffff, v53
	v_and_b32_e32 v48, 0x7fffffff, v52
	v_pk_fma_f32 v[48:49], v[48:49], s[8:9], 1.0 op_sel_hi:[1,0,0]
	v_pk_mul_f32 v[72:73], v[72:73], s[20:21] op_sel_hi:[1,0]
	v_rcp_f32_e32 v48, v48
; __device__ __forceinline__ unsigned long long f2ss(float v) { return (unsigned long long)(v * 16777216.0f); }
; __device__ __forceinline__ u32x4 pack8(f32x4 v0, f32x4 v1) { u32x4 w; w.x = cvt_pk_bf16(v0[0], v0[1]); w.y = cvt_pk_bf16(v0[2], v0[3]); w.z = cvt_pk_bf16(v1[0], v1[1]); w.w = cvt_pk_bf16(v1[2], v1[3]); return w; }
; __device__ __forceinline__ f32x2 gelu_pk(f32x2 v) {
;     const f32x2 av = __builtin_elementwise_abs(v), d = av * 0.2316418882f + 1.0f;
;     f32x2 t; t.x = __builtin_amdgcn_rcpf(d.x); t.y = __builtin_amdgcn_rcpf(d.y);
;     f32x2 q = t * 0.5307027145f + (-0.7265760135f); q = q * t + 0.7107068705f; q = q * t + (-0.142248368f); q = q * t + 0.127414796f; q = q * t;
;     const f32x2 s = (v * v) * (-0.72134752044f);
;     f32x2 e; e.x = __builtin_amdgcn_exp2f(s.x); e.y = __builtin_amdgcn_exp2f(s.y);
;     const f32x2 m = v * (q * e), r = v - m;
;     f32x2 o; o.x = v.x < 0.f ? m.x : r.x; o.y = v.y < 0.f ? m.y : r.y; return o;
;     __device__ __forceinline__ void operator()(const f32x4 (&acc)[2][2][4][2], const Unit& u, int wr, int wc, int fr, int fq, const Pre& pre) const {
;     ...
;                 for (int bj = 0; bj < 2; ++bj) { f32x4 v0 = acc[ai][bj][m][0] * r, v1 = acc[ai][bj][m][1] * r;
;                     f32x2 a = gelu_pk((f32x2){v0[0], v0[1]}), b = gelu_pk((f32x2){v0[2], v0[3]}), c = gelu_pk((f32x2){v1[0], v1[1]}), d = gelu_pk((f32x2){v1[2], v1[3]});
;                     v0 = (f32x4){a.x, a.y, b.x, b.y}; v1 = (f32x4){c.x, c.y, d.x, d.y};
;                     sq += (v0[0] * v0[0] + v0[1] * v0[1]) + (v0[2] * v0[2] + v0[3] * v0[3]) + (v1[0] * v1[0] + v1[1] * v1[1]) + (v1[2] * v1[2] + v1[3] * v1[3]);
;                     *(u32x4*)(rowp + bj * HALF) = pack8(v0, v1); }
;                 if (isv) { sq += __shfl_xor(sq, 16); sq += __shfl_xor(sq, 32); if (fq == 0) atomicAdd(vss + row, f2ss(sq)); } }
	v_rcp_f32_e32 v49, v49
	v_exp_f32_e32 v72, v72
	v_exp_f32_e32 v73, v73
	v_pk_fma_f32 v[70:71], v[48:49], s[10:11], v[56:57] op_sel_hi:[1,0,0]
	s_nop 0
	v_pk_fma_f32 v[70:71], v[48:49], v[70:71], s[14:15] op_sel_hi:[1,1,0]
	s_nop 0
	v_pk_fma_f32 v[70:71], v[48:49], v[70:71], s[36:37] op_sel_hi:[1,1,0]
	s_nop 0
	v_pk_fma_f32 v[70:71], v[48:49], v[70:71], s[66:67] op_sel_hi:[1,1,0]
	s_nop 0
	v_pk_mul_f32 v[48:49], v[48:49], v[70:71]
	v_pk_mul_f32 v[70:71], v[54:55], v[54:55]
	v_pk_mul_f32 v[48:49], v[72:73], v[48:49]
	v_pk_mul_f32 v[70:71], v[70:71], s[20:21] op_sel_hi:[1,0]
	v_pk_mul_f32 v[72:73], v[52:53], v[48:49]
	v_pk_fma_f32 v[48:49], v[52:53], v[48:49], v[52:53] neg_lo:[1,0,0] neg_hi:[1,0,0]
	v_and_b32_e32 v52, 0x7fffffff, v54
	v_cndmask_b32_e32 v48, v48, v72, vcc
	v_cmp_gt_f32_e32 vcc, 0, v53
	v_and_b32_e32 v53, 0x7fffffff, v55
	v_pk_fma_f32 v[52:53], v[52:53], s[8:9], 1.0 op_sel_hi:[1,0,0]
	v_cndmask_b32_e32 v49, v49, v73, vcc
	v_rcp_f32_e32 v52, v52
	v_rcp_f32_e32 v53, v53
	v_exp_f32_e32 v70, v70
	v_exp_f32_e32 v71, v71
	v_cmp_gt_f32_e32 vcc, 0, v54
	v_pk_fma_f32 v[72:73], v[52:53], s[10:11], v[56:57] op_sel_hi:[1,0,0]
	s_nop 0
	v_pk_fma_f32 v[72:73], v[52:53], v[72:73], s[14:15] op_sel_hi:[1,1,0]
	s_nop 0
	v_pk_fma_f32 v[72:73], v[52:53], v[72:73], s[36:37] op_sel_hi:[1,1,0]
	s_nop 0
	v_pk_fma_f32 v[72:73], v[52:53], v[72:73], s[66:67] op_sel_hi:[1,1,0]
	s_nop 0
	v_pk_mul_f32 v[52:53], v[52:53], v[72:73]
	v_pk_mul_f32 v[72:73], v[68:69], v[68:69]
	v_pk_mul_f32 v[52:53], v[70:71], v[52:53]
	v_pk_mul_f32 v[72:73], v[72:73], s[20:21] op_sel_hi:[1,0]
	v_pk_mul_f32 v[70:71], v[54:55], v[52:53]
	v_pk_fma_f32 v[52:53], v[54:55], v[52:53], v[54:55] neg_lo:[1,0,0] neg_hi:[1,0,0]
	v_and_b32_e32 v54, 0x7fffffff, v68
	v_cndmask_b32_e32 v52, v52, v70, vcc
	v_cmp_gt_f32_e32 vcc, 0, v55
	v_and_b32_e32 v55, 0x7fffffff, v69
	v_pk_fma_f32 v[54:55], v[54:55], s[8:9], 1.0 op_sel_hi:[1,0,0]
	v_cndmask_b32_e32 v53, v53, v71, vcc
	v_rcp_f32_e32 v54, v54
	v_rcp_f32_e32 v55, v55
	v_exp_f32_e32 v72, v72
	v_exp_f32_e32 v73, v73
	v_cmp_gt_f32_e32 vcc, 0, v68
	v_pk_fma_f32 v[70:71], v[54:55], s[10:11], v[56:57] op_sel_hi:[1,0,0]
	s_nop 0
	v_pk_fma_f32 v[70:71], v[54:55], v[70:71], s[14:15] op_sel_hi:[1,1,0]
	s_nop 0
	v_pk_fma_f32 v[70:71], v[54:55], v[70:71], s[36:37] op_sel_hi:[1,1,0]
	s_nop 0
	v_pk_fma_f32 v[70:71], v[54:55], v[70:71], s[66:67] op_sel_hi:[1,1,0]
	s_nop 0
	v_pk_mul_f32 v[54:55], v[54:55], v[70:71]
	v_pk_mul_f32 v[70:71], v[50:51], v[50:51]
	v_pk_mul_f32 v[54:55], v[72:73], v[54:55]
	s_nop 0
	v_pk_mul_f32 v[72:73], v[68:69], v[54:55]
	v_pk_fma_f32 v[54:55], v[68:69], v[54:55], v[68:69] neg_lo:[1,0,0] neg_hi:[1,0,0]
	v_and_b32_e32 v68, 0x7fffffff, v50
	v_cndmask_b32_e32 v54, v54, v72, vcc
	v_cmp_gt_f32_e32 vcc, 0, v69
	v_and_b32_e32 v69, 0x7fffffff, v51
	v_pk_fma_f32 v[68:69], v[68:69], s[8:9], 1.0 op_sel_hi:[1,0,0]
	v_cndmask_b32_e32 v55, v55, v73, vcc
	v_rcp_f32_e32 v68, v68
	v_rcp_f32_e32 v69, v69
	v_cmp_gt_f32_e32 vcc, 0, v50
	v_pk_fma_f32 v[56:57], v[68:69], s[10:11], v[56:57] op_sel_hi:[1,0,0]
	s_nop 0
	v_pk_fma_f32 v[56:57], v[68:69], v[56:57], s[14:15] op_sel_hi:[1,1,0]
	s_nop 0
	v_pk_fma_f32 v[56:57], v[68:69], v[56:57], s[36:37] op_sel_hi:[1,1,0]
	s_nop 0
	v_pk_fma_f32 v[56:57], v[68:69], v[56:57], s[66:67] op_sel_hi:[1,1,0]
	s_nop 0
	v_pk_mul_f32 v[56:57], v[68:69], v[56:57]
	v_pk_mul_f32 v[68:69], v[70:71], s[20:21] op_sel_hi:[1,0]
	s_nop 0
	v_exp_f32_e32 v68, v68
	v_exp_f32_e32 v69, v69
	s_nop 0
	v_pk_mul_f32 v[56:57], v[68:69], v[56:57]
	s_nop 0
	v_pk_mul_f32 v[68:69], v[50:51], v[56:57]
	v_pk_fma_f32 v[56:57], v[50:51], v[56:57], v[50:51] neg_lo:[1,0,0] neg_hi:[1,0,0]
	s_nop 0
	v_cndmask_b32_e32 v50, v56, v68, vcc
	v_cmp_gt_f32_e32 vcc, 0, v51
	v_cvt_pk_bf16_f32 v68, v48, v49
	s_nop 1
	v_cndmask_b32_e32 v51, v57, v69, vcc
	s_and_b64 vcc, exec, s[44:45]
	v_cvt_pk_bf16_f32 v69, v52, v53
	v_cvt_pk_bf16_f32 v70, v54, v55
	v_cvt_pk_bf16_f32 v71, v50, v51
	global_store_dwordx4 v[64:65], v[68:71], off offset:256 nt
	s_cbranch_vccnz .LBB0_77
	v_mul_f32_e32 v56, v59, v59
	v_mul_f32_e32 v49, v49, v49
	v_fmac_f32_e32 v56, v58, v58
	v_mul_f32_e32 v57, v61, v61
	v_mul_f32_e32 v58, v63, v63
	v_fmac_f32_e32 v49, v48, v48
	v_mul_f32_e32 v48, v53, v53
	v_fmac_f32_e32 v57, v60, v60
	v_fmac_f32_e32 v58, v62, v62
	v_fmac_f32_e32 v48, v52, v52
	v_add_f32_e32 v57, v57, v58
	v_mul_f32_e32 v58, v67, v67
	v_add_f32_e32 v48, v49, v48
	v_mul_f32_e32 v49, v55, v55
	v_fmac_f32_e32 v58, v66, v66
	v_mul_f32_e32 v51, v51, v51
	v_fmac_f32_e32 v49, v54, v54
	v_add_f32_e32 v57, v58, v57
	v_fmac_f32_e32 v51, v50, v50
	v_add_f32_e32 v48, v49, v48
	v_add_f32_e32 v56, v56, v57
	v_add_f32_e32 v48, v51, v48
	v_add_f32_e32 v48, v56, v48
	ds_bpermute_b32 v49, v147, v48
	s_waitcnt lgkmcnt(0)
	v_add_f32_e32 v48, v48, v49
	ds_bpermute_b32 v49, v165, v48
	s_and_saveexec_b64 s[26:27], s[40:41]
	s_cbranch_execz .LBB0_76
	s_waitcnt lgkmcnt(0)
	v_add_f32_e32 v48, v48, v49
	v_mul_f32_e32 v48, 0x4b800000, v48
	v_trunc_f32_e32 v48, v48
	v_mul_f32_e32 v49, 0x2f800000, v48
	v_floor_f32_e32 v49, v49
	v_fmac_f32_e32 v48, 0xcf800000, v49
	v_cvt_u32_f32_e32 v48, v48
	v_cvt_u32_f32_e32 v49, v49
	v_lshl_add_u64 v[50:51], v[142:143], 3, s[52:53]
	global_atomic_add_x2 v[50:51], v[48:49], off offset:1024

; __device__ __forceinline__ u32x4 pack8(f32x4 v0, f32x4 v1) { u32x4 w; w.x = cvt_pk_bf16(v0[0], v0[1]); w.y = cvt_pk_bf16(v0[2], v0[3]); w.z = cvt_pk_bf16(v1[0], v1[1]); w.w = cvt_pk_bf16(v1[2], v1[3]); return w; }
; __device__ __forceinline__ f32x2 gelu_pk(f32x2 v) {
;     const f32x2 av = __builtin_elementwise_abs(v), d = av * 0.2316418882f + 1.0f;
;     f32x2 t; t.x = __builtin_amdgcn_rcpf(d.x); t.y = __builtin_amdgcn_rcpf(d.y);
;     f32x2 q = t * 0.5307027145f + (-0.7265760135f); q = q * t + 0.7107068705f; q = q * t + (-0.142248368f); q = q * t + 0.127414796f; q = q * t;
;     const f32x2 s = (v * v) * (-0.72134752044f);
;     f32x2 e; e.x = __builtin_amdgcn_exp2f(s.x); e.y = __builtin_amdgcn_exp2f(s.y);
;     const f32x2 m = v * (q * e), r = v - m;
;     f32x2 o; o.x = v.x < 0.f ? m.x : r.x; o.y = v.y < 0.f ? m.y : r.y; return o;
;     __device__ __forceinline__ void operator()(const f32x4 (&acc)[2][2][4][2], const Unit& u, int wr, int wc, int fr, int fq, const Pre& pre) const {
;     ...
;             for (int m = 0; m < 4; ++m) { const int row = row0 + ai * HALF + m * 16; const float r = rs8[ai * 4 + m];
;                 bf16_t* rowp = O + (size_t)row * 2048 + col0; float sq = 0.f;
; #pragma unroll
;                 for (int bj = 0; bj < 2; ++bj) { f32x4 v0 = acc[ai][bj][m][0] * r, v1 = acc[ai][bj][m][1] * r;
;                     f32x2 a = gelu_pk((f32x2){v0[0], v0[1]}), b = gelu_pk((f32x2){v0[2], v0[3]}), c = gelu_pk((f32x2){v1[0], v1[1]}), d = gelu_pk((f32x2){v1[2], v1[3]});
;                     v0 = (f32x4){a.x, a.y, b.x, b.y}; v1 = (f32x4){c.x, c.y, d.x, d.y};
;                     sq += (v0[0] * v0[0] + v0[1] * v0[1]) + (v0[2] * v0[2] + v0[3] * v0[3]) + (v1[0] * v1[0] + v1[1] * v1[1]) + (v1[2] * v1[2] + v1[3] * v1[3]);
;                     *(u32x4*)(rowp + bj * HALF) = pack8(v0, v1); }
.LBB0_77:
	v_pk_mul_f32 v[44:45], v[44:45], v[156:157] op_sel_hi:[1,0]
	v_pk_mul_f32 v[50:51], v[40:41], v[156:157] op_sel_hi:[1,0]
	v_and_b32_e32 v41, 0x7fffffff, v45
	v_and_b32_e32 v40, 0x7fffffff, v44
	v_pk_fma_f32 v[40:41], v[40:41], s[8:9], 1.0 op_sel_hi:[1,0,0]
	s_mov_b64 s[20:21], 0x90000
	v_rcp_f32_e32 v52, v40
	v_rcp_f32_e32 v53, v41
	s_waitcnt lgkmcnt(0)
	v_lshl_add_u64 v[48:49], v[152:153], 0, s[20:21]
	v_mov_b64_e32 v[40:41], s[12:13]
	v_pk_mul_f32 v[56:57], v[44:45], v[44:45]
	s_mov_b32 s20, 0xbf38aa3b
	v_pk_fma_f32 v[54:55], v[52:53], s[10:11], v[40:41] op_sel_hi:[1,0,0]
	v_pk_mul_f32 v[56:57], v[56:57], s[20:21] op_sel_hi:[1,0]
	v_pk_fma_f32 v[54:55], v[52:53], v[54:55], s[14:15] op_sel_hi:[1,1,0]
	v_exp_f32_e32 v56, v56
	v_exp_f32_e32 v57, v57
	v_pk_fma_f32 v[54:55], v[52:53], v[54:55], s[36:37] op_sel_hi:[1,1,0]
	v_cmp_gt_f32_e32 vcc, 0, v44
	v_pk_fma_f32 v[54:55], v[52:53], v[54:55], s[66:67] op_sel_hi:[1,1,0]
	v_pk_mul_f32 v[46:47], v[46:47], v[156:157] op_sel_hi:[1,0]
	v_pk_mul_f32 v[52:53], v[52:53], v[54:55]
	v_pk_mul_f32 v[54:55], v[46:47], v[46:47]
	v_pk_mul_f32 v[52:53], v[56:57], v[52:53]
	v_pk_mul_f32 v[54:55], v[54:55], s[20:21] op_sel_hi:[1,0]
	v_pk_mul_f32 v[56:57], v[44:45], v[52:53]
	v_pk_fma_f32 v[52:53], v[44:45], v[52:53], v[44:45] neg_lo:[1,0,0] neg_hi:[1,0,0]
	v_exp_f32_e32 v54, v54
	v_cndmask_b32_e32 v44, v52, v56, vcc
	v_cmp_gt_f32_e32 vcc, 0, v45
	v_and_b32_e32 v52, 0x7fffffff, v46
	v_exp_f32_e32 v55, v55
	v_cndmask_b32_e32 v45, v53, v57, vcc
	v_and_b32_e32 v53, 0x7fffffff, v47
	v_pk_fma_f32 v[52:53], v[52:53], s[8:9], 1.0 op_sel_hi:[1,0,0]
	v_cmp_gt_f32_e32 vcc, 0, v46
	v_rcp_f32_e32 v52, v52
	v_rcp_f32_e32 v53, v53
	v_pk_mul_f32 v[42:43], v[42:43], v[156:157] op_sel_hi:[1,0]
	s_mov_b32 s4, 0x90000
	v_pk_mul_f32 v[36:37], v[36:37], v[156:157] op_sel_hi:[1,0]
	v_pk_fma_f32 v[56:57], v[52:53], s[10:11], v[40:41] op_sel_hi:[1,0,0]
	v_pk_mul_f32 v[38:39], v[38:39], v[156:157] op_sel_hi:[1,0]
	v_pk_fma_f32 v[56:57], v[52:53], v[56:57], s[14:15] op_sel_hi:[1,1,0]
	v_pk_mul_f32 v[34:35], v[34:35], v[156:157] op_sel_hi:[1,0]
	v_pk_fma_f32 v[56:57], v[52:53], v[56:57], s[36:37] op_sel_hi:[1,1,0]
	s_nop 0
	v_pk_fma_f32 v[56:57], v[52:53], v[56:57], s[66:67] op_sel_hi:[1,1,0]
	s_nop 0
	v_pk_mul_f32 v[52:53], v[52:53], v[56:57]
	v_pk_mul_f32 v[56:57], v[50:51], v[50:51]
	v_pk_mul_f32 v[52:53], v[54:55], v[52:53]
	v_pk_mul_f32 v[56:57], v[56:57], s[20:21] op_sel_hi:[1,0]
	v_pk_mul_f32 v[54:55], v[46:47], v[52:53]
	v_pk_fma_f32 v[52:53], v[46:47], v[52:53], v[46:47] neg_lo:[1,0,0] neg_hi:[1,0,0]
	v_exp_f32_e32 v56, v56
	v_cndmask_b32_e32 v46, v52, v54, vcc
	v_cmp_gt_f32_e32 vcc, 0, v47
	v_and_b32_e32 v52, 0x7fffffff, v50
	v_exp_f32_e32 v57, v57
	v_cndmask_b32_e32 v47, v53, v55, vcc
	v_and_b32_e32 v53, 0x7fffffff, v51
	v_pk_fma_f32 v[52:53], v[52:53], s[8:9], 1.0 op_sel_hi:[1,0,0]
	v_cmp_gt_f32_e32 vcc, 0, v50
	v_rcp_f32_e32 v52, v52
	v_rcp_f32_e32 v53, v53
	s_nop 0
	v_pk_fma_f32 v[54:55], v[52:53], s[10:11], v[40:41] op_sel_hi:[1,0,0]
	s_nop 0
	v_pk_fma_f32 v[54:55], v[52:53], v[54:55], s[14:15] op_sel_hi:[1,1,0]
	s_nop 0
	v_pk_fma_f32 v[54:55], v[52:53], v[54:55], s[36:37] op_sel_hi:[1,1,0]
	s_nop 0
	v_pk_fma_f32 v[54:55], v[52:53], v[54:55], s[66:67] op_sel_hi:[1,1,0]
	s_nop 0
	v_pk_mul_f32 v[52:53], v[52:53], v[54:55]
	v_pk_mul_f32 v[54:55], v[42:43], v[42:43]
	v_pk_mul_f32 v[52:53], v[56:57], v[52:53]
	v_pk_mul_f32 v[54:55], v[54:55], s[20:21] op_sel_hi:[1,0]
	v_pk_mul_f32 v[56:57], v[50:51], v[52:53]
	v_pk_fma_f32 v[52:53], v[50:51], v[52:53], v[50:51] neg_lo:[1,0,0] neg_hi:[1,0,0]
	v_exp_f32_e32 v54, v54
	v_cndmask_b32_e32 v50, v52, v56, vcc
	v_cmp_gt_f32_e32 vcc, 0, v51
	v_and_b32_e32 v52, 0x7fffffff, v42
	v_exp_f32_e32 v55, v55
	v_cndmask_b32_e32 v51, v53, v57, vcc
	v_and_b32_e32 v53, 0x7fffffff, v43
	v_pk_fma_f32 v[52:53], v[52:53], s[8:9], 1.0 op_sel_hi:[1,0,0]
	v_cmp_gt_f32_e32 vcc, 0, v42
	v_rcp_f32_e32 v52, v52
	v_rcp_f32_e32 v53, v53
	s_nop 0
	v_pk_fma_f32 v[56:57], v[52:53], s[10:11], v[40:41] op_sel_hi:[1,0,0]
	s_nop 0
	v_pk_fma_f32 v[56:57], v[52:53], v[56:57], s[14:15] op_sel_hi:[1,1,0]
	s_nop 0
	v_pk_fma_f32 v[56:57], v[52:53], v[56:57], s[36:37] op_sel_hi:[1,1,0]
	s_nop 0
	v_pk_fma_f32 v[56:57], v[52:53], v[56:57], s[66:67] op_sel_hi:[1,1,0]
	s_nop 0
	v_pk_mul_f32 v[52:53], v[52:53], v[56:57]
	s_nop 0
	v_pk_mul_f32 v[52:53], v[54:55], v[52:53]
	s_nop 0
	v_pk_mul_f32 v[54:55], v[42:43], v[52:53]
	v_pk_fma_f32 v[52:53], v[42:43], v[52:53], v[42:43] neg_lo:[1,0,0] neg_hi:[1,0,0]
	s_nop 0
	v_cndmask_b32_e32 v42, v52, v54, vcc
	v_cmp_gt_f32_e32 vcc, 0, v43
	v_cvt_pk_bf16_f32 v52, v44, v45
	s_nop 1
	v_cndmask_b32_e32 v43, v53, v55, vcc
	v_add_co_u32_e32 v56, vcc, s4, v152
	v_cvt_pk_bf16_f32 v53, v46, v47
	v_cvt_pk_bf16_f32 v54, v50, v51
	v_cvt_pk_bf16_f32 v55, v42, v43
	s_nop 1
	v_addc_co_u32_e32 v57, vcc, 0, v153, vcc
	global_store_dwordx4 v[56:57], v[52:55], off nt
	v_pk_mul_f32 v[56:57], v[36:37], v[36:37]
	v_cmp_gt_f32_e32 vcc, 0, v36
	v_pk_mul_f32 v[52:53], v[32:33], v[156:157] op_sel_hi:[1,0]
	v_and_b32_e32 v33, 0x7fffffff, v37
	v_and_b32_e32 v32, 0x7fffffff, v36
	v_pk_fma_f32 v[32:33], v[32:33], s[8:9], 1.0 op_sel_hi:[1,0,0]
	v_pk_mul_f32 v[56:57], v[56:57], s[20:21] op_sel_hi:[1,0]
	v_rcp_f32_e32 v32, v32
; __device__ __forceinline__ unsigned long long f2ss(float v) { return (unsigned long long)(v * 16777216.0f); }
; __device__ __forceinline__ u32x4 pack8(f32x4 v0, f32x4 v1) { u32x4 w; w.x = cvt_pk_bf16(v0[0], v0[1]); w.y = cvt_pk_bf16(v0[2], v0[3]); w.z = cvt_pk_bf16(v1[0], v1[1]); w.w = cvt_pk_bf16(v1[2], v1[3]); return w; }
; __device__ __forceinline__ f32x2 gelu_pk(f32x2 v) {
;     const f32x2 av = __builtin_elementwise_abs(v), d = av * 0.2316418882f + 1.0f;
;     f32x2 t; t.x = __builtin_amdgcn_rcpf(d.x); t.y = __builtin_amdgcn_rcpf(d.y);
;     f32x2 q = t * 0.5307027145f + (-0.7265760135f); q = q * t + 0.7107068705f; q = q * t + (-0.142248368f); q = q * t + 0.127414796f; q = q * t;
;     const f32x2 s = (v * v) * (-0.72134752044f);
;     f32x2 e; e.x = __builtin_amdgcn_exp2f(s.x); e.y = __builtin_amdgcn_exp2f(s.y);
;     const f32x2 m = v * (q * e), r = v - m;
;     f32x2 o; o.x = v.x < 0.f ? m.x : r.x; o.y = v.y < 0.f ? m.y : r.y; return o;
;     __device__ __forceinline__ void operator()(const f32x4 (&acc)[2][2][4][2], const Unit& u, int wr, int wc, int fr, int fq, const Pre& pre) const {
;     ...
;                 for (int bj = 0; bj < 2; ++bj) { f32x4 v0 = acc[ai][bj][m][0] * r, v1 = acc[ai][bj][m][1] * r;
;                     f32x2 a = gelu_pk((f32x2){v0[0], v0[1]}), b = gelu_pk((f32x2){v0[2], v0[3]}), c = gelu_pk((f32x2){v1[0], v1[1]}), d = gelu_pk((f32x2){v1[2], v1[3]});
;                     v0 = (f32x4){a.x, a.y, b.x, b.y}; v1 = (f32x4){c.x, c.y, d.x, d.y};
;                     sq += (v0[0] * v0[0] + v0[1] * v0[1]) + (v0[2] * v0[2] + v0[3] * v0[3]) + (v1[0] * v1[0] + v1[1] * v1[1]) + (v1[2] * v1[2] + v1[3] * v1[3]);
;                     *(u32x4*)(rowp + bj * HALF) = pack8(v0, v1); }
;                 if (isv) { sq += __shfl_xor(sq, 16); sq += __shfl_xor(sq, 32); if (fq == 0) atomicAdd(vss + row, f2ss(sq)); } }
	v_rcp_f32_e32 v33, v33
	v_exp_f32_e32 v56, v56
	v_exp_f32_e32 v57, v57
	v_pk_fma_f32 v[54:55], v[32:33], s[10:11], v[40:41] op_sel_hi:[1,0,0]
	s_nop 0
	v_pk_fma_f32 v[54:55], v[32:33], v[54:55], s[14:15] op_sel_hi:[1,1,0]
	s_nop 0
	v_pk_fma_f32 v[54:55], v[32:33], v[54:55], s[36:37] op_sel_hi:[1,1,0]
	s_nop 0
	v_pk_fma_f32 v[54:55], v[32:33], v[54:55], s[66:67] op_sel_hi:[1,1,0]
	s_nop 0
	v_pk_mul_f32 v[32:33], v[32:33], v[54:55]
	v_pk_mul_f32 v[54:55], v[38:39], v[38:39]
	v_pk_mul_f32 v[32:33], v[56:57], v[32:33]
	v_pk_mul_f32 v[54:55], v[54:55], s[20:21] op_sel_hi:[1,0]
	v_pk_mul_f32 v[56:57], v[36:37], v[32:33]
	v_pk_fma_f32 v[32:33], v[36:37], v[32:33], v[36:37] neg_lo:[1,0,0] neg_hi:[1,0,0]
	v_and_b32_e32 v36, 0x7fffffff, v38
	v_cndmask_b32_e32 v32, v32, v56, vcc
	v_cmp_gt_f32_e32 vcc, 0, v37
	v_and_b32_e32 v37, 0x7fffffff, v39
	v_pk_fma_f32 v[36:37], v[36:37], s[8:9], 1.0 op_sel_hi:[1,0,0]
	v_cndmask_b32_e32 v33, v33, v57, vcc
	v_rcp_f32_e32 v36, v36
	v_rcp_f32_e32 v37, v37
	v_exp_f32_e32 v54, v54
	v_exp_f32_e32 v55, v55
	v_cmp_gt_f32_e32 vcc, 0, v38
	v_pk_fma_f32 v[56:57], v[36:37], s[10:11], v[40:41] op_sel_hi:[1,0,0]
	s_nop 0
	v_pk_fma_f32 v[56:57], v[36:37], v[56:57], s[14:15] op_sel_hi:[1,1,0]
	s_nop 0
	v_pk_fma_f32 v[56:57], v[36:37], v[56:57], s[36:37] op_sel_hi:[1,1,0]
	s_nop 0
	v_pk_fma_f32 v[56:57], v[36:37], v[56:57], s[66:67] op_sel_hi:[1,1,0]
	s_nop 0
	v_pk_mul_f32 v[36:37], v[36:37], v[56:57]
	v_pk_mul_f32 v[56:57], v[52:53], v[52:53]
	v_pk_mul_f32 v[36:37], v[54:55], v[36:37]
	v_pk_mul_f32 v[56:57], v[56:57], s[20:21] op_sel_hi:[1,0]
	v_pk_mul_f32 v[54:55], v[38:39], v[36:37]
	v_pk_fma_f32 v[36:37], v[38:39], v[36:37], v[38:39] neg_lo:[1,0,0] neg_hi:[1,0,0]
	v_and_b32_e32 v38, 0x7fffffff, v52
	v_cndmask_b32_e32 v36, v36, v54, vcc
	v_cmp_gt_f32_e32 vcc, 0, v39
	v_and_b32_e32 v39, 0x7fffffff, v53
	v_pk_fma_f32 v[38:39], v[38:39], s[8:9], 1.0 op_sel_hi:[1,0,0]
	v_cndmask_b32_e32 v37, v37, v55, vcc
	v_rcp_f32_e32 v38, v38
	v_rcp_f32_e32 v39, v39
	v_exp_f32_e32 v56, v56
	v_exp_f32_e32 v57, v57
	v_cmp_gt_f32_e32 vcc, 0, v52
	v_pk_fma_f32 v[54:55], v[38:39], s[10:11], v[40:41] op_sel_hi:[1,0,0]
	s_nop 0
	v_pk_fma_f32 v[54:55], v[38:39], v[54:55], s[14:15] op_sel_hi:[1,1,0]
	s_nop 0
	v_pk_fma_f32 v[54:55], v[38:39], v[54:55], s[36:37] op_sel_hi:[1,1,0]
	s_nop 0
	v_pk_fma_f32 v[54:55], v[38:39], v[54:55], s[66:67] op_sel_hi:[1,1,0]
	s_nop 0
	v_pk_mul_f32 v[38:39], v[38:39], v[54:55]
	v_pk_mul_f32 v[54:55], v[34:35], v[34:35]
	v_pk_mul_f32 v[38:39], v[56:57], v[38:39]
	s_nop 0
	v_pk_mul_f32 v[56:57], v[52:53], v[38:39]
	v_pk_fma_f32 v[38:39], v[52:53], v[38:39], v[52:53] neg_lo:[1,0,0] neg_hi:[1,0,0]
	v_and_b32_e32 v52, 0x7fffffff, v34
	v_cndmask_b32_e32 v38, v38, v56, vcc
	v_cmp_gt_f32_e32 vcc, 0, v53
	v_and_b32_e32 v53, 0x7fffffff, v35
	v_pk_fma_f32 v[52:53], v[52:53], s[8:9], 1.0 op_sel_hi:[1,0,0]
	v_cndmask_b32_e32 v39, v39, v57, vcc
	v_rcp_f32_e32 v52, v52
	v_rcp_f32_e32 v53, v53
	v_cmp_gt_f32_e32 vcc, 0, v34
	v_pk_fma_f32 v[40:41], v[52:53], s[10:11], v[40:41] op_sel_hi:[1,0,0]
	s_nop 0
	v_pk_fma_f32 v[40:41], v[52:53], v[40:41], s[14:15] op_sel_hi:[1,1,0]
	s_nop 0
	v_pk_fma_f32 v[40:41], v[52:53], v[40:41], s[36:37] op_sel_hi:[1,1,0]
	s_nop 0
	v_pk_fma_f32 v[40:41], v[52:53], v[40:41], s[66:67] op_sel_hi:[1,1,0]
	s_nop 0
	v_pk_mul_f32 v[40:41], v[52:53], v[40:41]
	v_pk_mul_f32 v[52:53], v[54:55], s[20:21] op_sel_hi:[1,0]
	s_nop 0
	v_exp_f32_e32 v52, v52
	v_exp_f32_e32 v53, v53
	s_nop 0
	v_pk_mul_f32 v[40:41], v[52:53], v[40:41]
	s_nop 0
	v_pk_mul_f32 v[52:53], v[34:35], v[40:41]
	v_pk_fma_f32 v[40:41], v[34:35], v[40:41], v[34:35] neg_lo:[1,0,0] neg_hi:[1,0,0]
	s_nop 0
	v_cndmask_b32_e32 v34, v40, v52, vcc
	v_cmp_gt_f32_e32 vcc, 0, v35
	v_cvt_pk_bf16_f32 v52, v32, v33
	s_nop 1
	v_cndmask_b32_e32 v35, v41, v53, vcc
	s_and_b64 vcc, exec, s[44:45]
	v_cvt_pk_bf16_f32 v53, v36, v37
	v_cvt_pk_bf16_f32 v54, v38, v39
	v_cvt_pk_bf16_f32 v55, v34, v35
	global_store_dwordx4 v[48:49], v[52:55], off offset:256 nt
	s_cbranch_vccnz .LBB0_81
	v_mul_f32_e32 v40, v43, v43
	v_mul_f32_e32 v33, v33, v33
	v_fmac_f32_e32 v40, v42, v42
	v_mul_f32_e32 v41, v45, v45
	v_mul_f32_e32 v42, v47, v47
	v_fmac_f32_e32 v33, v32, v32
	v_mul_f32_e32 v32, v37, v37
	v_fmac_f32_e32 v41, v44, v44
	v_fmac_f32_e32 v42, v46, v46
	v_fmac_f32_e32 v32, v36, v36
	v_add_f32_e32 v41, v41, v42
	v_mul_f32_e32 v42, v51, v51
	v_add_f32_e32 v32, v33, v32
	v_mul_f32_e32 v33, v39, v39
	v_fmac_f32_e32 v42, v50, v50
	v_mul_f32_e32 v35, v35, v35
	v_fmac_f32_e32 v33, v38, v38
	v_add_f32_e32 v41, v42, v41
	v_fmac_f32_e32 v35, v34, v34
	v_add_f32_e32 v32, v33, v32
	v_add_f32_e32 v40, v40, v41
	v_add_f32_e32 v32, v35, v32
	v_add_f32_e32 v32, v40, v32
	ds_bpermute_b32 v33, v147, v32
	s_waitcnt lgkmcnt(0)
	v_add_f32_e32 v32, v32, v33
	ds_bpermute_b32 v33, v165, v32
	s_and_saveexec_b64 s[26:27], s[40:41]
	s_cbranch_execz .LBB0_80
	s_waitcnt lgkmcnt(0)
	v_add_f32_e32 v32, v32, v33
	v_mul_f32_e32 v32, 0x4b800000, v32
	v_trunc_f32_e32 v32, v32
	v_mul_f32_e32 v33, 0x2f800000, v32
	v_floor_f32_e32 v33, v33
	v_fmac_f32_e32 v32, 0xcf800000, v33
	v_cvt_u32_f32_e32 v32, v32
	v_cvt_u32_f32_e32 v33, v33
	v_lshl_add_u64 v[34:35], v[142:143], 3, s[52:53]
	global_atomic_add_x2 v[34:35], v[32:33], off offset:1152

; __device__ __forceinline__ u32x4 pack8(f32x4 v0, f32x4 v1) { u32x4 w; w.x = cvt_pk_bf16(v0[0], v0[1]); w.y = cvt_pk_bf16(v0[2], v0[3]); w.z = cvt_pk_bf16(v1[0], v1[1]); w.w = cvt_pk_bf16(v1[2], v1[3]); return w; }
; __device__ __forceinline__ f32x2 gelu_pk(f32x2 v) {
;     const f32x2 av = __builtin_elementwise_abs(v), d = av * 0.2316418882f + 1.0f;
;     f32x2 t; t.x = __builtin_amdgcn_rcpf(d.x); t.y = __builtin_amdgcn_rcpf(d.y);
;     f32x2 q = t * 0.5307027145f + (-0.7265760135f); q = q * t + 0.7107068705f; q = q * t + (-0.142248368f); q = q * t + 0.127414796f; q = q * t;
;     const f32x2 s = (v * v) * (-0.72134752044f);
;     f32x2 e; e.x = __builtin_amdgcn_exp2f(s.x); e.y = __builtin_amdgcn_exp2f(s.y);
;     const f32x2 m = v * (q * e), r = v - m;
;     f32x2 o; o.x = v.x < 0.f ? m.x : r.x; o.y = v.y < 0.f ? m.y : r.y; return o;
;     __device__ __forceinline__ void operator()(const f32x4 (&acc)[2][2][4][2], const Unit& u, int wr, int wc, int fr, int fq, const Pre& pre) const {
;     ...
;             for (int m = 0; m < 4; ++m) { const int row = row0 + ai * HALF + m * 16; const float r = rs8[ai * 4 + m];
;                 bf16_t* rowp = O + (size_t)row * 2048 + col0; float sq = 0.f;
; #pragma unroll
;                 for (int bj = 0; bj < 2; ++bj) { f32x4 v0 = acc[ai][bj][m][0] * r, v1 = acc[ai][bj][m][1] * r;
;                     f32x2 a = gelu_pk((f32x2){v0[0], v0[1]}), b = gelu_pk((f32x2){v0[2], v0[3]}), c = gelu_pk((f32x2){v1[0], v1[1]}), d = gelu_pk((f32x2){v1[2], v1[3]});
;                     v0 = (f32x4){a.x, a.y, b.x, b.y}; v1 = (f32x4){c.x, c.y, d.x, d.y};
;                     sq += (v0[0] * v0[0] + v0[1] * v0[1]) + (v0[2] * v0[2] + v0[3] * v0[3]) + (v1[0] * v1[0] + v1[1] * v1[1]) + (v1[2] * v1[2] + v1[3] * v1[3]);
;                     *(u32x4*)(rowp + bj * HALF) = pack8(v0, v1); }
.LBB0_81:
	v_pk_mul_f32 v[28:29], v[28:29], v[154:155] op_sel_hi:[1,0]
	v_pk_mul_f32 v[34:35], v[24:25], v[154:155] op_sel_hi:[1,0]
	v_and_b32_e32 v25, 0x7fffffff, v29
	v_and_b32_e32 v24, 0x7fffffff, v28
	v_pk_fma_f32 v[24:25], v[24:25], s[8:9], 1.0 op_sel_hi:[1,0,0]
	s_mov_b64 s[20:21], 0xa0000
	v_rcp_f32_e32 v36, v24
	v_rcp_f32_e32 v37, v25
	s_waitcnt lgkmcnt(0)
	v_lshl_add_u64 v[32:33], v[152:153], 0, s[20:21]
	v_mov_b64_e32 v[24:25], s[12:13]
	v_pk_mul_f32 v[40:41], v[28:29], v[28:29]
	s_mov_b32 s20, 0xbf38aa3b
	v_pk_fma_f32 v[38:39], v[36:37], s[10:11], v[24:25] op_sel_hi:[1,0,0]
	v_pk_mul_f32 v[40:41], v[40:41], s[20:21] op_sel_hi:[1,0]
	v_pk_fma_f32 v[38:39], v[36:37], v[38:39], s[14:15] op_sel_hi:[1,1,0]
	v_exp_f32_e32 v40, v40
	v_exp_f32_e32 v41, v41
	v_pk_fma_f32 v[38:39], v[36:37], v[38:39], s[36:37] op_sel_hi:[1,1,0]
	v_cmp_gt_f32_e32 vcc, 0, v28
	v_pk_fma_f32 v[38:39], v[36:37], v[38:39], s[66:67] op_sel_hi:[1,1,0]
	v_pk_mul_f32 v[30:31], v[30:31], v[154:155] op_sel_hi:[1,0]
	v_pk_mul_f32 v[36:37], v[36:37], v[38:39]
	v_pk_mul_f32 v[38:39], v[30:31], v[30:31]
	v_pk_mul_f32 v[36:37], v[40:41], v[36:37]
	v_pk_mul_f32 v[38:39], v[38:39], s[20:21] op_sel_hi:[1,0]
	v_pk_mul_f32 v[40:41], v[28:29], v[36:37]
	v_pk_fma_f32 v[36:37], v[28:29], v[36:37], v[28:29] neg_lo:[1,0,0] neg_hi:[1,0,0]
	v_exp_f32_e32 v38, v38
	v_cndmask_b32_e32 v28, v36, v40, vcc
	v_cmp_gt_f32_e32 vcc, 0, v29
	v_and_b32_e32 v36, 0x7fffffff, v30
	v_exp_f32_e32 v39, v39
	v_cndmask_b32_e32 v29, v37, v41, vcc
	v_and_b32_e32 v37, 0x7fffffff, v31
	v_pk_fma_f32 v[36:37], v[36:37], s[8:9], 1.0 op_sel_hi:[1,0,0]
	v_cmp_gt_f32_e32 vcc, 0, v30
	v_rcp_f32_e32 v36, v36
	v_rcp_f32_e32 v37, v37
	v_pk_mul_f32 v[26:27], v[26:27], v[154:155] op_sel_hi:[1,0]
	s_mov_b32 s4, 0xa0000
	v_pk_mul_f32 v[20:21], v[20:21], v[154:155] op_sel_hi:[1,0]
	v_pk_fma_f32 v[40:41], v[36:37], s[10:11], v[24:25] op_sel_hi:[1,0,0]
	v_pk_mul_f32 v[22:23], v[22:23], v[154:155] op_sel_hi:[1,0]
	v_pk_fma_f32 v[40:41], v[36:37], v[40:41], s[14:15] op_sel_hi:[1,1,0]
	v_pk_mul_f32 v[18:19], v[18:19], v[154:155] op_sel_hi:[1,0]
	v_pk_fma_f32 v[40:41], v[36:37], v[40:41], s[36:37] op_sel_hi:[1,1,0]
	s_nop 0
	v_pk_fma_f32 v[40:41], v[36:37], v[40:41], s[66:67] op_sel_hi:[1,1,0]
	s_nop 0
	v_pk_mul_f32 v[36:37], v[36:37], v[40:41]
	v_pk_mul_f32 v[40:41], v[34:35], v[34:35]
	v_pk_mul_f32 v[36:37], v[38:39], v[36:37]
	v_pk_mul_f32 v[40:41], v[40:41], s[20:21] op_sel_hi:[1,0]
	v_pk_mul_f32 v[38:39], v[30:31], v[36:37]
	v_pk_fma_f32 v[36:37], v[30:31], v[36:37], v[30:31] neg_lo:[1,0,0] neg_hi:[1,0,0]
	v_exp_f32_e32 v40, v40
	v_cndmask_b32_e32 v30, v36, v38, vcc
	v_cmp_gt_f32_e32 vcc, 0, v31
	v_and_b32_e32 v36, 0x7fffffff, v34
	v_exp_f32_e32 v41, v41
	v_cndmask_b32_e32 v31, v37, v39, vcc
	v_and_b32_e32 v37, 0x7fffffff, v35
	v_pk_fma_f32 v[36:37], v[36:37], s[8:9], 1.0 op_sel_hi:[1,0,0]
	v_cmp_gt_f32_e32 vcc, 0, v34
	v_rcp_f32_e32 v36, v36
	v_rcp_f32_e32 v37, v37
	s_nop 0
	v_pk_fma_f32 v[38:39], v[36:37], s[10:11], v[24:25] op_sel_hi:[1,0,0]
	s_nop 0
	v_pk_fma_f32 v[38:39], v[36:37], v[38:39], s[14:15] op_sel_hi:[1,1,0]
	s_nop 0
	v_pk_fma_f32 v[38:39], v[36:37], v[38:39], s[36:37] op_sel_hi:[1,1,0]
	s_nop 0
	v_pk_fma_f32 v[38:39], v[36:37], v[38:39], s[66:67] op_sel_hi:[1,1,0]
	s_nop 0
	v_pk_mul_f32 v[36:37], v[36:37], v[38:39]
	v_pk_mul_f32 v[38:39], v[26:27], v[26:27]
	v_pk_mul_f32 v[36:37], v[40:41], v[36:37]
	v_pk_mul_f32 v[38:39], v[38:39], s[20:21] op_sel_hi:[1,0]
	v_pk_mul_f32 v[40:41], v[34:35], v[36:37]
	v_pk_fma_f32 v[36:37], v[34:35], v[36:37], v[34:35] neg_lo:[1,0,0] neg_hi:[1,0,0]
	v_exp_f32_e32 v38, v38
	v_cndmask_b32_e32 v34, v36, v40, vcc
	v_cmp_gt_f32_e32 vcc, 0, v35
	v_and_b32_e32 v36, 0x7fffffff, v26
	v_exp_f32_e32 v39, v39
	v_cndmask_b32_e32 v35, v37, v41, vcc
	v_and_b32_e32 v37, 0x7fffffff, v27
	v_pk_fma_f32 v[36:37], v[36:37], s[8:9], 1.0 op_sel_hi:[1,0,0]
	v_cmp_gt_f32_e32 vcc, 0, v26
	v_rcp_f32_e32 v36, v36
	v_rcp_f32_e32 v37, v37
	s_nop 0
	v_pk_fma_f32 v[40:41], v[36:37], s[10:11], v[24:25] op_sel_hi:[1,0,0]
	s_nop 0
	v_pk_fma_f32 v[40:41], v[36:37], v[40:41], s[14:15] op_sel_hi:[1,1,0]
	s_nop 0
	v_pk_fma_f32 v[40:41], v[36:37], v[40:41], s[36:37] op_sel_hi:[1,1,0]
	s_nop 0
	v_pk_fma_f32 v[40:41], v[36:37], v[40:41], s[66:67] op_sel_hi:[1,1,0]
	s_nop 0
	v_pk_mul_f32 v[36:37], v[36:37], v[40:41]
	s_nop 0
	v_pk_mul_f32 v[36:37], v[38:39], v[36:37]
	s_nop 0
	v_pk_mul_f32 v[38:39], v[26:27], v[36:37]
	v_pk_fma_f32 v[36:37], v[26:27], v[36:37], v[26:27] neg_lo:[1,0,0] neg_hi:[1,0,0]
	s_nop 0
	v_cndmask_b32_e32 v26, v36, v38, vcc
	v_cmp_gt_f32_e32 vcc, 0, v27
	v_cvt_pk_bf16_f32 v36, v28, v29
	s_nop 1
	v_cndmask_b32_e32 v27, v37, v39, vcc
	v_add_co_u32_e32 v40, vcc, s4, v152
	v_cvt_pk_bf16_f32 v37, v30, v31
	v_cvt_pk_bf16_f32 v38, v34, v35
	v_cvt_pk_bf16_f32 v39, v26, v27
	s_nop 1
	v_addc_co_u32_e32 v41, vcc, 0, v153, vcc
	global_store_dwordx4 v[40:41], v[36:39], off nt
	v_pk_mul_f32 v[40:41], v[20:21], v[20:21]
	v_cmp_gt_f32_e32 vcc, 0, v20
	v_pk_mul_f32 v[36:37], v[16:17], v[154:155] op_sel_hi:[1,0]
	v_and_b32_e32 v17, 0x7fffffff, v21
	v_and_b32_e32 v16, 0x7fffffff, v20
	v_pk_fma_f32 v[16:17], v[16:17], s[8:9], 1.0 op_sel_hi:[1,0,0]
	v_pk_mul_f32 v[40:41], v[40:41], s[20:21] op_sel_hi:[1,0]
	v_rcp_f32_e32 v16, v16
; __device__ __forceinline__ unsigned long long f2ss(float v) { return (unsigned long long)(v * 16777216.0f); }
; __device__ __forceinline__ u32x4 pack8(f32x4 v0, f32x4 v1) { u32x4 w; w.x = cvt_pk_bf16(v0[0], v0[1]); w.y = cvt_pk_bf16(v0[2], v0[3]); w.z = cvt_pk_bf16(v1[0], v1[1]); w.w = cvt_pk_bf16(v1[2], v1[3]); return w; }
; __device__ __forceinline__ f32x2 gelu_pk(f32x2 v) {
;     const f32x2 av = __builtin_elementwise_abs(v), d = av * 0.2316418882f + 1.0f;
;     f32x2 t; t.x = __builtin_amdgcn_rcpf(d.x); t.y = __builtin_amdgcn_rcpf(d.y);
;     f32x2 q = t * 0.5307027145f + (-0.7265760135f); q = q * t + 0.7107068705f; q = q * t + (-0.142248368f); q = q * t + 0.127414796f; q = q * t;
;     const f32x2 s = (v * v) * (-0.72134752044f);
;     f32x2 e; e.x = __builtin_amdgcn_exp2f(s.x); e.y = __builtin_amdgcn_exp2f(s.y);
;     const f32x2 m = v * (q * e), r = v - m;
;     f32x2 o; o.x = v.x < 0.f ? m.x : r.x; o.y = v.y < 0.f ? m.y : r.y; return o;
;     __device__ __forceinline__ void operator()(const f32x4 (&acc)[2][2][4][2], const Unit& u, int wr, int wc, int fr, int fq, const Pre& pre) const {
;     ...
;                 for (int bj = 0; bj < 2; ++bj) { f32x4 v0 = acc[ai][bj][m][0] * r, v1 = acc[ai][bj][m][1] * r;
;                     f32x2 a = gelu_pk((f32x2){v0[0], v0[1]}), b = gelu_pk((f32x2){v0[2], v0[3]}), c = gelu_pk((f32x2){v1[0], v1[1]}), d = gelu_pk((f32x2){v1[2], v1[3]});
;                     v0 = (f32x4){a.x, a.y, b.x, b.y}; v1 = (f32x4){c.x, c.y, d.x, d.y};
;                     sq += (v0[0] * v0[0] + v0[1] * v0[1]) + (v0[2] * v0[2] + v0[3] * v0[3]) + (v1[0] * v1[0] + v1[1] * v1[1]) + (v1[2] * v1[2] + v1[3] * v1[3]);
;                     *(u32x4*)(rowp + bj * HALF) = pack8(v0, v1); }
;                 if (isv) { sq += __shfl_xor(sq, 16); sq += __shfl_xor(sq, 32); if (fq == 0) atomicAdd(vss + row, f2ss(sq)); } }
	v_rcp_f32_e32 v17, v17
	v_exp_f32_e32 v40, v40
	v_exp_f32_e32 v41, v41
	v_pk_fma_f32 v[38:39], v[16:17], s[10:11], v[24:25] op_sel_hi:[1,0,0]
	s_nop 0
	v_pk_fma_f32 v[38:39], v[16:17], v[38:39], s[14:15] op_sel_hi:[1,1,0]
	s_nop 0
	v_pk_fma_f32 v[38:39], v[16:17], v[38:39], s[36:37] op_sel_hi:[1,1,0]
	s_nop 0
	v_pk_fma_f32 v[38:39], v[16:17], v[38:39], s[66:67] op_sel_hi:[1,1,0]
	s_nop 0
	v_pk_mul_f32 v[16:17], v[16:17], v[38:39]
	v_pk_mul_f32 v[38:39], v[22:23], v[22:23]
	v_pk_mul_f32 v[16:17], v[40:41], v[16:17]
	v_pk_mul_f32 v[38:39], v[38:39], s[20:21] op_sel_hi:[1,0]
	v_pk_mul_f32 v[40:41], v[20:21], v[16:17]
	v_pk_fma_f32 v[16:17], v[20:21], v[16:17], v[20:21] neg_lo:[1,0,0] neg_hi:[1,0,0]
	v_and_b32_e32 v20, 0x7fffffff, v22
	v_cndmask_b32_e32 v16, v16, v40, vcc
	v_cmp_gt_f32_e32 vcc, 0, v21
	v_and_b32_e32 v21, 0x7fffffff, v23
	v_pk_fma_f32 v[20:21], v[20:21], s[8:9], 1.0 op_sel_hi:[1,0,0]
	v_cndmask_b32_e32 v17, v17, v41, vcc
	v_rcp_f32_e32 v20, v20
	v_rcp_f32_e32 v21, v21
	v_exp_f32_e32 v38, v38
	v_exp_f32_e32 v39, v39
	v_cmp_gt_f32_e32 vcc, 0, v22
	v_pk_fma_f32 v[40:41], v[20:21], s[10:11], v[24:25] op_sel_hi:[1,0,0]
	s_nop 0
	v_pk_fma_f32 v[40:41], v[20:21], v[40:41], s[14:15] op_sel_hi:[1,1,0]
	s_nop 0
	v_pk_fma_f32 v[40:41], v[20:21], v[40:41], s[36:37] op_sel_hi:[1,1,0]
	s_nop 0
	v_pk_fma_f32 v[40:41], v[20:21], v[40:41], s[66:67] op_sel_hi:[1,1,0]
	s_nop 0
	v_pk_mul_f32 v[20:21], v[20:21], v[40:41]
	v_pk_mul_f32 v[40:41], v[36:37], v[36:37]
	v_pk_mul_f32 v[20:21], v[38:39], v[20:21]
	v_pk_mul_f32 v[40:41], v[40:41], s[20:21] op_sel_hi:[1,0]
	v_pk_mul_f32 v[38:39], v[22:23], v[20:21]
	v_pk_fma_f32 v[20:21], v[22:23], v[20:21], v[22:23] neg_lo:[1,0,0] neg_hi:[1,0,0]
	v_and_b32_e32 v22, 0x7fffffff, v36
	v_cndmask_b32_e32 v20, v20, v38, vcc
	v_cmp_gt_f32_e32 vcc, 0, v23
	v_and_b32_e32 v23, 0x7fffffff, v37
	v_pk_fma_f32 v[22:23], v[22:23], s[8:9], 1.0 op_sel_hi:[1,0,0]
	v_cndmask_b32_e32 v21, v21, v39, vcc
	v_rcp_f32_e32 v22, v22
	v_rcp_f32_e32 v23, v23
	v_exp_f32_e32 v40, v40
	v_exp_f32_e32 v41, v41
	v_cmp_gt_f32_e32 vcc, 0, v36
	v_pk_fma_f32 v[38:39], v[22:23], s[10:11], v[24:25] op_sel_hi:[1,0,0]
	s_nop 0
	v_pk_fma_f32 v[38:39], v[22:23], v[38:39], s[14:15] op_sel_hi:[1,1,0]
	s_nop 0
	v_pk_fma_f32 v[38:39], v[22:23], v[38:39], s[36:37] op_sel_hi:[1,1,0]
	s_nop 0
	v_pk_fma_f32 v[38:39], v[22:23], v[38:39], s[66:67] op_sel_hi:[1,1,0]
	s_nop 0
	v_pk_mul_f32 v[22:23], v[22:23], v[38:39]
	v_pk_mul_f32 v[38:39], v[18:19], v[18:19]
	v_pk_mul_f32 v[22:23], v[40:41], v[22:23]
	s_nop 0
	v_pk_mul_f32 v[40:41], v[36:37], v[22:23]
	v_pk_fma_f32 v[22:23], v[36:37], v[22:23], v[36:37] neg_lo:[1,0,0] neg_hi:[1,0,0]
	v_and_b32_e32 v36, 0x7fffffff, v18
	v_cndmask_b32_e32 v22, v22, v40, vcc
	v_cmp_gt_f32_e32 vcc, 0, v37
	v_and_b32_e32 v37, 0x7fffffff, v19
	v_pk_fma_f32 v[36:37], v[36:37], s[8:9], 1.0 op_sel_hi:[1,0,0]
	v_cndmask_b32_e32 v23, v23, v41, vcc
	v_rcp_f32_e32 v36, v36
	v_rcp_f32_e32 v37, v37
	v_cmp_gt_f32_e32 vcc, 0, v18
	v_pk_fma_f32 v[24:25], v[36:37], s[10:11], v[24:25] op_sel_hi:[1,0,0]
	s_nop 0
	v_pk_fma_f32 v[24:25], v[36:37], v[24:25], s[14:15] op_sel_hi:[1,1,0]
	s_nop 0
	v_pk_fma_f32 v[24:25], v[36:37], v[24:25], s[36:37] op_sel_hi:[1,1,0]
	s_nop 0
	v_pk_fma_f32 v[24:25], v[36:37], v[24:25], s[66:67] op_sel_hi:[1,1,0]
	s_nop 0
	v_pk_mul_f32 v[24:25], v[36:37], v[24:25]
	v_pk_mul_f32 v[36:37], v[38:39], s[20:21] op_sel_hi:[1,0]
	s_nop 0
	v_exp_f32_e32 v36, v36
	v_exp_f32_e32 v37, v37
	s_nop 0
	v_pk_mul_f32 v[24:25], v[36:37], v[24:25]
	s_nop 0
	v_pk_mul_f32 v[36:37], v[18:19], v[24:25]
	v_pk_fma_f32 v[24:25], v[18:19], v[24:25], v[18:19] neg_lo:[1,0,0] neg_hi:[1,0,0]
	s_nop 0
	v_cndmask_b32_e32 v18, v24, v36, vcc
	v_cmp_gt_f32_e32 vcc, 0, v19
	v_cvt_pk_bf16_f32 v36, v16, v17
	s_nop 1
	v_cndmask_b32_e32 v19, v25, v37, vcc
	s_and_b64 vcc, exec, s[44:45]
	v_cvt_pk_bf16_f32 v37, v20, v21
	v_cvt_pk_bf16_f32 v38, v22, v23
	v_cvt_pk_bf16_f32 v39, v18, v19
	global_store_dwordx4 v[32:33], v[36:39], off offset:256 nt
	s_cbranch_vccnz .LBB0_85
	v_mul_f32_e32 v24, v27, v27
	v_mul_f32_e32 v17, v17, v17
	v_fmac_f32_e32 v24, v26, v26
	v_mul_f32_e32 v25, v29, v29
	v_mul_f32_e32 v26, v31, v31
	v_fmac_f32_e32 v17, v16, v16
	v_mul_f32_e32 v16, v21, v21
	v_fmac_f32_e32 v25, v28, v28
	v_fmac_f32_e32 v26, v30, v30
	v_fmac_f32_e32 v16, v20, v20
	v_add_f32_e32 v25, v25, v26
	v_mul_f32_e32 v26, v35, v35
	v_add_f32_e32 v16, v17, v16
	v_mul_f32_e32 v17, v23, v23
	v_fmac_f32_e32 v26, v34, v34
	v_mul_f32_e32 v19, v19, v19
	v_fmac_f32_e32 v17, v22, v22
	v_add_f32_e32 v25, v26, v25
	v_fmac_f32_e32 v19, v18, v18
	v_add_f32_e32 v16, v17, v16
	v_add_f32_e32 v24, v24, v25
	v_add_f32_e32 v16, v19, v16
	v_add_f32_e32 v16, v24, v16
	ds_bpermute_b32 v17, v147, v16
	s_waitcnt lgkmcnt(0)
	v_add_f32_e32 v16, v16, v17
	ds_bpermute_b32 v17, v165, v16
	s_and_saveexec_b64 s[26:27], s[40:41]
	s_cbranch_execz .LBB0_84
	s_waitcnt lgkmcnt(0)
	v_add_f32_e32 v16, v16, v17
	v_mul_f32_e32 v16, 0x4b800000, v16
	v_trunc_f32_e32 v16, v16
	v_mul_f32_e32 v17, 0x2f800000, v16
	v_floor_f32_e32 v17, v17
	v_fmac_f32_e32 v16, 0xcf800000, v17
	v_cvt_u32_f32_e32 v16, v16
	v_cvt_u32_f32_e32 v17, v17
	v_lshl_add_u64 v[18:19], v[142:143], 3, s[52:53]
	global_atomic_add_x2 v[18:19], v[16:17], off offset:1280

; __device__ __forceinline__ u32x4 pack8(f32x4 v0, f32x4 v1) { u32x4 w; w.x = cvt_pk_bf16(v0[0], v0[1]); w.y = cvt_pk_bf16(v0[2], v0[3]); w.z = cvt_pk_bf16(v1[0], v1[1]); w.w = cvt_pk_bf16(v1[2], v1[3]); return w; }
; __device__ __forceinline__ f32x2 gelu_pk(f32x2 v) {
;     const f32x2 av = __builtin_elementwise_abs(v), d = av * 0.2316418882f + 1.0f;
;     f32x2 t; t.x = __builtin_amdgcn_rcpf(d.x); t.y = __builtin_amdgcn_rcpf(d.y);
;     f32x2 q = t * 0.5307027145f + (-0.7265760135f); q = q * t + 0.7107068705f; q = q * t + (-0.142248368f); q = q * t + 0.127414796f; q = q * t;
;     const f32x2 s = (v * v) * (-0.72134752044f);
;     f32x2 e; e.x = __builtin_amdgcn_exp2f(s.x); e.y = __builtin_amdgcn_exp2f(s.y);
;     const f32x2 m = v * (q * e), r = v - m;
;     f32x2 o; o.x = v.x < 0.f ? m.x : r.x; o.y = v.y < 0.f ? m.y : r.y; return o;
;     __device__ __forceinline__ void operator()(const f32x4 (&acc)[2][2][4][2], const Unit& u, int wr, int wc, int fr, int fq, const Pre& pre) const {
;     ...
;             for (int m = 0; m < 4; ++m) { const int row = row0 + ai * HALF + m * 16; const float r = rs8[ai * 4 + m];
;                 bf16_t* rowp = O + (size_t)row * 2048 + col0; float sq = 0.f;
; #pragma unroll
;                 for (int bj = 0; bj < 2; ++bj) { f32x4 v0 = acc[ai][bj][m][0] * r, v1 = acc[ai][bj][m][1] * r;
;                     f32x2 a = gelu_pk((f32x2){v0[0], v0[1]}), b = gelu_pk((f32x2){v0[2], v0[3]}), c = gelu_pk((f32x2){v1[0], v1[1]}), d = gelu_pk((f32x2){v1[2], v1[3]});
;                     v0 = (f32x4){a.x, a.y, b.x, b.y}; v1 = (f32x4){c.x, c.y, d.x, d.y};
;                     sq += (v0[0] * v0[0] + v0[1] * v0[1]) + (v0[2] * v0[2] + v0[3] * v0[3]) + (v1[0] * v1[0] + v1[1] * v1[1]) + (v1[2] * v1[2] + v1[3] * v1[3]);
;                     *(u32x4*)(rowp + bj * HALF) = pack8(v0, v1); }
.LBB0_85:
	v_pk_mul_f32 v[12:13], v[12:13], v[146:147] op_sel_hi:[1,0]
	v_pk_mul_f32 v[18:19], v[8:9], v[146:147] op_sel_hi:[1,0]
	v_and_b32_e32 v9, 0x7fffffff, v13
	v_and_b32_e32 v8, 0x7fffffff, v12
	v_pk_fma_f32 v[8:9], v[8:9], s[8:9], 1.0 op_sel_hi:[1,0,0]
	v_pk_mul_f32 v[24:25], v[12:13], v[12:13]
	v_rcp_f32_e32 v20, v8
	v_rcp_f32_e32 v21, v9
	v_mov_b64_e32 v[8:9], s[12:13]
	s_mov_b32 s12, 0xbf38aa3b
	v_pk_mul_f32 v[24:25], v[24:25], s[12:13] op_sel_hi:[1,0]
	v_pk_fma_f32 v[22:23], v[20:21], s[10:11], v[8:9] op_sel_hi:[1,0,0]
	v_exp_f32_e32 v24, v24
	v_pk_fma_f32 v[22:23], v[20:21], v[22:23], s[14:15] op_sel_hi:[1,1,0]
	v_exp_f32_e32 v25, v25
	v_pk_fma_f32 v[22:23], v[20:21], v[22:23], s[36:37] op_sel_hi:[1,1,0]
	v_cmp_gt_f32_e32 vcc, 0, v12
	v_pk_fma_f32 v[22:23], v[20:21], v[22:23], s[66:67] op_sel_hi:[1,1,0]
	v_pk_mul_f32 v[14:15], v[14:15], v[146:147] op_sel_hi:[1,0]
	v_pk_mul_f32 v[20:21], v[20:21], v[22:23]
	v_pk_mul_f32 v[22:23], v[14:15], v[14:15]
	v_pk_mul_f32 v[20:21], v[24:25], v[20:21]
	v_pk_mul_f32 v[22:23], v[22:23], s[12:13] op_sel_hi:[1,0]
	v_pk_mul_f32 v[24:25], v[12:13], v[20:21]
	v_pk_fma_f32 v[20:21], v[12:13], v[20:21], v[12:13] neg_lo:[1,0,0] neg_hi:[1,0,0]
	v_exp_f32_e32 v22, v22
	v_cndmask_b32_e32 v12, v20, v24, vcc
	v_cmp_gt_f32_e32 vcc, 0, v13
	v_and_b32_e32 v20, 0x7fffffff, v14
	v_exp_f32_e32 v23, v23
	v_cndmask_b32_e32 v13, v21, v25, vcc
	v_and_b32_e32 v21, 0x7fffffff, v15
	v_pk_fma_f32 v[20:21], v[20:21], s[8:9], 1.0 op_sel_hi:[1,0,0]
	v_cmp_gt_f32_e32 vcc, 0, v14
	v_rcp_f32_e32 v20, v20
	v_rcp_f32_e32 v21, v21
	v_pk_mul_f32 v[10:11], v[10:11], v[146:147] op_sel_hi:[1,0]
	s_mov_b32 s4, 0xb0000
	v_pk_mul_f32 v[4:5], v[4:5], v[146:147] op_sel_hi:[1,0]
	v_pk_fma_f32 v[24:25], v[20:21], s[10:11], v[8:9] op_sel_hi:[1,0,0]
	v_pk_mul_f32 v[6:7], v[6:7], v[146:147] op_sel_hi:[1,0]
	v_pk_fma_f32 v[24:25], v[20:21], v[24:25], s[14:15] op_sel_hi:[1,1,0]
	v_pk_mul_f32 v[2:3], v[2:3], v[146:147] op_sel_hi:[1,0]
	v_pk_fma_f32 v[24:25], v[20:21], v[24:25], s[36:37] op_sel_hi:[1,1,0]
	s_mov_b64 s[20:21], 0xb0000
	v_pk_fma_f32 v[24:25], v[20:21], v[24:25], s[66:67] op_sel_hi:[1,1,0]
	s_waitcnt lgkmcnt(0)
	v_lshl_add_u64 v[16:17], v[152:153], 0, s[20:21]
	v_pk_mul_f32 v[20:21], v[20:21], v[24:25]
	v_pk_mul_f32 v[24:25], v[18:19], v[18:19]
	v_pk_mul_f32 v[20:21], v[22:23], v[20:21]
	v_pk_mul_f32 v[24:25], v[24:25], s[12:13] op_sel_hi:[1,0]
	v_pk_mul_f32 v[22:23], v[14:15], v[20:21]
	v_pk_fma_f32 v[20:21], v[14:15], v[20:21], v[14:15] neg_lo:[1,0,0] neg_hi:[1,0,0]
	v_exp_f32_e32 v24, v24
	v_cndmask_b32_e32 v14, v20, v22, vcc
	v_cmp_gt_f32_e32 vcc, 0, v15
	v_and_b32_e32 v20, 0x7fffffff, v18
	v_exp_f32_e32 v25, v25
	v_cndmask_b32_e32 v15, v21, v23, vcc
	v_and_b32_e32 v21, 0x7fffffff, v19
	v_pk_fma_f32 v[20:21], v[20:21], s[8:9], 1.0 op_sel_hi:[1,0,0]
	v_cmp_gt_f32_e32 vcc, 0, v18
	v_rcp_f32_e32 v20, v20
	v_rcp_f32_e32 v21, v21
	s_nop 0
	v_pk_fma_f32 v[22:23], v[20:21], s[10:11], v[8:9] op_sel_hi:[1,0,0]
	s_nop 0
	v_pk_fma_f32 v[22:23], v[20:21], v[22:23], s[14:15] op_sel_hi:[1,1,0]
	s_nop 0
	v_pk_fma_f32 v[22:23], v[20:21], v[22:23], s[36:37] op_sel_hi:[1,1,0]
	s_nop 0
	v_pk_fma_f32 v[22:23], v[20:21], v[22:23], s[66:67] op_sel_hi:[1,1,0]
	s_nop 0
	v_pk_mul_f32 v[20:21], v[20:21], v[22:23]
	v_pk_mul_f32 v[22:23], v[10:11], v[10:11]
	v_pk_mul_f32 v[20:21], v[24:25], v[20:21]
	v_pk_mul_f32 v[22:23], v[22:23], s[12:13] op_sel_hi:[1,0]
	v_pk_mul_f32 v[24:25], v[18:19], v[20:21]
	v_pk_fma_f32 v[20:21], v[18:19], v[20:21], v[18:19] neg_lo:[1,0,0] neg_hi:[1,0,0]
	v_exp_f32_e32 v22, v22
	v_cndmask_b32_e32 v18, v20, v24, vcc
	v_cmp_gt_f32_e32 vcc, 0, v19
	v_and_b32_e32 v20, 0x7fffffff, v10
	v_exp_f32_e32 v23, v23
	v_cndmask_b32_e32 v19, v21, v25, vcc
	v_and_b32_e32 v21, 0x7fffffff, v11
	v_pk_fma_f32 v[20:21], v[20:21], s[8:9], 1.0 op_sel_hi:[1,0,0]
	v_cmp_gt_f32_e32 vcc, 0, v10
	v_rcp_f32_e32 v20, v20
	v_rcp_f32_e32 v21, v21
	s_nop 0
	v_pk_fma_f32 v[24:25], v[20:21], s[10:11], v[8:9] op_sel_hi:[1,0,0]
	s_nop 0
	v_pk_fma_f32 v[24:25], v[20:21], v[24:25], s[14:15] op_sel_hi:[1,1,0]
	s_nop 0
	v_pk_fma_f32 v[24:25], v[20:21], v[24:25], s[36:37] op_sel_hi:[1,1,0]
	s_nop 0
	v_pk_fma_f32 v[24:25], v[20:21], v[24:25], s[66:67] op_sel_hi:[1,1,0]
	s_nop 0
	v_pk_mul_f32 v[20:21], v[20:21], v[24:25]
	s_nop 0
	v_pk_mul_f32 v[20:21], v[22:23], v[20:21]
	s_nop 0
	v_pk_mul_f32 v[22:23], v[10:11], v[20:21]
	v_pk_fma_f32 v[20:21], v[10:11], v[20:21], v[10:11] neg_lo:[1,0,0] neg_hi:[1,0,0]
	s_nop 0
	v_cndmask_b32_e32 v10, v20, v22, vcc
	v_cmp_gt_f32_e32 vcc, 0, v11
	v_cvt_pk_bf16_f32 v20, v12, v13
	s_nop 1
	v_cndmask_b32_e32 v11, v21, v23, vcc
	v_add_co_u32_e32 v24, vcc, s4, v152
	v_cvt_pk_bf16_f32 v21, v14, v15
	v_cvt_pk_bf16_f32 v22, v18, v19
	v_cvt_pk_bf16_f32 v23, v10, v11
	s_nop 1
	v_addc_co_u32_e32 v25, vcc, 0, v153, vcc
	global_store_dwordx4 v[24:25], v[20:23], off nt
	v_pk_mul_f32 v[24:25], v[4:5], v[4:5]
	v_cmp_gt_f32_e32 vcc, 0, v4
	v_pk_mul_f32 v[20:21], v[0:1], v[146:147] op_sel_hi:[1,0]
	v_and_b32_e32 v1, 0x7fffffff, v5
	v_and_b32_e32 v0, 0x7fffffff, v4
	v_pk_fma_f32 v[0:1], v[0:1], s[8:9], 1.0 op_sel_hi:[1,0,0]
; __device__ __forceinline__ unsigned long long f2ss(float v) { return (unsigned long long)(v * 16777216.0f); }
; __device__ __forceinline__ u32x4 pack8(f32x4 v0, f32x4 v1) { u32x4 w; w.x = cvt_pk_bf16(v0[0], v0[1]); w.y = cvt_pk_bf16(v0[2], v0[3]); w.z = cvt_pk_bf16(v1[0], v1[1]); w.w = cvt_pk_bf16(v1[2], v1[3]); return w; }
; __device__ __forceinline__ f32x2 gelu_pk(f32x2 v) {
;     const f32x2 av = __builtin_elementwise_abs(v), d = av * 0.2316418882f + 1.0f;
;     f32x2 t; t.x = __builtin_amdgcn_rcpf(d.x); t.y = __builtin_amdgcn_rcpf(d.y);
;     f32x2 q = t * 0.5307027145f + (-0.7265760135f); q = q * t + 0.7107068705f; q = q * t + (-0.142248368f); q = q * t + 0.127414796f; q = q * t;
;     const f32x2 s = (v * v) * (-0.72134752044f);
;     f32x2 e; e.x = __builtin_amdgcn_exp2f(s.x); e.y = __builtin_amdgcn_exp2f(s.y);
;     const f32x2 m = v * (q * e), r = v - m;
;     f32x2 o; o.x = v.x < 0.f ? m.x : r.x; o.y = v.y < 0.f ? m.y : r.y; return o;
;     __device__ __forceinline__ void operator()(const f32x4 (&acc)[2][2][4][2], const Unit& u, int wr, int wc, int fr, int fq, const Pre& pre) const {
;     ...
;                 for (int bj = 0; bj < 2; ++bj) { f32x4 v0 = acc[ai][bj][m][0] * r, v1 = acc[ai][bj][m][1] * r;
;                     f32x2 a = gelu_pk((f32x2){v0[0], v0[1]}), b = gelu_pk((f32x2){v0[2], v0[3]}), c = gelu_pk((f32x2){v1[0], v1[1]}), d = gelu_pk((f32x2){v1[2], v1[3]});
;                     v0 = (f32x4){a.x, a.y, b.x, b.y}; v1 = (f32x4){c.x, c.y, d.x, d.y};
;                     sq += (v0[0] * v0[0] + v0[1] * v0[1]) + (v0[2] * v0[2] + v0[3] * v0[3]) + (v1[0] * v1[0] + v1[1] * v1[1]) + (v1[2] * v1[2] + v1[3] * v1[3]);
;                     *(u32x4*)(rowp + bj * HALF) = pack8(v0, v1); }
;                 if (isv) { sq += __shfl_xor(sq, 16); sq += __shfl_xor(sq, 32); if (fq == 0) atomicAdd(vss + row, f2ss(sq)); } }
	v_pk_mul_f32 v[24:25], v[24:25], s[12:13] op_sel_hi:[1,0]
	v_rcp_f32_e32 v0, v0
	v_rcp_f32_e32 v1, v1
	v_exp_f32_e32 v24, v24
	v_exp_f32_e32 v25, v25
	v_pk_fma_f32 v[22:23], v[0:1], s[10:11], v[8:9] op_sel_hi:[1,0,0]
	s_nop 0
	v_pk_fma_f32 v[22:23], v[0:1], v[22:23], s[14:15] op_sel_hi:[1,1,0]
	s_nop 0
	v_pk_fma_f32 v[22:23], v[0:1], v[22:23], s[36:37] op_sel_hi:[1,1,0]
	s_nop 0
	v_pk_fma_f32 v[22:23], v[0:1], v[22:23], s[66:67] op_sel_hi:[1,1,0]
	s_nop 0
	v_pk_mul_f32 v[0:1], v[0:1], v[22:23]
	v_pk_mul_f32 v[22:23], v[6:7], v[6:7]
	v_pk_mul_f32 v[0:1], v[24:25], v[0:1]
	v_pk_mul_f32 v[22:23], v[22:23], s[12:13] op_sel_hi:[1,0]
	v_pk_mul_f32 v[24:25], v[4:5], v[0:1]
	v_pk_fma_f32 v[0:1], v[4:5], v[0:1], v[4:5] neg_lo:[1,0,0] neg_hi:[1,0,0]
	v_and_b32_e32 v4, 0x7fffffff, v6
	v_cndmask_b32_e32 v0, v0, v24, vcc
	v_cmp_gt_f32_e32 vcc, 0, v5
	v_and_b32_e32 v5, 0x7fffffff, v7
	v_pk_fma_f32 v[4:5], v[4:5], s[8:9], 1.0 op_sel_hi:[1,0,0]
	v_cndmask_b32_e32 v1, v1, v25, vcc
	v_rcp_f32_e32 v4, v4
	v_rcp_f32_e32 v5, v5
	v_exp_f32_e32 v22, v22
	v_exp_f32_e32 v23, v23
	v_cmp_gt_f32_e32 vcc, 0, v6
	v_pk_fma_f32 v[24:25], v[4:5], s[10:11], v[8:9] op_sel_hi:[1,0,0]
	s_nop 0
	v_pk_fma_f32 v[24:25], v[4:5], v[24:25], s[14:15] op_sel_hi:[1,1,0]
	s_nop 0
	v_pk_fma_f32 v[24:25], v[4:5], v[24:25], s[36:37] op_sel_hi:[1,1,0]
	s_nop 0
	v_pk_fma_f32 v[24:25], v[4:5], v[24:25], s[66:67] op_sel_hi:[1,1,0]
	s_nop 0
	v_pk_mul_f32 v[4:5], v[4:5], v[24:25]
	v_pk_mul_f32 v[24:25], v[20:21], v[20:21]
	v_pk_mul_f32 v[4:5], v[22:23], v[4:5]
	v_pk_mul_f32 v[24:25], v[24:25], s[12:13] op_sel_hi:[1,0]
	v_pk_mul_f32 v[22:23], v[6:7], v[4:5]
	v_pk_fma_f32 v[4:5], v[6:7], v[4:5], v[6:7] neg_lo:[1,0,0] neg_hi:[1,0,0]
	v_and_b32_e32 v6, 0x7fffffff, v20
	v_cndmask_b32_e32 v4, v4, v22, vcc
	v_cmp_gt_f32_e32 vcc, 0, v7
	v_and_b32_e32 v7, 0x7fffffff, v21
	v_pk_fma_f32 v[6:7], v[6:7], s[8:9], 1.0 op_sel_hi:[1,0,0]
	v_cndmask_b32_e32 v5, v5, v23, vcc
	v_rcp_f32_e32 v6, v6
	v_rcp_f32_e32 v7, v7
	v_exp_f32_e32 v24, v24
	v_exp_f32_e32 v25, v25
	v_cmp_gt_f32_e32 vcc, 0, v20
	v_pk_fma_f32 v[22:23], v[6:7], s[10:11], v[8:9] op_sel_hi:[1,0,0]
	s_nop 0
	v_pk_fma_f32 v[22:23], v[6:7], v[22:23], s[14:15] op_sel_hi:[1,1,0]
	s_nop 0
	v_pk_fma_f32 v[22:23], v[6:7], v[22:23], s[36:37] op_sel_hi:[1,1,0]
	s_nop 0
	v_pk_fma_f32 v[22:23], v[6:7], v[22:23], s[66:67] op_sel_hi:[1,1,0]
	s_nop 0
	v_pk_mul_f32 v[6:7], v[6:7], v[22:23]
	v_pk_mul_f32 v[22:23], v[2:3], v[2:3]
	v_pk_mul_f32 v[6:7], v[24:25], v[6:7]
	s_nop 0
	v_pk_mul_f32 v[24:25], v[20:21], v[6:7]
	v_pk_fma_f32 v[6:7], v[20:21], v[6:7], v[20:21] neg_lo:[1,0,0] neg_hi:[1,0,0]
	v_and_b32_e32 v20, 0x7fffffff, v2
	v_cndmask_b32_e32 v6, v6, v24, vcc
	v_cmp_gt_f32_e32 vcc, 0, v21
	v_and_b32_e32 v21, 0x7fffffff, v3
	v_pk_fma_f32 v[20:21], v[20:21], s[8:9], 1.0 op_sel_hi:[1,0,0]
	v_cndmask_b32_e32 v7, v7, v25, vcc
	v_rcp_f32_e32 v20, v20
	v_rcp_f32_e32 v21, v21
	v_cmp_gt_f32_e32 vcc, 0, v2
	v_pk_fma_f32 v[8:9], v[20:21], s[10:11], v[8:9] op_sel_hi:[1,0,0]
	s_nop 0
	v_pk_fma_f32 v[8:9], v[20:21], v[8:9], s[14:15] op_sel_hi:[1,1,0]
	s_nop 0
	v_pk_fma_f32 v[8:9], v[20:21], v[8:9], s[36:37] op_sel_hi:[1,1,0]
	s_nop 0
	v_pk_fma_f32 v[8:9], v[20:21], v[8:9], s[66:67] op_sel_hi:[1,1,0]
	s_nop 0
	v_pk_mul_f32 v[8:9], v[20:21], v[8:9]
	v_pk_mul_f32 v[20:21], v[22:23], s[12:13] op_sel_hi:[1,0]
	s_nop 0
	v_exp_f32_e32 v20, v20
	v_exp_f32_e32 v21, v21
	s_nop 0
	v_pk_mul_f32 v[8:9], v[20:21], v[8:9]
	s_nop 0
	v_pk_mul_f32 v[20:21], v[2:3], v[8:9]
	v_pk_fma_f32 v[8:9], v[2:3], v[8:9], v[2:3] neg_lo:[1,0,0] neg_hi:[1,0,0]
	s_nop 0
	v_cndmask_b32_e32 v2, v8, v20, vcc
	v_cmp_gt_f32_e32 vcc, 0, v3
	v_cvt_pk_bf16_f32 v20, v0, v1
	s_nop 1
	v_cndmask_b32_e32 v3, v9, v21, vcc
	s_and_b64 vcc, exec, s[44:45]
	v_cvt_pk_bf16_f32 v21, v4, v5
	v_cvt_pk_bf16_f32 v22, v6, v7
	v_cvt_pk_bf16_f32 v23, v2, v3
	global_store_dwordx4 v[16:17], v[20:23], off offset:256 nt
	s_cbranch_vccnz .LBB0_89
	v_mul_f32_e32 v8, v11, v11
	v_mul_f32_e32 v1, v1, v1
	v_fmac_f32_e32 v8, v10, v10
	v_mul_f32_e32 v9, v13, v13
	v_mul_f32_e32 v10, v15, v15
	v_fmac_f32_e32 v1, v0, v0
	v_mul_f32_e32 v0, v5, v5
	v_fmac_f32_e32 v9, v12, v12
	v_fmac_f32_e32 v10, v14, v14
	v_fmac_f32_e32 v0, v4, v4
	v_add_f32_e32 v9, v9, v10
	v_mul_f32_e32 v10, v19, v19
	v_add_f32_e32 v0, v1, v0
	v_mul_f32_e32 v1, v7, v7
	v_fmac_f32_e32 v10, v18, v18
	v_mul_f32_e32 v3, v3, v3
	v_fmac_f32_e32 v1, v6, v6
	v_add_f32_e32 v9, v10, v9
	v_fmac_f32_e32 v3, v2, v2
	v_add_f32_e32 v0, v1, v0
	v_add_f32_e32 v8, v8, v9
	v_add_f32_e32 v0, v3, v0
	v_add_f32_e32 v0, v8, v0
	ds_bpermute_b32 v1, v147, v0
	s_waitcnt lgkmcnt(0)
	v_add_f32_e32 v0, v0, v1
	ds_bpermute_b32 v1, v165, v0
	s_and_saveexec_b64 s[26:27], s[40:41]
	s_cbranch_execz .LBB0_88
	s_waitcnt lgkmcnt(0)
	v_add_f32_e32 v0, v0, v1
	v_mul_f32_e32 v0, 0x4b800000, v0
	v_trunc_f32_e32 v0, v0
	v_mul_f32_e32 v1, 0x2f800000, v0
	v_floor_f32_e32 v1, v1
	v_fmac_f32_e32 v0, 0xcf800000, v1
	v_cvt_u32_f32_e32 v0, v0
	v_cvt_u32_f32_e32 v1, v1
	v_lshl_add_u64 v[2:3], v[142:143], 3, s[52:53]
	global_atomic_add_x2 v[2:3], v[0:1], off offset:1408

; __device__ __forceinline__ unsigned long long f2ss(float v) { return (unsigned long long)(v * 16777216.0f); }
; __device__ __forceinline__ u32x4 pack8(f32x4 v0, f32x4 v1) { u32x4 w; w.x = cvt_pk_bf16(v0[0], v0[1]); w.y = cvt_pk_bf16(v0[2], v0[3]); w.z = cvt_pk_bf16(v1[0], v1[1]); w.w = cvt_pk_bf16(v1[2], v1[3]); return w; }
;     __device__ __forceinline__ void operator()(const f32x4 (&acc)[2][2][4][2], const Unit& u, int wr, int wc, int fr, int fq, const Pre&) const {
;         const int row0 = u.pm * BM + wr * 64 + fr, col0 = u.pn * BM + wc * 32 + 8 * fq;
;         typedef __attribute__((address_space(1))) u32x4 gu32x4;
;         u32x4 bwv[2][4][2];
; #pragma unroll
;         for (int ai = 0; ai < 2; ++ai)
; #pragma unroll
;             for (int m = 0; m < 4; ++m)
; #pragma unroll
;                 for (int bj = 0; bj < 2; ++bj) bwv[ai][m][bj] = *(const gu32x4*)(hb + (size_t)(row0 + ai * HALF + m * 16) * 1024 + col0 + bj * HALF);
; #pragma unroll
;         for (int ai = 0; ai < 2; ++ai)
; #pragma unroll
;             for (int m = 0; m < 4; ++m) { const int row = row0 + ai * HALF + m * 16; const size_t off = (size_t)row * 1024 + col0; float sq = 0.f;
; #pragma unroll
;                 for (int bj = 0; bj < 2; ++bj) { const u32x4 bw = bwv[ai][m][bj];
;                     const f32x4 b0 = (f32x4){__uint_as_float(bw.x << 16), __uint_as_float(bw.x & 0xffff0000u), __uint_as_float(bw.y << 16), __uint_as_float(bw.y & 0xffff0000u)};
;                     const f32x4 b1 = (f32x4){__uint_as_float(bw.z << 16), __uint_as_float(bw.z & 0xffff0000u), __uint_as_float(bw.w << 16), __uint_as_float(bw.w & 0xffff0000u)};
;                     const f32x4 v0 = acc[ai][bj][m][0] + b0, v1 = acc[ai][bj][m][1] + b1;
;                     *(gu32x4*)(hb + off + bj * HALF) = pack8(v0, v1);
;                     sq += (v0[0] * v0[0] + v0[1] * v0[1]) + (v0[2] * v0[2] + v0[3] * v0[3]) + (v1[0] * v1[0] + v1[1] * v1[1]) + (v1[2] * v1[2] + v1[3] * v1[3]); }
;                 sq += __shfl_xor(sq, 16); sq += __shfl_xor(sq, 32); if (fq == 0) atomicAdd(ssn + row, f2ss(sq)); }
.LBB0_115:
	v_lshl_or_b32 v210, s36, 8, v241
	v_lshl_add_u32 v226, s4, 8, v145
	v_ashrrev_i32_e32 v211, 31, v210
	v_lshlrev_b64 v[228:229], 1, v[210:211]
	v_ashrrev_i32_e32 v227, 31, v226
	v_lshl_add_u64 v[112:113], s[28:29], 0, v[228:229]
	v_lshlrev_b64 v[230:231], 11, v[226:227]
	v_lshl_add_u64 v[114:115], v[112:113], 0, v[230:231]
	global_load_dwordx4 v[244:247], v[114:115], off
	global_load_dwordx4 v[192:195], v[114:115], off offset:256
	v_or_b32_e32 v114, 16, v226
	v_ashrrev_i32_e32 v115, 31, v114
	v_lshlrev_b64 v[224:225], 11, v[114:115]
	v_lshl_add_u64 v[114:115], v[112:113], 0, v[224:225]
	global_load_dwordx4 v[188:191], v[114:115], off
	global_load_dwordx4 v[184:187], v[114:115], off offset:256
	v_or_b32_e32 v114, 32, v226
	v_ashrrev_i32_e32 v115, 31, v114
	v_lshlrev_b64 v[222:223], 11, v[114:115]
	v_lshl_add_u64 v[114:115], v[112:113], 0, v[222:223]
	global_load_dwordx4 v[180:183], v[114:115], off
	global_load_dwordx4 v[176:179], v[114:115], off offset:256
	v_or_b32_e32 v114, 48, v226
	v_ashrrev_i32_e32 v115, 31, v114
	s_mov_b64 s[4:5], 0x40000
	v_lshlrev_b64 v[220:221], 11, v[114:115]
	v_lshl_add_u64 v[218:219], v[230:231], 0, s[4:5]
	s_mov_b64 s[4:5], 0x48000
	v_lshl_add_u64 v[114:115], v[112:113], 0, v[220:221]
	v_lshl_add_u64 v[216:217], v[230:231], 0, s[4:5]
	s_mov_b64 s[4:5], 0x50000
	global_load_dwordx4 v[172:175], v[114:115], off
	global_load_dwordx4 v[164:167], v[114:115], off offset:256
	v_lshl_add_u64 v[114:115], v[112:113], 0, v[218:219]
	v_lshl_add_u64 v[214:215], v[230:231], 0, s[4:5]
	s_mov_b64 s[4:5], 0x58000
	global_load_dwordx4 v[156:159], v[114:115], off
	global_load_dwordx4 v[152:155], v[114:115], off offset:256
	v_lshl_add_u64 v[114:115], v[112:113], 0, v[216:217]
	v_lshl_add_u64 v[212:213], v[230:231], 0, s[4:5]
	global_load_dwordx4 v[140:143], v[114:115], off
	global_load_dwordx4 v[132:135], v[114:115], off offset:256
	v_lshl_add_u64 v[114:115], v[112:113], 0, v[214:215]
	v_lshl_add_u64 v[112:113], v[112:113], 0, v[212:213]
	global_load_dwordx4 v[124:127], v[114:115], off
	global_load_dwordx4 v[116:119], v[114:115], off offset:256
	global_load_dwordx4 v[120:123], v[112:113], off
	s_nop 0
	global_load_dwordx4 v[112:115], v[112:113], off offset:256
	v_lshl_add_u64 v[230:231], s[28:29], 0, v[230:231]
	v_lshl_add_u64 v[228:229], v[230:231], 0, v[228:229]
	s_waitcnt vmcnt(0)
	v_lshlrev_b32_e32 v248, 16, v244
	v_and_b32_e32 v249, 0xffff0000, v244
	v_lshlrev_b32_e32 v244, 16, v245
	v_and_b32_e32 v245, 0xffff0000, v245
	v_lshlrev_b32_e32 v250, 16, v246
	v_and_b32_e32 v251, 0xffff0000, v246
	v_lshlrev_b32_e32 v246, 16, v247
	v_and_b32_e32 v247, 0xffff0000, v247
	v_pk_add_f32 v[170:171], v[170:171], v[244:245]
	v_pk_add_f32 v[168:169], v[168:169], v[248:249]
	v_pk_add_f32 v[244:245], v[162:163], v[246:247]
	v_pk_add_f32 v[246:247], v[160:161], v[250:251]
	v_cvt_pk_bf16_f32 v160, v168, v169
	v_cvt_pk_bf16_f32 v161, v170, v171
	s_nop 0
	v_cvt_pk_bf16_f32 v162, v246, v247
	v_cvt_pk_bf16_f32 v163, v244, v245
	global_store_dwordx4 v[228:229], v[160:163], off
	s_nop 1
	v_mul_f32_e32 v160, v169, v169
	v_mul_f32_e32 v161, v171, v171
	v_fmac_f32_e32 v160, v168, v168
	v_fmac_f32_e32 v161, v170, v170
	v_add_f32_e32 v160, v160, v161
	v_mul_f32_e32 v161, v247, v247
	v_fmac_f32_e32 v161, v246, v246
	v_add_f32_e32 v160, v161, v160
	v_mul_f32_e32 v161, v245, v245
	v_fmac_f32_e32 v161, v244, v244
	v_add_f32_e32 v196, v161, v160
	v_lshlrev_b32_e32 v160, 16, v192
	v_and_b32_e32 v161, 0xffff0000, v192
	v_lshlrev_b32_e32 v162, 16, v193
	v_and_b32_e32 v163, 0xffff0000, v193
	v_lshlrev_b32_e32 v168, 16, v194
	v_and_b32_e32 v169, 0xffff0000, v194
	v_lshlrev_b32_e32 v170, 16, v195
	v_and_b32_e32 v171, 0xffff0000, v195
	v_pk_add_f32 v[138:139], v[138:139], v[162:163]
	v_pk_add_f32 v[136:137], v[136:137], v[160:161]
	v_pk_add_f32 v[162:163], v[128:129], v[168:169]
	v_cvt_pk_bf16_f32 v128, v136, v137
	v_cvt_pk_bf16_f32 v129, v138, v139
	v_pk_add_f32 v[160:161], v[130:131], v[170:171]
	v_cvt_pk_bf16_f32 v130, v162, v163
	s_nop 0
	v_cvt_pk_bf16_f32 v131, v160, v161
	global_store_dwordx4 v[228:229], v[128:131], off offset:256
	s_nop 1
	v_mul_f32_e32 v128, v137, v137
	v_mul_f32_e32 v129, v139, v139
	v_fmac_f32_e32 v128, v136, v136
	v_fmac_f32_e32 v129, v138, v138
	v_add_f32_e32 v128, v128, v129
	v_mul_f32_e32 v129, v163, v163
	v_fmac_f32_e32 v129, v162, v162
	v_add_f32_e32 v128, v129, v128
	v_mul_f32_e32 v129, v161, v161
	v_fmac_f32_e32 v129, v160, v160
	v_and_b32_e32 v130, 64, v236
	v_add_f32_e32 v128, v129, v128
	v_xor_b32_e32 v129, 16, v236
	v_add_u32_e32 v131, 64, v130
	v_cmp_lt_i32_e32 vcc, v129, v131
	v_add_f32_e32 v128, v196, v128
	s_nop 0
	v_cndmask_b32_e32 v129, v236, v129, vcc
	v_lshlrev_b32_e32 v130, 2, v129
	ds_bpermute_b32 v129, v130, v128
	s_waitcnt lgkmcnt(0)
	v_add_f32_e32 v136, v128, v129
	v_xor_b32_e32 v128, 32, v236
	v_cmp_lt_i32_e32 vcc, v128, v131
	s_nop 1
	v_cndmask_b32_e32 v128, v236, v128, vcc
	v_lshlrev_b32_e32 v131, 2, v128
	ds_bpermute_b32 v137, v131, v136
	v_lshl_add_u64 v[128:129], v[226:227], 3, s[52:53]
	s_and_saveexec_b64 s[26:27], s[40:41]
	s_cbranch_execz .LBB0_117
	s_waitcnt lgkmcnt(0)
	v_add_f32_e32 v136, v136, v137
	v_mul_f32_e32 v136, 0x4b800000, v136
	v_trunc_f32_e32 v136, v136
	v_mul_f32_e32 v137, 0x2f800000, v136
	v_floor_f32_e32 v137, v137
	v_fmac_f32_e32 v136, 0xcf800000, v137
	v_cvt_u32_f32_e32 v136, v136
	v_cvt_u32_f32_e32 v137, v137
	global_atomic_add_x2 v[128:129], v[136:137], off
; __device__ __forceinline__ unsigned long long f2ss(float v) { return (unsigned long long)(v * 16777216.0f); }
; __device__ __forceinline__ u32x4 pack8(f32x4 v0, f32x4 v1) { u32x4 w; w.x = cvt_pk_bf16(v0[0], v0[1]); w.y = cvt_pk_bf16(v0[2], v0[3]); w.z = cvt_pk_bf16(v1[0], v1[1]); w.w = cvt_pk_bf16(v1[2], v1[3]); return w; }
;     __device__ __forceinline__ void operator()(const f32x4 (&acc)[2][2][4][2], const Unit& u, int wr, int wc, int fr, int fq, const Pre&) const {
;     ...
;             for (int m = 0; m < 4; ++m) { const int row = row0 + ai * HALF + m * 16; const size_t off = (size_t)row * 1024 + col0; float sq = 0.f;
; #pragma unroll
;                 for (int bj = 0; bj < 2; ++bj) { const u32x4 bw = bwv[ai][m][bj];
;                     const f32x4 b0 = (f32x4){__uint_as_float(bw.x << 16), __uint_as_float(bw.x & 0xffff0000u), __uint_as_float(bw.y << 16), __uint_as_float(bw.y & 0xffff0000u)};
;                     const f32x4 b1 = (f32x4){__uint_as_float(bw.z << 16), __uint_as_float(bw.z & 0xffff0000u), __uint_as_float(bw.w << 16), __uint_as_float(bw.w & 0xffff0000u)};
;                     const f32x4 v0 = acc[ai][bj][m][0] + b0, v1 = acc[ai][bj][m][1] + b1;
;                     *(gu32x4*)(hb + off + bj * HALF) = pack8(v0, v1);
;                     sq += (v0[0] * v0[0] + v0[1] * v0[1]) + (v0[2] * v0[2] + v0[3] * v0[3]) + (v1[0] * v1[0] + v1[1] * v1[1]) + (v1[2] * v1[2] + v1[3] * v1[3]); }
;                 sq += __shfl_xor(sq, 16); sq += __shfl_xor(sq, 32); if (fq == 0) atomicAdd(ssn + row, f2ss(sq)); }
.LBB0_117:
	s_or_b64 exec, exec, s[26:27]
	v_lshlrev_b32_e32 v136, 16, v188
	s_waitcnt lgkmcnt(0)
	v_and_b32_e32 v137, 0xffff0000, v188
	v_lshlrev_b32_e32 v138, 16, v189
	v_and_b32_e32 v139, 0xffff0000, v189
	v_lshlrev_b32_e32 v160, 16, v190
	v_and_b32_e32 v161, 0xffff0000, v190
	v_pk_add_f32 v[108:109], v[108:109], v[136:137]
	v_pk_add_f32 v[110:111], v[110:111], v[138:139]
	v_pk_add_f32 v[138:139], v[104:105], v[160:161]
	v_cvt_pk_bf16_f32 v104, v108, v109
	v_mul_f32_e32 v109, v109, v109
	v_fmac_f32_e32 v109, v108, v108
	v_mul_f32_e32 v108, v111, v111
	v_fmac_f32_e32 v108, v110, v110
	v_lshlrev_b32_e32 v162, 16, v191
	v_and_b32_e32 v163, 0xffff0000, v191
	v_add_f32_e32 v108, v109, v108
	v_mul_f32_e32 v109, v139, v139
	v_pk_add_f32 v[136:137], v[106:107], v[162:163]
	v_fmac_f32_e32 v109, v138, v138
	v_add_f32_e32 v108, v109, v108
	v_mul_f32_e32 v109, v137, v137
	v_fmac_f32_e32 v109, v136, v136
	v_cvt_pk_bf16_f32 v105, v110, v111
	v_add_f32_e32 v160, v109, v108
	v_lshlrev_b32_e32 v108, 16, v184
	v_and_b32_e32 v109, 0xffff0000, v184
	v_lshlrev_b32_e32 v110, 16, v185
	v_and_b32_e32 v111, 0xffff0000, v185
	v_cvt_pk_bf16_f32 v106, v138, v139
	v_cvt_pk_bf16_f32 v107, v136, v137
	v_lshlrev_b32_e32 v136, 16, v186
	v_and_b32_e32 v137, 0xffff0000, v186
	v_pk_add_f32 v[102:103], v[102:103], v[110:111]
	v_pk_add_f32 v[100:101], v[100:101], v[108:109]
	v_pk_add_f32 v[110:111], v[96:97], v[136:137]
	v_mul_f32_e32 v96, v101, v101
	v_mul_f32_e32 v97, v103, v103
	v_fmac_f32_e32 v96, v100, v100
	v_fmac_f32_e32 v97, v102, v102
	v_lshlrev_b32_e32 v138, 16, v187
	v_and_b32_e32 v139, 0xffff0000, v187
	v_add_f32_e32 v96, v96, v97
	v_mul_f32_e32 v97, v111, v111
	v_pk_add_f32 v[108:109], v[98:99], v[138:139]
	v_fmac_f32_e32 v97, v110, v110
	v_add_f32_e32 v96, v97, v96
	v_mul_f32_e32 v97, v109, v109
	v_fmac_f32_e32 v97, v108, v108
	v_add_f32_e32 v96, v97, v96
	v_add_f32_e32 v99, v160, v96
	ds_bpermute_b32 v138, v130, v99
	v_lshl_add_u64 v[96:97], s[28:29], 0, v[224:225]
	v_lshl_add_u64 v[136:137], v[210:211], 1, v[96:97]
	global_store_dwordx4 v[136:137], v[104:107], off
	v_cvt_pk_bf16_f32 v98, v100, v101
	s_waitcnt lgkmcnt(0)
	v_add_f32_e32 v96, v99, v138
	ds_bpermute_b32 v97, v131, v96
	v_cvt_pk_bf16_f32 v99, v102, v103
	v_cvt_pk_bf16_f32 v100, v110, v111
	v_cvt_pk_bf16_f32 v101, v108, v109
	global_store_dwordx4 v[136:137], v[98:101], off offset:256
	s_and_saveexec_b64 s[26:27], s[40:41]
	s_cbranch_execz .LBB0_119
	s_waitcnt lgkmcnt(0)
	v_add_f32_e32 v96, v96, v97
	v_mul_f32_e32 v96, 0x4b800000, v96
	v_trunc_f32_e32 v96, v96
	v_mul_f32_e32 v97, 0x2f800000, v96
	v_floor_f32_e32 v97, v97
	v_fmac_f32_e32 v96, 0xcf800000, v97
	v_cvt_u32_f32_e32 v96, v96
	v_cvt_u32_f32_e32 v97, v97
	global_atomic_add_x2 v[128:129], v[96:97], off offset:128
.LBB0_119:
	s_or_b64 exec, exec, s[26:27]
	v_lshlrev_b32_e32 v96, 16, v180
	s_waitcnt lgkmcnt(0)
	v_and_b32_e32 v97, 0xffff0000, v180
	v_lshlrev_b32_e32 v98, 16, v181
	v_and_b32_e32 v99, 0xffff0000, v181
	v_lshlrev_b32_e32 v100, 16, v182
	v_and_b32_e32 v101, 0xffff0000, v182
	v_pk_add_f32 v[92:93], v[92:93], v[96:97]
	v_pk_add_f32 v[94:95], v[94:95], v[98:99]
	v_pk_add_f32 v[98:99], v[88:89], v[100:101]
	v_cvt_pk_bf16_f32 v88, v92, v93
	v_mul_f32_e32 v93, v93, v93
	v_fmac_f32_e32 v93, v92, v92
	v_mul_f32_e32 v92, v95, v95
	v_fmac_f32_e32 v92, v94, v94
	v_lshlrev_b32_e32 v102, 16, v183
	v_and_b32_e32 v103, 0xffff0000, v183
	v_add_f32_e32 v92, v93, v92
	v_mul_f32_e32 v93, v99, v99
	v_pk_add_f32 v[96:97], v[90:91], v[102:103]
	v_fmac_f32_e32 v93, v98, v98
	v_add_f32_e32 v92, v93, v92
	v_mul_f32_e32 v93, v97, v97
	v_fmac_f32_e32 v93, v96, v96
	v_cvt_pk_bf16_f32 v89, v94, v95
	v_add_f32_e32 v100, v93, v92
	v_lshlrev_b32_e32 v92, 16, v176
	v_and_b32_e32 v93, 0xffff0000, v176
	v_lshlrev_b32_e32 v94, 16, v177
	v_and_b32_e32 v95, 0xffff0000, v177
	v_cvt_pk_bf16_f32 v90, v98, v99
	v_cvt_pk_bf16_f32 v91, v96, v97
	v_lshlrev_b32_e32 v96, 16, v178
	v_and_b32_e32 v97, 0xffff0000, v178
	v_pk_add_f32 v[86:87], v[86:87], v[94:95]
	v_pk_add_f32 v[84:85], v[84:85], v[92:93]
	v_pk_add_f32 v[94:95], v[80:81], v[96:97]
	v_mul_f32_e32 v80, v85, v85
	v_mul_f32_e32 v81, v87, v87
	v_fmac_f32_e32 v80, v84, v84
	v_fmac_f32_e32 v81, v86, v86
	v_lshlrev_b32_e32 v98, 16, v179
	v_and_b32_e32 v99, 0xffff0000, v179
	v_add_f32_e32 v80, v80, v81
	v_mul_f32_e32 v81, v95, v95
	v_pk_add_f32 v[92:93], v[82:83], v[98:99]
	v_fmac_f32_e32 v81, v94, v94
	v_add_f32_e32 v80, v81, v80
	v_mul_f32_e32 v81, v93, v93
	v_fmac_f32_e32 v81, v92, v92
	v_add_f32_e32 v80, v81, v80
	v_add_f32_e32 v83, v100, v80
	ds_bpermute_b32 v98, v130, v83
	v_lshl_add_u64 v[80:81], s[28:29], 0, v[222:223]
	v_lshl_add_u64 v[96:97], v[210:211], 1, v[80:81]
	global_store_dwordx4 v[96:97], v[88:91], off
	v_cvt_pk_bf16_f32 v82, v84, v85
	s_waitcnt lgkmcnt(0)
	v_add_f32_e32 v80, v83, v98
	ds_bpermute_b32 v81, v131, v80
	v_cvt_pk_bf16_f32 v83, v86, v87
	v_cvt_pk_bf16_f32 v84, v94, v95
	v_cvt_pk_bf16_f32 v85, v92, v93
	global_store_dwordx4 v[96:97], v[82:85], off offset:256
	s_and_saveexec_b64 s[26:27], s[40:41]
	s_cbranch_execz .LBB0_121
	s_waitcnt lgkmcnt(0)
	v_add_f32_e32 v80, v80, v81
	v_mul_f32_e32 v80, 0x4b800000, v80
	v_trunc_f32_e32 v80, v80
	v_mul_f32_e32 v81, 0x2f800000, v80
	v_floor_f32_e32 v81, v81
	v_fmac_f32_e32 v80, 0xcf800000, v81
	v_cvt_u32_f32_e32 v80, v80
	v_cvt_u32_f32_e32 v81, v81
	global_atomic_add_x2 v[128:129], v[80:81], off offset:256
; __device__ __forceinline__ unsigned long long f2ss(float v) { return (unsigned long long)(v * 16777216.0f); }
; __device__ __forceinline__ u32x4 pack8(f32x4 v0, f32x4 v1) { u32x4 w; w.x = cvt_pk_bf16(v0[0], v0[1]); w.y = cvt_pk_bf16(v0[2], v0[3]); w.z = cvt_pk_bf16(v1[0], v1[1]); w.w = cvt_pk_bf16(v1[2], v1[3]); return w; }
;     __device__ __forceinline__ void operator()(const f32x4 (&acc)[2][2][4][2], const Unit& u, int wr, int wc, int fr, int fq, const Pre&) const {
;     ...
;             for (int m = 0; m < 4; ++m) { const int row = row0 + ai * HALF + m * 16; const size_t off = (size_t)row * 1024 + col0; float sq = 0.f;
; #pragma unroll
;                 for (int bj = 0; bj < 2; ++bj) { const u32x4 bw = bwv[ai][m][bj];
;                     const f32x4 b0 = (f32x4){__uint_as_float(bw.x << 16), __uint_as_float(bw.x & 0xffff0000u), __uint_as_float(bw.y << 16), __uint_as_float(bw.y & 0xffff0000u)};
;                     const f32x4 b1 = (f32x4){__uint_as_float(bw.z << 16), __uint_as_float(bw.z & 0xffff0000u), __uint_as_float(bw.w << 16), __uint_as_float(bw.w & 0xffff0000u)};
;                     const f32x4 v0 = acc[ai][bj][m][0] + b0, v1 = acc[ai][bj][m][1] + b1;
;                     *(gu32x4*)(hb + off + bj * HALF) = pack8(v0, v1);
;                     sq += (v0[0] * v0[0] + v0[1] * v0[1]) + (v0[2] * v0[2] + v0[3] * v0[3]) + (v1[0] * v1[0] + v1[1] * v1[1]) + (v1[2] * v1[2] + v1[3] * v1[3]); }
;                 sq += __shfl_xor(sq, 16); sq += __shfl_xor(sq, 32); if (fq == 0) atomicAdd(ssn + row, f2ss(sq)); }
.LBB0_121:
	s_or_b64 exec, exec, s[26:27]
	v_lshlrev_b32_e32 v80, 16, v172
	s_waitcnt lgkmcnt(0)
	v_and_b32_e32 v81, 0xffff0000, v172
	v_lshlrev_b32_e32 v82, 16, v173
	v_and_b32_e32 v83, 0xffff0000, v173
	v_lshlrev_b32_e32 v84, 16, v174
	v_and_b32_e32 v85, 0xffff0000, v174
	v_pk_add_f32 v[76:77], v[76:77], v[80:81]
	v_pk_add_f32 v[78:79], v[78:79], v[82:83]
	v_pk_add_f32 v[82:83], v[72:73], v[84:85]
	v_cvt_pk_bf16_f32 v72, v76, v77
	v_mul_f32_e32 v77, v77, v77
	v_fmac_f32_e32 v77, v76, v76
	v_mul_f32_e32 v76, v79, v79
	v_fmac_f32_e32 v76, v78, v78
	v_lshlrev_b32_e32 v86, 16, v175
	v_and_b32_e32 v87, 0xffff0000, v175
	v_add_f32_e32 v76, v77, v76
	v_mul_f32_e32 v77, v83, v83
	v_pk_add_f32 v[80:81], v[74:75], v[86:87]
	v_fmac_f32_e32 v77, v82, v82
	v_add_f32_e32 v76, v77, v76
	v_mul_f32_e32 v77, v81, v81
	v_fmac_f32_e32 v77, v80, v80
	v_cvt_pk_bf16_f32 v73, v78, v79
	v_add_f32_e32 v84, v77, v76
	v_lshlrev_b32_e32 v76, 16, v164
	v_and_b32_e32 v77, 0xffff0000, v164
	v_lshlrev_b32_e32 v78, 16, v165
	v_and_b32_e32 v79, 0xffff0000, v165
	v_cvt_pk_bf16_f32 v74, v82, v83
	v_cvt_pk_bf16_f32 v75, v80, v81
	v_lshlrev_b32_e32 v80, 16, v166
	v_and_b32_e32 v81, 0xffff0000, v166
	v_pk_add_f32 v[70:71], v[70:71], v[78:79]
	v_pk_add_f32 v[68:69], v[68:69], v[76:77]
	v_pk_add_f32 v[78:79], v[64:65], v[80:81]
	v_mul_f32_e32 v64, v69, v69
	v_mul_f32_e32 v65, v71, v71
	v_fmac_f32_e32 v64, v68, v68
	v_fmac_f32_e32 v65, v70, v70
	v_lshlrev_b32_e32 v82, 16, v167
	v_and_b32_e32 v83, 0xffff0000, v167
	v_add_f32_e32 v64, v64, v65
	v_mul_f32_e32 v65, v79, v79
	v_pk_add_f32 v[76:77], v[66:67], v[82:83]
	v_fmac_f32_e32 v65, v78, v78
	v_add_f32_e32 v64, v65, v64
	v_mul_f32_e32 v65, v77, v77
	v_fmac_f32_e32 v65, v76, v76
	v_add_f32_e32 v64, v65, v64
	v_add_f32_e32 v67, v84, v64
	ds_bpermute_b32 v82, v130, v67
	v_lshl_add_u64 v[64:65], s[28:29], 0, v[220:221]
	v_lshl_add_u64 v[80:81], v[210:211], 1, v[64:65]
	global_store_dwordx4 v[80:81], v[72:75], off
	v_cvt_pk_bf16_f32 v66, v68, v69
	s_waitcnt lgkmcnt(0)
	v_add_f32_e32 v64, v67, v82
	ds_bpermute_b32 v65, v131, v64
	v_cvt_pk_bf16_f32 v67, v70, v71
	v_cvt_pk_bf16_f32 v68, v78, v79
	v_cvt_pk_bf16_f32 v69, v76, v77
	global_store_dwordx4 v[80:81], v[66:69], off offset:256
	s_and_saveexec_b64 s[26:27], s[40:41]
	s_cbranch_execz .LBB0_123
	s_waitcnt lgkmcnt(0)
	v_add_f32_e32 v64, v64, v65
	v_mul_f32_e32 v64, 0x4b800000, v64
	v_trunc_f32_e32 v64, v64
	v_mul_f32_e32 v65, 0x2f800000, v64
	v_floor_f32_e32 v65, v65
	v_fmac_f32_e32 v64, 0xcf800000, v65
	v_cvt_u32_f32_e32 v64, v64
	v_cvt_u32_f32_e32 v65, v65
	global_atomic_add_x2 v[128:129], v[64:65], off offset:384
.LBB0_123:
	s_or_b64 exec, exec, s[26:27]
	v_lshlrev_b32_e32 v64, 16, v156
	s_waitcnt lgkmcnt(0)
	v_and_b32_e32 v65, 0xffff0000, v156
	v_lshlrev_b32_e32 v66, 16, v157
	v_and_b32_e32 v67, 0xffff0000, v157
	v_lshlrev_b32_e32 v68, 16, v158
	v_and_b32_e32 v69, 0xffff0000, v158
	v_pk_add_f32 v[60:61], v[60:61], v[64:65]
	v_pk_add_f32 v[62:63], v[62:63], v[66:67]
	v_pk_add_f32 v[66:67], v[56:57], v[68:69]
	v_cvt_pk_bf16_f32 v56, v60, v61
	v_mul_f32_e32 v61, v61, v61
	v_fmac_f32_e32 v61, v60, v60
	v_mul_f32_e32 v60, v63, v63
	v_fmac_f32_e32 v60, v62, v62
	v_lshlrev_b32_e32 v70, 16, v159
	v_and_b32_e32 v71, 0xffff0000, v159
	v_add_f32_e32 v60, v61, v60
	v_mul_f32_e32 v61, v67, v67
	v_pk_add_f32 v[64:65], v[58:59], v[70:71]
	v_fmac_f32_e32 v61, v66, v66
	v_add_f32_e32 v60, v61, v60
	v_mul_f32_e32 v61, v65, v65
	v_fmac_f32_e32 v61, v64, v64
	v_cvt_pk_bf16_f32 v57, v62, v63
	v_add_f32_e32 v68, v61, v60
	v_lshlrev_b32_e32 v60, 16, v152
	v_and_b32_e32 v61, 0xffff0000, v152
	v_lshlrev_b32_e32 v62, 16, v153
	v_and_b32_e32 v63, 0xffff0000, v153
	v_cvt_pk_bf16_f32 v58, v66, v67
	v_cvt_pk_bf16_f32 v59, v64, v65
	v_lshlrev_b32_e32 v64, 16, v154
	v_and_b32_e32 v65, 0xffff0000, v154
	v_pk_add_f32 v[54:55], v[54:55], v[62:63]
	v_pk_add_f32 v[52:53], v[52:53], v[60:61]
	v_pk_add_f32 v[62:63], v[48:49], v[64:65]
	v_mul_f32_e32 v48, v53, v53
	v_mul_f32_e32 v49, v55, v55
	v_fmac_f32_e32 v48, v52, v52
	v_fmac_f32_e32 v49, v54, v54
	v_lshlrev_b32_e32 v66, 16, v155
	v_and_b32_e32 v67, 0xffff0000, v155
	v_add_f32_e32 v48, v48, v49
	v_mul_f32_e32 v49, v63, v63
	v_pk_add_f32 v[60:61], v[50:51], v[66:67]
	v_fmac_f32_e32 v49, v62, v62
	v_add_f32_e32 v48, v49, v48
	v_mul_f32_e32 v49, v61, v61
	v_fmac_f32_e32 v49, v60, v60
	v_add_f32_e32 v48, v49, v48
	v_add_f32_e32 v51, v68, v48
	ds_bpermute_b32 v66, v130, v51
	v_lshl_add_u64 v[48:49], s[28:29], 0, v[218:219]
	v_lshl_add_u64 v[64:65], v[210:211], 1, v[48:49]
	global_store_dwordx4 v[64:65], v[56:59], off
	v_cvt_pk_bf16_f32 v50, v52, v53
	s_waitcnt lgkmcnt(0)
	v_add_f32_e32 v48, v51, v66
	ds_bpermute_b32 v49, v131, v48
	v_cvt_pk_bf16_f32 v51, v54, v55
	v_cvt_pk_bf16_f32 v52, v62, v63
	v_cvt_pk_bf16_f32 v53, v60, v61
	global_store_dwordx4 v[64:65], v[50:53], off offset:256
	s_and_saveexec_b64 s[26:27], s[40:41]
	s_cbranch_execz .LBB0_125
	s_waitcnt lgkmcnt(0)
	v_add_f32_e32 v48, v48, v49
	v_mul_f32_e32 v48, 0x4b800000, v48
	v_trunc_f32_e32 v48, v48
	v_mul_f32_e32 v49, 0x2f800000, v48
	v_floor_f32_e32 v49, v49
	v_fmac_f32_e32 v48, 0xcf800000, v49
	v_cvt_u32_f32_e32 v48, v48
	v_cvt_u32_f32_e32 v49, v49
	global_atomic_add_x2 v[128:129], v[48:49], off offset:1024
; __device__ __forceinline__ unsigned long long f2ss(float v) { return (unsigned long long)(v * 16777216.0f); }
; __device__ __forceinline__ u32x4 pack8(f32x4 v0, f32x4 v1) { u32x4 w; w.x = cvt_pk_bf16(v0[0], v0[1]); w.y = cvt_pk_bf16(v0[2], v0[3]); w.z = cvt_pk_bf16(v1[0], v1[1]); w.w = cvt_pk_bf16(v1[2], v1[3]); return w; }
;     __device__ __forceinline__ void operator()(const f32x4 (&acc)[2][2][4][2], const Unit& u, int wr, int wc, int fr, int fq, const Pre&) const {
;     ...
;             for (int m = 0; m < 4; ++m) { const int row = row0 + ai * HALF + m * 16; const size_t off = (size_t)row * 1024 + col0; float sq = 0.f;
; #pragma unroll
;                 for (int bj = 0; bj < 2; ++bj) { const u32x4 bw = bwv[ai][m][bj];
;                     const f32x4 b0 = (f32x4){__uint_as_float(bw.x << 16), __uint_as_float(bw.x & 0xffff0000u), __uint_as_float(bw.y << 16), __uint_as_float(bw.y & 0xffff0000u)};
;                     const f32x4 b1 = (f32x4){__uint_as_float(bw.z << 16), __uint_as_float(bw.z & 0xffff0000u), __uint_as_float(bw.w << 16), __uint_as_float(bw.w & 0xffff0000u)};
;                     const f32x4 v0 = acc[ai][bj][m][0] + b0, v1 = acc[ai][bj][m][1] + b1;
;                     *(gu32x4*)(hb + off + bj * HALF) = pack8(v0, v1);
;                     sq += (v0[0] * v0[0] + v0[1] * v0[1]) + (v0[2] * v0[2] + v0[3] * v0[3]) + (v1[0] * v1[0] + v1[1] * v1[1]) + (v1[2] * v1[2] + v1[3] * v1[3]); }
;                 sq += __shfl_xor(sq, 16); sq += __shfl_xor(sq, 32); if (fq == 0) atomicAdd(ssn + row, f2ss(sq)); }
.LBB0_125:
	s_or_b64 exec, exec, s[26:27]
	v_lshlrev_b32_e32 v48, 16, v140
	s_waitcnt lgkmcnt(0)
	v_and_b32_e32 v49, 0xffff0000, v140
	v_lshlrev_b32_e32 v50, 16, v141
	v_and_b32_e32 v51, 0xffff0000, v141
	v_lshlrev_b32_e32 v52, 16, v142
	v_and_b32_e32 v53, 0xffff0000, v142
	v_pk_add_f32 v[44:45], v[44:45], v[48:49]
	v_pk_add_f32 v[46:47], v[46:47], v[50:51]
	v_pk_add_f32 v[50:51], v[40:41], v[52:53]
	v_cvt_pk_bf16_f32 v40, v44, v45
	v_mul_f32_e32 v45, v45, v45
	v_fmac_f32_e32 v45, v44, v44
	v_mul_f32_e32 v44, v47, v47
	v_fmac_f32_e32 v44, v46, v46
	v_lshlrev_b32_e32 v54, 16, v143
	v_and_b32_e32 v55, 0xffff0000, v143
	v_add_f32_e32 v44, v45, v44
	v_mul_f32_e32 v45, v51, v51
	v_pk_add_f32 v[48:49], v[42:43], v[54:55]
	v_fmac_f32_e32 v45, v50, v50
	v_add_f32_e32 v44, v45, v44
	v_mul_f32_e32 v45, v49, v49
	v_fmac_f32_e32 v45, v48, v48
	v_cvt_pk_bf16_f32 v41, v46, v47
	v_add_f32_e32 v52, v45, v44
	v_lshlrev_b32_e32 v44, 16, v132
	v_and_b32_e32 v45, 0xffff0000, v132
	v_lshlrev_b32_e32 v46, 16, v133
	v_and_b32_e32 v47, 0xffff0000, v133
	v_cvt_pk_bf16_f32 v42, v50, v51
	v_cvt_pk_bf16_f32 v43, v48, v49
	v_lshlrev_b32_e32 v48, 16, v134
	v_and_b32_e32 v49, 0xffff0000, v134
	v_pk_add_f32 v[38:39], v[38:39], v[46:47]
	v_pk_add_f32 v[36:37], v[36:37], v[44:45]
	v_pk_add_f32 v[46:47], v[32:33], v[48:49]
	v_mul_f32_e32 v32, v37, v37
	v_mul_f32_e32 v33, v39, v39
	v_fmac_f32_e32 v32, v36, v36
	v_fmac_f32_e32 v33, v38, v38
	v_lshlrev_b32_e32 v50, 16, v135
	v_and_b32_e32 v51, 0xffff0000, v135
	v_add_f32_e32 v32, v32, v33
	v_mul_f32_e32 v33, v47, v47
	v_pk_add_f32 v[44:45], v[34:35], v[50:51]
	v_fmac_f32_e32 v33, v46, v46
	v_add_f32_e32 v32, v33, v32
	v_mul_f32_e32 v33, v45, v45
	v_fmac_f32_e32 v33, v44, v44
	v_add_f32_e32 v32, v33, v32
	v_add_f32_e32 v35, v52, v32
	ds_bpermute_b32 v50, v130, v35
	v_lshl_add_u64 v[32:33], s[28:29], 0, v[216:217]
	v_lshl_add_u64 v[48:49], v[210:211], 1, v[32:33]
	global_store_dwordx4 v[48:49], v[40:43], off
	v_cvt_pk_bf16_f32 v34, v36, v37
	s_waitcnt lgkmcnt(0)
	v_add_f32_e32 v32, v35, v50
	ds_bpermute_b32 v33, v131, v32
	v_cvt_pk_bf16_f32 v35, v38, v39
	v_cvt_pk_bf16_f32 v36, v46, v47
	v_cvt_pk_bf16_f32 v37, v44, v45
	global_store_dwordx4 v[48:49], v[34:37], off offset:256
	s_and_saveexec_b64 s[26:27], s[40:41]
	s_cbranch_execz .LBB0_127
	s_waitcnt lgkmcnt(0)
	v_add_f32_e32 v32, v32, v33
	v_mul_f32_e32 v32, 0x4b800000, v32
	v_trunc_f32_e32 v32, v32
	v_mul_f32_e32 v33, 0x2f800000, v32
	v_floor_f32_e32 v33, v33
	v_fmac_f32_e32 v32, 0xcf800000, v33
	v_cvt_u32_f32_e32 v32, v32
	v_cvt_u32_f32_e32 v33, v33
	global_atomic_add_x2 v[128:129], v[32:33], off offset:1152
; __device__ __forceinline__ unsigned long long f2ss(float v) { return (unsigned long long)(v * 16777216.0f); }
; __device__ __forceinline__ u32x4 pack8(f32x4 v0, f32x4 v1) { u32x4 w; w.x = cvt_pk_bf16(v0[0], v0[1]); w.y = cvt_pk_bf16(v0[2], v0[3]); w.z = cvt_pk_bf16(v1[0], v1[1]); w.w = cvt_pk_bf16(v1[2], v1[3]); return w; }
;     __device__ __forceinline__ void operator()(const f32x4 (&acc)[2][2][4][2], const Unit& u, int wr, int wc, int fr, int fq, const Pre&) const {
;     ...
;             for (int m = 0; m < 4; ++m) { const int row = row0 + ai * HALF + m * 16; const size_t off = (size_t)row * 1024 + col0; float sq = 0.f;
; #pragma unroll
;                 for (int bj = 0; bj < 2; ++bj) { const u32x4 bw = bwv[ai][m][bj];
;                     const f32x4 b0 = (f32x4){__uint_as_float(bw.x << 16), __uint_as_float(bw.x & 0xffff0000u), __uint_as_float(bw.y << 16), __uint_as_float(bw.y & 0xffff0000u)};
;                     const f32x4 b1 = (f32x4){__uint_as_float(bw.z << 16), __uint_as_float(bw.z & 0xffff0000u), __uint_as_float(bw.w << 16), __uint_as_float(bw.w & 0xffff0000u)};
;                     const f32x4 v0 = acc[ai][bj][m][0] + b0, v1 = acc[ai][bj][m][1] + b1;
;                     *(gu32x4*)(hb + off + bj * HALF) = pack8(v0, v1);
;                     sq += (v0[0] * v0[0] + v0[1] * v0[1]) + (v0[2] * v0[2] + v0[3] * v0[3]) + (v1[0] * v1[0] + v1[1] * v1[1]) + (v1[2] * v1[2] + v1[3] * v1[3]); }
;                 sq += __shfl_xor(sq, 16); sq += __shfl_xor(sq, 32); if (fq == 0) atomicAdd(ssn + row, f2ss(sq)); }
.LBB0_127:
	s_or_b64 exec, exec, s[26:27]
	v_lshlrev_b32_e32 v32, 16, v124
	s_waitcnt lgkmcnt(0)
	v_and_b32_e32 v33, 0xffff0000, v124
	v_lshlrev_b32_e32 v34, 16, v125
	v_and_b32_e32 v35, 0xffff0000, v125
	v_lshlrev_b32_e32 v36, 16, v126
	v_and_b32_e32 v37, 0xffff0000, v126
	v_pk_add_f32 v[28:29], v[28:29], v[32:33]
	v_pk_add_f32 v[30:31], v[30:31], v[34:35]
	v_pk_add_f32 v[34:35], v[24:25], v[36:37]
	v_cvt_pk_bf16_f32 v24, v28, v29
	v_mul_f32_e32 v29, v29, v29
	v_fmac_f32_e32 v29, v28, v28
	v_mul_f32_e32 v28, v31, v31
	v_fmac_f32_e32 v28, v30, v30
	v_lshlrev_b32_e32 v38, 16, v127
	v_and_b32_e32 v39, 0xffff0000, v127
	v_add_f32_e32 v28, v29, v28
	v_mul_f32_e32 v29, v35, v35
	v_pk_add_f32 v[32:33], v[26:27], v[38:39]
	v_fmac_f32_e32 v29, v34, v34
	v_add_f32_e32 v28, v29, v28
	v_mul_f32_e32 v29, v33, v33
	v_fmac_f32_e32 v29, v32, v32
	v_cvt_pk_bf16_f32 v25, v30, v31
	v_add_f32_e32 v36, v29, v28
	v_lshlrev_b32_e32 v28, 16, v116
	v_and_b32_e32 v29, 0xffff0000, v116
	v_lshlrev_b32_e32 v30, 16, v117
	v_and_b32_e32 v31, 0xffff0000, v117
	v_cvt_pk_bf16_f32 v26, v34, v35
	v_cvt_pk_bf16_f32 v27, v32, v33
	v_lshlrev_b32_e32 v32, 16, v118
	v_and_b32_e32 v33, 0xffff0000, v118
	v_pk_add_f32 v[22:23], v[22:23], v[30:31]
	v_pk_add_f32 v[20:21], v[20:21], v[28:29]
	v_pk_add_f32 v[30:31], v[16:17], v[32:33]
	v_mul_f32_e32 v16, v21, v21
	v_mul_f32_e32 v17, v23, v23
	v_fmac_f32_e32 v16, v20, v20
	v_fmac_f32_e32 v17, v22, v22
	v_lshlrev_b32_e32 v34, 16, v119
	v_and_b32_e32 v35, 0xffff0000, v119
	v_add_f32_e32 v16, v16, v17
	v_mul_f32_e32 v17, v31, v31
	v_pk_add_f32 v[28:29], v[18:19], v[34:35]
	v_fmac_f32_e32 v17, v30, v30
	v_add_f32_e32 v16, v17, v16
	v_mul_f32_e32 v17, v29, v29
	v_fmac_f32_e32 v17, v28, v28
	v_add_f32_e32 v16, v17, v16
	v_add_f32_e32 v19, v36, v16
	ds_bpermute_b32 v34, v130, v19
	v_lshl_add_u64 v[16:17], s[28:29], 0, v[214:215]
	v_lshl_add_u64 v[32:33], v[210:211], 1, v[16:17]
	global_store_dwordx4 v[32:33], v[24:27], off
	v_cvt_pk_bf16_f32 v18, v20, v21
	s_waitcnt lgkmcnt(0)
	v_add_f32_e32 v16, v19, v34
	ds_bpermute_b32 v17, v131, v16
	v_cvt_pk_bf16_f32 v19, v22, v23
	v_cvt_pk_bf16_f32 v20, v30, v31
	v_cvt_pk_bf16_f32 v21, v28, v29
	global_store_dwordx4 v[32:33], v[18:21], off offset:256
	s_and_saveexec_b64 s[26:27], s[40:41]
	s_cbranch_execz .LBB0_129
	s_waitcnt lgkmcnt(0)
	v_add_f32_e32 v16, v16, v17
	v_mul_f32_e32 v16, 0x4b800000, v16
	v_trunc_f32_e32 v16, v16
	v_mul_f32_e32 v17, 0x2f800000, v16
	v_floor_f32_e32 v17, v17
	v_fmac_f32_e32 v16, 0xcf800000, v17
	v_cvt_u32_f32_e32 v16, v16
	v_cvt_u32_f32_e32 v17, v17
	global_atomic_add_x2 v[128:129], v[16:17], off offset:1280
.LBB0_129:
	s_or_b64 exec, exec, s[26:27]
	v_lshlrev_b32_e32 v16, 16, v120
	s_waitcnt lgkmcnt(0)
	v_and_b32_e32 v17, 0xffff0000, v120
	v_lshlrev_b32_e32 v18, 16, v121
	v_and_b32_e32 v19, 0xffff0000, v121
	v_lshlrev_b32_e32 v20, 16, v122
	v_and_b32_e32 v21, 0xffff0000, v122
	v_pk_add_f32 v[12:13], v[12:13], v[16:17]
	v_pk_add_f32 v[14:15], v[14:15], v[18:19]
	v_pk_add_f32 v[18:19], v[8:9], v[20:21]
	v_cvt_pk_bf16_f32 v8, v12, v13
	v_mul_f32_e32 v13, v13, v13
	v_fmac_f32_e32 v13, v12, v12
	v_mul_f32_e32 v12, v15, v15
	v_fmac_f32_e32 v12, v14, v14
	v_lshlrev_b32_e32 v22, 16, v123
	v_and_b32_e32 v23, 0xffff0000, v123
	v_add_f32_e32 v12, v13, v12
	v_mul_f32_e32 v13, v19, v19
	v_pk_add_f32 v[16:17], v[10:11], v[22:23]
	v_fmac_f32_e32 v13, v18, v18
	v_add_f32_e32 v12, v13, v12
	v_mul_f32_e32 v13, v17, v17
	v_fmac_f32_e32 v13, v16, v16
	v_cvt_pk_bf16_f32 v9, v14, v15
	v_add_f32_e32 v20, v13, v12
	v_lshlrev_b32_e32 v12, 16, v112
	v_and_b32_e32 v13, 0xffff0000, v112
	v_lshlrev_b32_e32 v14, 16, v113
	v_and_b32_e32 v15, 0xffff0000, v113
	v_cvt_pk_bf16_f32 v10, v18, v19
	v_cvt_pk_bf16_f32 v11, v16, v17
	v_lshlrev_b32_e32 v16, 16, v114
	v_and_b32_e32 v17, 0xffff0000, v114
	v_pk_add_f32 v[6:7], v[6:7], v[14:15]
	v_pk_add_f32 v[4:5], v[4:5], v[12:13]
	v_pk_add_f32 v[14:15], v[0:1], v[16:17]
	v_mul_f32_e32 v0, v5, v5
	v_mul_f32_e32 v1, v7, v7
	v_fmac_f32_e32 v0, v4, v4
	v_fmac_f32_e32 v1, v6, v6
	v_lshlrev_b32_e32 v18, 16, v115
	v_and_b32_e32 v19, 0xffff0000, v115
	v_add_f32_e32 v0, v0, v1
	v_mul_f32_e32 v1, v15, v15
	v_pk_add_f32 v[12:13], v[2:3], v[18:19]
	v_fmac_f32_e32 v1, v14, v14
	v_add_f32_e32 v0, v1, v0
	v_mul_f32_e32 v1, v13, v13
	v_fmac_f32_e32 v1, v12, v12
	v_add_f32_e32 v0, v1, v0
	v_add_f32_e32 v3, v20, v0
	ds_bpermute_b32 v18, v130, v3
	v_lshl_add_u64 v[0:1], s[28:29], 0, v[212:213]
	v_lshl_add_u64 v[16:17], v[210:211], 1, v[0:1]
	global_store_dwordx4 v[16:17], v[8:11], off
	v_cvt_pk_bf16_f32 v2, v4, v5
	s_waitcnt lgkmcnt(0)
	v_add_f32_e32 v0, v3, v18
	ds_bpermute_b32 v1, v131, v0
	v_cvt_pk_bf16_f32 v3, v6, v7
	v_cvt_pk_bf16_f32 v4, v14, v15
	v_cvt_pk_bf16_f32 v5, v12, v13
	global_store_dwordx4 v[16:17], v[2:5], off offset:256
	s_and_saveexec_b64 s[26:27], s[40:41]
	s_cbranch_execz .LBB0_131
	s_waitcnt lgkmcnt(0)
	v_add_f32_e32 v0, v0, v1
	v_mul_f32_e32 v0, 0x4b800000, v0
	v_trunc_f32_e32 v0, v0
	v_mul_f32_e32 v1, 0x2f800000, v0
	v_floor_f32_e32 v1, v1
	v_fmac_f32_e32 v0, 0xcf800000, v1
	v_cvt_u32_f32_e32 v0, v0
	v_cvt_u32_f32_e32 v1, v1
	global_atomic_add_x2 v[128:129], v[0:1], off offset:1408

; __device__ __forceinline__ float ss2f(unsigned long long v) { return (float)v * (1.0f / 16777216.0f); }
; __device__ __forceinline__ f32x4 silu4(f32x4 v) { return (f32x4){silu1(v[0]), silu1(v[1]), silu1(v[2]), silu1(v[3])}; }
; __device__ __forceinline__ u32x4 pack8(f32x4 v0, f32x4 v1) { u32x4 w; w.x = cvt_pk_bf16(v0[0], v0[1]); w.y = cvt_pk_bf16(v0[2], v0[3]); w.z = cvt_pk_bf16(v1[0], v1[1]); w.w = cvt_pk_bf16(v1[2], v1[3]); return w; }
; __device__ __forceinline__ void rstd8(float (&r)[8], const PreSS& p, int fr) {
;     const float a = __builtin_amdgcn_rsqf(ss2f(p.v0) * (1.0f / 1024.0f) + RMS_EPS), b = __builtin_amdgcn_rsqf(ss2f(p.v1) * (1.0f / 1024.0f) + RMS_EPS);
; #pragma unroll
;     for (int k = 0; k < 8; ++k) r[k] = __shfl((k & 1) ? b : a, fr + 16 * (k >> 1));
; }
;     __device__ __forceinline__ void operator()(const f32x4 (&acc)[2][2][4][2], const Unit& u, int wr, int wc, int fr, int fq, const Pre& pre) const {
;         const int row0 = u.pm * BM + wr * 64 + fr, col0 = u.pn * HALF + wc * 32 + 8 * fq;
;         float rs8[8]; rstd8(rs8, pre, fr);
; #pragma unroll
;         for (int ai = 0; ai < 2; ++ai)
; #pragma unroll
;             for (int m = 0; m < 4; ++m) { const int row = row0 + ai * HALF + m * 16; const float r = rs8[ai * 4 + m];
;                 const f32x4 g0 = silu4(acc[ai][0][m][0] * r), g1 = silu4(acc[ai][0][m][1] * r);
;                 const f32x4 v0 = g0 * (acc[ai][1][m][0] * r), v1 = g1 * (acc[ai][1][m][1] * r);
;                 *(u32x4*)(O + (size_t)row * 2816 + col0) = pack8(v0, v1); }
.LBB0_155:
	s_waitcnt vmcnt(8)
	v_ffbh_u32_e32 v143, v153
	v_min_u32_e32 v143, 32, v143
	v_lshlrev_b64 v[152:153], v143, v[152:153]
	v_min_u32_e32 v152, 1, v152
	v_or_b32_e32 v152, v153, v152
	v_cvt_f32_u32_e32 v152, v152
	v_sub_u32_e32 v143, 32, v143
	v_lshl_or_b32 v164, s4, 7, v159
	v_ashrrev_i32_e32 v165, 31, v164
	v_ldexp_f32 v143, v152, v143
	v_ffbh_u32_e32 v152, v147
	v_min_u32_e32 v152, 32, v152
	v_lshlrev_b64 v[146:147], v152, v[146:147]
	v_min_u32_e32 v146, 1, v146
	v_or_b32_e32 v146, v147, v146
	v_mul_f32_e32 v143, 0x33800000, v143
	v_cvt_f32_u32_e32 v146, v146
	v_fmamk_f32 v143, v143, 0x3a800000, v233
	v_rsq_f32_e32 v143, v143
	v_sub_u32_e32 v147, 32, v152
	v_ldexp_f32 v146, v146, v147
	v_and_or_b32 v147, v236, 64, v145
	v_lshlrev_b32_e32 v147, 2, v147
	ds_bpermute_b32 v166, v147, v143
	ds_bpermute_b32 v160, v147, v143 offset:64
	ds_bpermute_b32 v156, v147, v143 offset:128
	ds_bpermute_b32 v152, v147, v143 offset:192
	v_mul_f32_e32 v146, 0x33800000, v146
	s_waitcnt lgkmcnt(3)
	v_pk_mul_f32 v[124:125], v[124:125], v[166:167] op_sel_hi:[1,0]
	v_pk_mul_f32 v[126:127], v[126:127], v[166:167] op_sel_hi:[1,0]
	v_mul_f32_e32 v143, 0xbfb8aa3b, v124
	v_exp_f32_e32 v143, v143
	v_pk_mul_f32 v[120:121], v[120:121], v[166:167] op_sel_hi:[1,0]
	v_pk_mul_f32 v[122:123], v[122:123], v[166:167] op_sel_hi:[1,0]
	v_fmamk_f32 v146, v146, 0x3a800000, v233
	v_add_f32_e32 v143, 1.0, v143
	v_rcp_f32_e32 v168, v143
	v_mul_f32_e32 v143, 0xbfb8aa3b, v125
	v_exp_f32_e32 v143, v143
	v_rsq_f32_e32 v146, v146
	v_pk_mul_f32 v[116:117], v[116:117], v[166:167] op_sel_hi:[1,0]
	v_pk_mul_f32 v[118:119], v[118:119], v[166:167] op_sel_hi:[1,0]
	v_add_f32_e32 v143, 1.0, v143
	v_rcp_f32_e32 v169, v143
	v_mul_f32_e32 v143, 0xbfb8aa3b, v126
	v_exp_f32_e32 v143, v143
	ds_bpermute_b32 v162, v147, v146
	v_pk_mul_f32 v[124:125], v[124:125], v[168:169]
	v_pk_mul_f32 v[112:113], v[112:113], v[166:167] op_sel_hi:[1,0]
	v_add_f32_e32 v143, 1.0, v143
	v_rcp_f32_e32 v170, v143
	v_mul_f32_e32 v143, 0xbfb8aa3b, v127
	v_exp_f32_e32 v143, v143
	v_pk_mul_f32 v[116:117], v[116:117], v[124:125]
	v_pk_mul_f32 v[114:115], v[114:115], v[166:167] op_sel_hi:[1,0]
	v_cvt_pk_bf16_f32 v116, v116, v117
	v_add_f32_e32 v143, 1.0, v143
	v_rcp_f32_e32 v171, v143
	v_mul_f32_e32 v143, 0xbfb8aa3b, v120
	v_exp_f32_e32 v143, v143
	s_movk_i32 s4, 0x1600
	v_pk_mul_f32 v[126:127], v[126:127], v[170:171]
	s_waitcnt lgkmcnt(0)
	v_pk_mul_f32 v[110:111], v[110:111], v[162:163] op_sel_hi:[1,0]
	v_add_f32_e32 v143, 1.0, v143
	v_rcp_f32_e32 v168, v143
	v_mul_f32_e32 v143, 0xbfb8aa3b, v121
	v_exp_f32_e32 v143, v143
	v_pk_mul_f32 v[118:119], v[118:119], v[126:127]
	v_pk_mul_f32 v[108:109], v[108:109], v[162:163] op_sel_hi:[1,0]
	v_cvt_pk_bf16_f32 v117, v118, v119
	v_add_f32_e32 v143, 1.0, v143
	v_rcp_f32_e32 v169, v143
	v_mul_f32_e32 v143, 0xbfb8aa3b, v122
	v_exp_f32_e32 v143, v143
	v_pk_mul_f32 v[106:107], v[106:107], v[162:163] op_sel_hi:[1,0]
	v_pk_mul_f32 v[120:121], v[120:121], v[168:169]
	v_pk_mul_f32 v[104:105], v[104:105], v[162:163] op_sel_hi:[1,0]
	v_add_f32_e32 v143, 1.0, v143
	v_rcp_f32_e32 v170, v143
	v_mul_f32_e32 v143, 0xbfb8aa3b, v123
	v_exp_f32_e32 v143, v143
	v_pk_mul_f32 v[112:113], v[112:113], v[120:121]
	v_pk_mul_f32 v[100:101], v[100:101], v[162:163] op_sel_hi:[1,0]
	v_cvt_pk_bf16_f32 v118, v112, v113
	v_add_f32_e32 v143, 1.0, v143
	v_rcp_f32_e32 v171, v143
	v_mov_b64_e32 v[112:113], s[30:31]
	v_mad_i64_i32 v[120:121], s[20:21], v142, s4, v[112:113]
	v_pk_mul_f32 v[122:123], v[122:123], v[170:171]
	v_pk_mul_f32 v[96:97], v[96:97], v[162:163] op_sel_hi:[1,0]
	v_pk_mul_f32 v[114:115], v[114:115], v[122:123]
	v_pk_mul_f32 v[98:99], v[98:99], v[162:163] op_sel_hi:[1,0]
	v_cvt_pk_bf16_f32 v119, v114, v115
	v_lshlrev_b64 v[114:115], 1, v[164:165]
	v_lshl_add_u64 v[120:121], v[120:121], 0, v[114:115]
	global_store_dwordx4 v[120:121], v[116:119], off nt
	v_or_b32_e32 v120, 16, v142
	v_pk_mul_f32 v[102:103], v[102:103], v[162:163] op_sel_hi:[1,0]
	v_mul_f32_e32 v116, 0xbfb8aa3b, v108
	v_mul_f32_e32 v117, 0xbfb8aa3b, v109
	v_mul_f32_e32 v118, 0xbfb8aa3b, v110
	v_mul_f32_e32 v119, 0xbfb8aa3b, v111
	v_exp_f32_e32 v116, v116
	v_exp_f32_e32 v117, v117
	v_exp_f32_e32 v118, v118
	v_exp_f32_e32 v119, v119
	v_add_f32_e32 v116, 1.0, v116
	v_add_f32_e32 v117, 1.0, v117
	v_add_f32_e32 v118, 1.0, v118
	v_add_f32_e32 v119, 1.0, v119
	v_rcp_f32_e32 v116, v116
	v_rcp_f32_e32 v117, v117
	v_rcp_f32_e32 v118, v118
	v_rcp_f32_e32 v119, v119
	v_pk_mul_f32 v[94:95], v[94:95], v[160:161] op_sel_hi:[1,0]
	v_pk_mul_f32 v[108:109], v[108:109], v[116:117]
	v_mul_f32_e32 v116, 0xbfb8aa3b, v104
	v_pk_mul_f32 v[110:111], v[110:111], v[118:119]
	v_mul_f32_e32 v117, 0xbfb8aa3b, v105
	v_mul_f32_e32 v118, 0xbfb8aa3b, v106
	v_mul_f32_e32 v119, 0xbfb8aa3b, v107
	v_exp_f32_e32 v116, v116
	v_exp_f32_e32 v117, v117
	v_exp_f32_e32 v118, v118
	v_exp_f32_e32 v119, v119
	v_add_f32_e32 v116, 1.0, v116
	v_add_f32_e32 v117, 1.0, v117
	v_add_f32_e32 v118, 1.0, v118
	v_add_f32_e32 v119, 1.0, v119
	v_rcp_f32_e32 v116, v116
	v_rcp_f32_e32 v117, v117
	v_rcp_f32_e32 v118, v118
	v_rcp_f32_e32 v119, v119
	v_pk_mul_f32 v[100:101], v[100:101], v[108:109]
	v_pk_mul_f32 v[104:105], v[104:105], v[116:117]
	v_pk_mul_f32 v[102:103], v[102:103], v[110:111]
	v_pk_mul_f32 v[106:107], v[106:107], v[118:119]
	v_pk_mul_f32 v[92:93], v[92:93], v[160:161] op_sel_hi:[1,0]
	v_pk_mul_f32 v[106:107], v[98:99], v[106:107]
	v_pk_mul_f32 v[98:99], v[96:97], v[104:105]
	v_cvt_pk_bf16_f32 v96, v100, v101
	v_mad_i64_i32 v[100:101], s[20:21], v120, s4, v[112:113]
	v_cvt_pk_bf16_f32 v97, v102, v103
	v_cvt_pk_bf16_f32 v98, v98, v99
	v_cvt_pk_bf16_f32 v99, v106, v107
; __device__ __forceinline__ f32x4 silu4(f32x4 v) { return (f32x4){silu1(v[0]), silu1(v[1]), silu1(v[2]), silu1(v[3])}; }
; __device__ __forceinline__ u32x4 pack8(f32x4 v0, f32x4 v1) { u32x4 w; w.x = cvt_pk_bf16(v0[0], v0[1]); w.y = cvt_pk_bf16(v0[2], v0[3]); w.z = cvt_pk_bf16(v1[0], v1[1]); w.w = cvt_pk_bf16(v1[2], v1[3]); return w; }
;     __device__ __forceinline__ void operator()(const f32x4 (&acc)[2][2][4][2], const Unit& u, int wr, int wc, int fr, int fq, const Pre& pre) const {
;     ...
;             for (int m = 0; m < 4; ++m) { const int row = row0 + ai * HALF + m * 16; const float r = rs8[ai * 4 + m];
;                 const f32x4 g0 = silu4(acc[ai][0][m][0] * r), g1 = silu4(acc[ai][0][m][1] * r);
;                 const f32x4 v0 = g0 * (acc[ai][1][m][0] * r), v1 = g1 * (acc[ai][1][m][1] * r);
;                 *(u32x4*)(O + (size_t)row * 2816 + col0) = pack8(v0, v1); }
	v_lshl_add_u64 v[100:101], v[100:101], 0, v[114:115]
	global_store_dwordx4 v[100:101], v[96:99], off nt
	v_pk_mul_f32 v[90:91], v[90:91], v[160:161] op_sel_hi:[1,0]
	v_pk_mul_f32 v[88:89], v[88:89], v[160:161] op_sel_hi:[1,0]
	v_mul_f32_e32 v96, 0xbfb8aa3b, v92
	v_mul_f32_e32 v97, 0xbfb8aa3b, v93
	v_mul_f32_e32 v98, 0xbfb8aa3b, v94
	v_mul_f32_e32 v99, 0xbfb8aa3b, v95
	v_exp_f32_e32 v96, v96
	v_exp_f32_e32 v97, v97
	v_exp_f32_e32 v98, v98
	v_exp_f32_e32 v99, v99
	v_add_f32_e32 v96, 1.0, v96
	v_add_f32_e32 v97, 1.0, v97
	v_add_f32_e32 v98, 1.0, v98
	v_add_f32_e32 v99, 1.0, v99
	v_rcp_f32_e32 v96, v96
	v_rcp_f32_e32 v97, v97
	v_rcp_f32_e32 v98, v98
	v_rcp_f32_e32 v99, v99
	ds_bpermute_b32 v158, v147, v146 offset:64
	v_pk_mul_f32 v[92:93], v[92:93], v[96:97]
	v_mul_f32_e32 v96, 0xbfb8aa3b, v88
	v_pk_mul_f32 v[94:95], v[94:95], v[98:99]
	v_mul_f32_e32 v97, 0xbfb8aa3b, v89
	v_mul_f32_e32 v98, 0xbfb8aa3b, v90
	v_mul_f32_e32 v99, 0xbfb8aa3b, v91
	v_exp_f32_e32 v96, v96
	v_exp_f32_e32 v97, v97
	v_exp_f32_e32 v98, v98
	v_exp_f32_e32 v99, v99
	v_add_f32_e32 v96, 1.0, v96
	v_add_f32_e32 v97, 1.0, v97
	v_add_f32_e32 v98, 1.0, v98
	v_add_f32_e32 v99, 1.0, v99
	v_rcp_f32_e32 v96, v96
	v_rcp_f32_e32 v97, v97
	v_rcp_f32_e32 v98, v98
	v_rcp_f32_e32 v99, v99
	v_pk_mul_f32 v[84:85], v[84:85], v[160:161] op_sel_hi:[1,0]
	v_or_b32_e32 v100, 32, v142
	v_pk_mul_f32 v[88:89], v[88:89], v[96:97]
	v_pk_mul_f32 v[90:91], v[90:91], v[98:99]
	v_pk_mul_f32 v[84:85], v[84:85], v[92:93]
	v_pk_mul_f32 v[80:81], v[80:81], v[160:161] op_sel_hi:[1,0]
	v_pk_mul_f32 v[82:83], v[82:83], v[160:161] op_sel_hi:[1,0]
	v_pk_mul_f32 v[86:87], v[86:87], v[160:161] op_sel_hi:[1,0]
	v_pk_mul_f32 v[90:91], v[82:83], v[90:91]
	v_pk_mul_f32 v[82:83], v[80:81], v[88:89]
	v_cvt_pk_bf16_f32 v80, v84, v85
	v_mad_i64_i32 v[84:85], s[20:21], v100, s4, v[112:113]
	v_pk_mul_f32 v[86:87], v[86:87], v[94:95]
	v_lshl_add_u64 v[84:85], v[84:85], 0, v[114:115]
	v_cvt_pk_bf16_f32 v81, v86, v87
	v_cvt_pk_bf16_f32 v82, v82, v83
	v_cvt_pk_bf16_f32 v83, v90, v91
	s_waitcnt lgkmcnt(0)
	v_pk_mul_f32 v[78:79], v[78:79], v[158:159] op_sel_hi:[1,0]
	v_pk_mul_f32 v[76:77], v[76:77], v[158:159] op_sel_hi:[1,0]
	global_store_dwordx4 v[84:85], v[80:83], off nt
	v_pk_mul_f32 v[74:75], v[74:75], v[158:159] op_sel_hi:[1,0]
	v_pk_mul_f32 v[72:73], v[72:73], v[158:159] op_sel_hi:[1,0]
	v_mul_f32_e32 v80, 0xbfb8aa3b, v76
	v_mul_f32_e32 v81, 0xbfb8aa3b, v77
	v_mul_f32_e32 v82, 0xbfb8aa3b, v78
	v_mul_f32_e32 v83, 0xbfb8aa3b, v79
	v_exp_f32_e32 v80, v80
	v_exp_f32_e32 v81, v81
	v_exp_f32_e32 v82, v82
	v_exp_f32_e32 v83, v83
	v_add_f32_e32 v80, 1.0, v80
	v_add_f32_e32 v81, 1.0, v81
	v_add_f32_e32 v82, 1.0, v82
	v_add_f32_e32 v83, 1.0, v83
	v_rcp_f32_e32 v80, v80
	v_rcp_f32_e32 v81, v81
	v_rcp_f32_e32 v82, v82
	v_rcp_f32_e32 v83, v83
	v_pk_mul_f32 v[68:69], v[68:69], v[158:159] op_sel_hi:[1,0]
	v_pk_mul_f32 v[76:77], v[76:77], v[80:81]
	v_mul_f32_e32 v80, 0xbfb8aa3b, v72
	v_pk_mul_f32 v[78:79], v[78:79], v[82:83]
	v_mul_f32_e32 v81, 0xbfb8aa3b, v73
	v_mul_f32_e32 v82, 0xbfb8aa3b, v74
	v_mul_f32_e32 v83, 0xbfb8aa3b, v75
	v_exp_f32_e32 v80, v80
	v_exp_f32_e32 v81, v81
	v_exp_f32_e32 v82, v82
	v_exp_f32_e32 v83, v83
	v_add_f32_e32 v80, 1.0, v80
	v_add_f32_e32 v81, 1.0, v81
	v_add_f32_e32 v82, 1.0, v82
	v_add_f32_e32 v83, 1.0, v83
	v_rcp_f32_e32 v80, v80
	v_rcp_f32_e32 v81, v81
	v_rcp_f32_e32 v82, v82
	v_rcp_f32_e32 v83, v83
	v_or_b32_e32 v84, 48, v142
	v_pk_mul_f32 v[72:73], v[72:73], v[80:81]
	v_pk_mul_f32 v[68:69], v[68:69], v[76:77]
	v_pk_mul_f32 v[74:75], v[74:75], v[82:83]
	v_pk_mul_f32 v[64:65], v[64:65], v[158:159] op_sel_hi:[1,0]
	v_pk_mul_f32 v[66:67], v[66:67], v[158:159] op_sel_hi:[1,0]
	v_pk_mul_f32 v[70:71], v[70:71], v[158:159] op_sel_hi:[1,0]
	v_pk_mul_f32 v[74:75], v[66:67], v[74:75]
	v_pk_mul_f32 v[66:67], v[64:65], v[72:73]
	v_cvt_pk_bf16_f32 v64, v68, v69
	v_mad_i64_i32 v[68:69], s[20:21], v84, s4, v[112:113]
	v_pk_mul_f32 v[70:71], v[70:71], v[78:79]
	v_lshl_add_u64 v[68:69], v[68:69], 0, v[114:115]
	v_cvt_pk_bf16_f32 v65, v70, v71
	v_cvt_pk_bf16_f32 v66, v66, v67
	v_cvt_pk_bf16_f32 v67, v74, v75
	v_pk_mul_f32 v[62:63], v[62:63], v[156:157] op_sel_hi:[1,0]
	v_pk_mul_f32 v[60:61], v[60:61], v[156:157] op_sel_hi:[1,0]
	global_store_dwordx4 v[68:69], v[64:67], off nt
	v_pk_mul_f32 v[58:59], v[58:59], v[156:157] op_sel_hi:[1,0]
	v_pk_mul_f32 v[56:57], v[56:57], v[156:157] op_sel_hi:[1,0]
	v_mul_f32_e32 v64, 0xbfb8aa3b, v60
	v_mul_f32_e32 v65, 0xbfb8aa3b, v61
	v_mul_f32_e32 v66, 0xbfb8aa3b, v62
	v_mul_f32_e32 v67, 0xbfb8aa3b, v63
	v_exp_f32_e32 v64, v64
	v_exp_f32_e32 v65, v65
	v_exp_f32_e32 v66, v66
	v_exp_f32_e32 v67, v67
	v_add_f32_e32 v64, 1.0, v64
	v_add_f32_e32 v65, 1.0, v65
	v_add_f32_e32 v66, 1.0, v66
	v_add_f32_e32 v67, 1.0, v67
	v_rcp_f32_e32 v64, v64
	v_rcp_f32_e32 v65, v65
	v_rcp_f32_e32 v66, v66
	v_rcp_f32_e32 v67, v67
	ds_bpermute_b32 v154, v147, v146 offset:128
	v_pk_mul_f32 v[60:61], v[60:61], v[64:65]
	v_mul_f32_e32 v64, 0xbfb8aa3b, v56
	v_pk_mul_f32 v[62:63], v[62:63], v[66:67]
	v_mul_f32_e32 v65, 0xbfb8aa3b, v57
	v_mul_f32_e32 v66, 0xbfb8aa3b, v58
	v_mul_f32_e32 v67, 0xbfb8aa3b, v59
	v_exp_f32_e32 v64, v64
	v_exp_f32_e32 v65, v65
	v_exp_f32_e32 v66, v66
	v_exp_f32_e32 v67, v67
	v_add_f32_e32 v64, 1.0, v64
	v_add_f32_e32 v65, 1.0, v65
	v_add_f32_e32 v66, 1.0, v66
	v_add_f32_e32 v67, 1.0, v67
	v_rcp_f32_e32 v64, v64
	v_rcp_f32_e32 v65, v65
	v_rcp_f32_e32 v66, v66
	v_rcp_f32_e32 v67, v67
	v_pk_mul_f32 v[52:53], v[52:53], v[156:157] op_sel_hi:[1,0]
	v_add_u32_e32 v68, 0x80, v142
	v_pk_mul_f32 v[56:57], v[56:57], v[64:65]
	v_pk_mul_f32 v[58:59], v[58:59], v[66:67]
	v_pk_mul_f32 v[52:53], v[52:53], v[60:61]
	v_pk_mul_f32 v[48:49], v[48:49], v[156:157] op_sel_hi:[1,0]
	v_pk_mul_f32 v[50:51], v[50:51], v[156:157] op_sel_hi:[1,0]
	v_pk_mul_f32 v[54:55], v[54:55], v[156:157] op_sel_hi:[1,0]
	v_pk_mul_f32 v[58:59], v[50:51], v[58:59]
	v_pk_mul_f32 v[50:51], v[48:49], v[56:57]
	v_cvt_pk_bf16_f32 v48, v52, v53
	v_mad_i64_i32 v[52:53], s[20:21], v68, s4, v[112:113]
	v_pk_mul_f32 v[54:55], v[54:55], v[62:63]
	v_lshl_add_u64 v[52:53], v[52:53], 0, v[114:115]
	v_cvt_pk_bf16_f32 v49, v54, v55
	v_cvt_pk_bf16_f32 v50, v50, v51
	v_cvt_pk_bf16_f32 v51, v58, v59
	s_waitcnt lgkmcnt(0)
; __device__ __forceinline__ f32x4 silu4(f32x4 v) { return (f32x4){silu1(v[0]), silu1(v[1]), silu1(v[2]), silu1(v[3])}; }
; __device__ __forceinline__ u32x4 pack8(f32x4 v0, f32x4 v1) { u32x4 w; w.x = cvt_pk_bf16(v0[0], v0[1]); w.y = cvt_pk_bf16(v0[2], v0[3]); w.z = cvt_pk_bf16(v1[0], v1[1]); w.w = cvt_pk_bf16(v1[2], v1[3]); return w; }
;     __device__ __forceinline__ void operator()(const f32x4 (&acc)[2][2][4][2], const Unit& u, int wr, int wc, int fr, int fq, const Pre& pre) const {
;     ...
;             for (int m = 0; m < 4; ++m) { const int row = row0 + ai * HALF + m * 16; const float r = rs8[ai * 4 + m];
;                 const f32x4 g0 = silu4(acc[ai][0][m][0] * r), g1 = silu4(acc[ai][0][m][1] * r);
;                 const f32x4 v0 = g0 * (acc[ai][1][m][0] * r), v1 = g1 * (acc[ai][1][m][1] * r);
;                 *(u32x4*)(O + (size_t)row * 2816 + col0) = pack8(v0, v1); }
	v_pk_mul_f32 v[46:47], v[46:47], v[154:155] op_sel_hi:[1,0]
	v_pk_mul_f32 v[44:45], v[44:45], v[154:155] op_sel_hi:[1,0]
	global_store_dwordx4 v[52:53], v[48:51], off nt
	v_pk_mul_f32 v[42:43], v[42:43], v[154:155] op_sel_hi:[1,0]
	v_pk_mul_f32 v[40:41], v[40:41], v[154:155] op_sel_hi:[1,0]
	v_mul_f32_e32 v48, 0xbfb8aa3b, v44
	v_mul_f32_e32 v49, 0xbfb8aa3b, v45
	v_mul_f32_e32 v50, 0xbfb8aa3b, v46
	v_mul_f32_e32 v51, 0xbfb8aa3b, v47
	v_exp_f32_e32 v48, v48
	v_exp_f32_e32 v49, v49
	v_exp_f32_e32 v50, v50
	v_exp_f32_e32 v51, v51
	v_add_f32_e32 v48, 1.0, v48
	v_add_f32_e32 v49, 1.0, v49
	v_add_f32_e32 v50, 1.0, v50
	v_add_f32_e32 v51, 1.0, v51
	v_rcp_f32_e32 v48, v48
	v_rcp_f32_e32 v49, v49
	v_rcp_f32_e32 v50, v50
	v_rcp_f32_e32 v51, v51
	v_pk_mul_f32 v[36:37], v[36:37], v[154:155] op_sel_hi:[1,0]
	v_pk_mul_f32 v[44:45], v[44:45], v[48:49]
	v_mul_f32_e32 v48, 0xbfb8aa3b, v40
	v_pk_mul_f32 v[46:47], v[46:47], v[50:51]
	v_mul_f32_e32 v49, 0xbfb8aa3b, v41
	v_mul_f32_e32 v50, 0xbfb8aa3b, v42
	v_mul_f32_e32 v51, 0xbfb8aa3b, v43
	v_exp_f32_e32 v48, v48
	v_exp_f32_e32 v49, v49
	v_exp_f32_e32 v50, v50
	v_exp_f32_e32 v51, v51
	v_add_f32_e32 v48, 1.0, v48
	v_add_f32_e32 v49, 1.0, v49
	v_add_f32_e32 v50, 1.0, v50
	v_add_f32_e32 v51, 1.0, v51
	v_rcp_f32_e32 v48, v48
	v_rcp_f32_e32 v49, v49
	v_rcp_f32_e32 v50, v50
	v_rcp_f32_e32 v51, v51
	v_add_u32_e32 v52, 0x90, v142
	v_pk_mul_f32 v[40:41], v[40:41], v[48:49]
	v_pk_mul_f32 v[36:37], v[36:37], v[44:45]
	v_pk_mul_f32 v[42:43], v[42:43], v[50:51]
	v_pk_mul_f32 v[32:33], v[32:33], v[154:155] op_sel_hi:[1,0]
	v_pk_mul_f32 v[34:35], v[34:35], v[154:155] op_sel_hi:[1,0]
	v_pk_mul_f32 v[38:39], v[38:39], v[154:155] op_sel_hi:[1,0]
	v_pk_mul_f32 v[42:43], v[34:35], v[42:43]
	v_pk_mul_f32 v[34:35], v[32:33], v[40:41]
	v_cvt_pk_bf16_f32 v32, v36, v37
	v_mad_i64_i32 v[36:37], s[20:21], v52, s4, v[112:113]
	v_pk_mul_f32 v[38:39], v[38:39], v[46:47]
	v_lshl_add_u64 v[36:37], v[36:37], 0, v[114:115]
	v_cvt_pk_bf16_f32 v33, v38, v39
	v_cvt_pk_bf16_f32 v34, v34, v35
	v_cvt_pk_bf16_f32 v35, v42, v43
	v_pk_mul_f32 v[30:31], v[30:31], v[152:153] op_sel_hi:[1,0]
	v_pk_mul_f32 v[28:29], v[28:29], v[152:153] op_sel_hi:[1,0]
	global_store_dwordx4 v[36:37], v[32:35], off nt
	v_pk_mul_f32 v[26:27], v[26:27], v[152:153] op_sel_hi:[1,0]
	v_pk_mul_f32 v[24:25], v[24:25], v[152:153] op_sel_hi:[1,0]
	v_mul_f32_e32 v32, 0xbfb8aa3b, v28
	v_mul_f32_e32 v33, 0xbfb8aa3b, v29
	v_mul_f32_e32 v34, 0xbfb8aa3b, v30
	v_mul_f32_e32 v35, 0xbfb8aa3b, v31
	v_exp_f32_e32 v32, v32
	v_exp_f32_e32 v33, v33
	v_exp_f32_e32 v34, v34
	v_exp_f32_e32 v35, v35
	v_add_f32_e32 v32, 1.0, v32
	v_add_f32_e32 v33, 1.0, v33
	v_add_f32_e32 v34, 1.0, v34
	v_add_f32_e32 v35, 1.0, v35
	v_rcp_f32_e32 v32, v32
	v_rcp_f32_e32 v33, v33
	v_rcp_f32_e32 v34, v34
	v_rcp_f32_e32 v35, v35
	ds_bpermute_b32 v146, v147, v146 offset:192
	v_pk_mul_f32 v[28:29], v[28:29], v[32:33]
	v_mul_f32_e32 v32, 0xbfb8aa3b, v24
	v_pk_mul_f32 v[30:31], v[30:31], v[34:35]
	v_mul_f32_e32 v33, 0xbfb8aa3b, v25
	v_mul_f32_e32 v34, 0xbfb8aa3b, v26
	v_mul_f32_e32 v35, 0xbfb8aa3b, v27
	v_exp_f32_e32 v32, v32
	v_exp_f32_e32 v33, v33
	v_exp_f32_e32 v34, v34
	v_exp_f32_e32 v35, v35
	v_add_f32_e32 v32, 1.0, v32
	v_add_f32_e32 v33, 1.0, v33
	v_add_f32_e32 v34, 1.0, v34
	v_add_f32_e32 v35, 1.0, v35
	v_rcp_f32_e32 v32, v32
	v_rcp_f32_e32 v33, v33
	v_rcp_f32_e32 v34, v34
	v_rcp_f32_e32 v35, v35
	v_pk_mul_f32 v[20:21], v[20:21], v[152:153] op_sel_hi:[1,0]
	v_add_u32_e32 v36, 0xa0, v142
	v_pk_mul_f32 v[24:25], v[24:25], v[32:33]
	v_pk_mul_f32 v[26:27], v[26:27], v[34:35]
	v_pk_mul_f32 v[20:21], v[20:21], v[28:29]
	v_pk_mul_f32 v[16:17], v[16:17], v[152:153] op_sel_hi:[1,0]
	v_pk_mul_f32 v[18:19], v[18:19], v[152:153] op_sel_hi:[1,0]
	v_pk_mul_f32 v[22:23], v[22:23], v[152:153] op_sel_hi:[1,0]
	v_pk_mul_f32 v[26:27], v[18:19], v[26:27]
	v_pk_mul_f32 v[18:19], v[16:17], v[24:25]
	v_cvt_pk_bf16_f32 v16, v20, v21
	v_mad_i64_i32 v[20:21], s[20:21], v36, s4, v[112:113]
	v_pk_mul_f32 v[22:23], v[22:23], v[30:31]
	v_lshl_add_u64 v[20:21], v[20:21], 0, v[114:115]
	v_cvt_pk_bf16_f32 v17, v22, v23
	v_cvt_pk_bf16_f32 v18, v18, v19
	v_cvt_pk_bf16_f32 v19, v26, v27
	s_waitcnt lgkmcnt(0)
	v_pk_mul_f32 v[14:15], v[14:15], v[146:147] op_sel_hi:[1,0]
	v_pk_mul_f32 v[12:13], v[12:13], v[146:147] op_sel_hi:[1,0]
	global_store_dwordx4 v[20:21], v[16:19], off nt
	v_pk_mul_f32 v[10:11], v[10:11], v[146:147] op_sel_hi:[1,0]
	v_pk_mul_f32 v[8:9], v[8:9], v[146:147] op_sel_hi:[1,0]
	v_mul_f32_e32 v16, 0xbfb8aa3b, v12
	v_mul_f32_e32 v17, 0xbfb8aa3b, v13
	v_mul_f32_e32 v18, 0xbfb8aa3b, v14
	v_mul_f32_e32 v19, 0xbfb8aa3b, v15
	v_exp_f32_e32 v16, v16
	v_exp_f32_e32 v17, v17
	v_exp_f32_e32 v18, v18
	v_exp_f32_e32 v19, v19
	v_add_f32_e32 v16, 1.0, v16
	v_add_f32_e32 v17, 1.0, v17
	v_add_f32_e32 v18, 1.0, v18
	v_add_f32_e32 v19, 1.0, v19
	v_rcp_f32_e32 v16, v16
	v_rcp_f32_e32 v17, v17
	v_rcp_f32_e32 v18, v18
	v_rcp_f32_e32 v19, v19
	v_pk_mul_f32 v[4:5], v[4:5], v[146:147] op_sel_hi:[1,0]
	v_pk_mul_f32 v[12:13], v[12:13], v[16:17]
	v_mul_f32_e32 v16, 0xbfb8aa3b, v8
	v_pk_mul_f32 v[14:15], v[14:15], v[18:19]
	v_mul_f32_e32 v17, 0xbfb8aa3b, v9
	v_mul_f32_e32 v18, 0xbfb8aa3b, v10
	v_mul_f32_e32 v19, 0xbfb8aa3b, v11
	v_exp_f32_e32 v16, v16
	v_exp_f32_e32 v17, v17
	v_exp_f32_e32 v18, v18
	v_exp_f32_e32 v19, v19
	v_add_f32_e32 v16, 1.0, v16
	v_add_f32_e32 v17, 1.0, v17
	v_add_f32_e32 v18, 1.0, v18
	v_add_f32_e32 v19, 1.0, v19
	v_rcp_f32_e32 v16, v16
	v_rcp_f32_e32 v17, v17
	v_rcp_f32_e32 v18, v18
	v_rcp_f32_e32 v19, v19
	v_add_u32_e32 v20, 0xb0, v142
	v_pk_mul_f32 v[8:9], v[8:9], v[16:17]
	v_pk_mul_f32 v[4:5], v[4:5], v[12:13]
	v_pk_mul_f32 v[10:11], v[10:11], v[18:19]
	v_pk_mul_f32 v[0:1], v[0:1], v[146:147] op_sel_hi:[1,0]
	v_pk_mul_f32 v[2:3], v[2:3], v[146:147] op_sel_hi:[1,0]
	v_pk_mul_f32 v[6:7], v[6:7], v[146:147] op_sel_hi:[1,0]
	v_pk_mul_f32 v[10:11], v[2:3], v[10:11]
	v_pk_mul_f32 v[2:3], v[0:1], v[8:9]
	v_cvt_pk_bf16_f32 v0, v4, v5
	v_mad_i64_i32 v[4:5], s[20:21], v20, s4, v[112:113]
	v_lshl_add_u64 v[4:5], v[4:5], 0, v[114:115]
	s_mov_b64 s[26:27], -1
	s_andn2_b64 vcc, exec, s[40:41]
	v_pk_mul_f32 v[6:7], v[6:7], v[14:15]
	s_nop 0
	v_cvt_pk_bf16_f32 v1, v6, v7
	v_cvt_pk_bf16_f32 v2, v2, v3
	v_cvt_pk_bf16_f32 v3, v10, v11
	global_store_dwordx4 v[4:5], v[0:3], off nt
	s_cbranch_vccnz .LBB0_148
	s_andn2_b64 vcc, exec, s[44:45]
	s_cbranch_vccnz .LBB0_147
	s_barrier
	s_branch .LBB0_147

; __device__ __forceinline__ unsigned long long f2ss(float v) { return (unsigned long long)(v * 16777216.0f); }
; __device__ __forceinline__ u32x4 pack8(f32x4 v0, f32x4 v1) { u32x4 w; w.x = cvt_pk_bf16(v0[0], v0[1]); w.y = cvt_pk_bf16(v0[2], v0[3]); w.z = cvt_pk_bf16(v1[0], v1[1]); w.w = cvt_pk_bf16(v1[2], v1[3]); return w; }
;     __device__ __forceinline__ void operator()(const f32x4 (&acc)[2][2][4][2], const Unit& u, int wr, int wc, int fr, int fq, const Pre&) const {
;         const int row0 = u.pm * BM + wr * 64 + fr, col0 = u.pn * BM + wc * 32 + 8 * fq;
;         typedef __attribute__((address_space(1))) u32x4 gu32x4;
;         u32x4 bwv[2][4][2];
; #pragma unroll
;         for (int ai = 0; ai < 2; ++ai)
; #pragma unroll
;             for (int m = 0; m < 4; ++m)
; #pragma unroll
;                 for (int bj = 0; bj < 2; ++bj) bwv[ai][m][bj] = *(const gu32x4*)(hb + (size_t)(row0 + ai * HALF + m * 16) * 1024 + col0 + bj * HALF);
; #pragma unroll
;         for (int ai = 0; ai < 2; ++ai)
; #pragma unroll
;             for (int m = 0; m < 4; ++m) { const int row = row0 + ai * HALF + m * 16; const size_t off = (size_t)row * 1024 + col0; float sq = 0.f;
; #pragma unroll
;                 for (int bj = 0; bj < 2; ++bj) { const u32x4 bw = bwv[ai][m][bj];
;                     const f32x4 b0 = (f32x4){__uint_as_float(bw.x << 16), __uint_as_float(bw.x & 0xffff0000u), __uint_as_float(bw.y << 16), __uint_as_float(bw.y & 0xffff0000u)};
;                     const f32x4 b1 = (f32x4){__uint_as_float(bw.z << 16), __uint_as_float(bw.z & 0xffff0000u), __uint_as_float(bw.w << 16), __uint_as_float(bw.w & 0xffff0000u)};
;                     const f32x4 v0 = acc[ai][bj][m][0] + b0, v1 = acc[ai][bj][m][1] + b1;
;                     *(gu32x4*)(hb + off + bj * HALF) = pack8(v0, v1);
;                     sq += (v0[0] * v0[0] + v0[1] * v0[1]) + (v0[2] * v0[2] + v0[3] * v0[3]) + (v1[0] * v1[0] + v1[1] * v1[1]) + (v1[2] * v1[2] + v1[3] * v1[3]); }
;                 sq += __shfl_xor(sq, 16); sq += __shfl_xor(sq, 32); if (fq == 0) atomicAdd(ssn + row, f2ss(sq)); }
.LBB0_177:
	v_lshl_or_b32 v210, s36, 8, v241
	v_lshl_add_u32 v226, s4, 8, v145
	v_ashrrev_i32_e32 v211, 31, v210
	v_lshlrev_b64 v[228:229], 1, v[210:211]
	v_ashrrev_i32_e32 v227, 31, v226
	v_lshl_add_u64 v[112:113], s[28:29], 0, v[228:229]
	v_lshlrev_b64 v[230:231], 11, v[226:227]
	v_lshl_add_u64 v[114:115], v[112:113], 0, v[230:231]
	global_load_dwordx4 v[244:247], v[114:115], off
	global_load_dwordx4 v[192:195], v[114:115], off offset:256
	v_or_b32_e32 v114, 16, v226
	v_ashrrev_i32_e32 v115, 31, v114
	v_lshlrev_b64 v[224:225], 11, v[114:115]
	v_lshl_add_u64 v[114:115], v[112:113], 0, v[224:225]
	global_load_dwordx4 v[188:191], v[114:115], off
	global_load_dwordx4 v[184:187], v[114:115], off offset:256
	v_or_b32_e32 v114, 32, v226
	v_ashrrev_i32_e32 v115, 31, v114
	v_lshlrev_b64 v[222:223], 11, v[114:115]
	v_lshl_add_u64 v[114:115], v[112:113], 0, v[222:223]
	global_load_dwordx4 v[180:183], v[114:115], off
	global_load_dwordx4 v[176:179], v[114:115], off offset:256
	v_or_b32_e32 v114, 48, v226
	v_ashrrev_i32_e32 v115, 31, v114
	s_mov_b64 s[4:5], 0x40000
	v_lshlrev_b64 v[220:221], 11, v[114:115]
	v_lshl_add_u64 v[218:219], v[230:231], 0, s[4:5]
	s_mov_b64 s[4:5], 0x48000
	v_lshl_add_u64 v[114:115], v[112:113], 0, v[220:221]
	v_lshl_add_u64 v[216:217], v[230:231], 0, s[4:5]
	s_mov_b64 s[4:5], 0x50000
	global_load_dwordx4 v[172:175], v[114:115], off
	global_load_dwordx4 v[164:167], v[114:115], off offset:256
	v_lshl_add_u64 v[114:115], v[112:113], 0, v[218:219]
	v_lshl_add_u64 v[214:215], v[230:231], 0, s[4:5]
	s_mov_b64 s[4:5], 0x58000
	global_load_dwordx4 v[156:159], v[114:115], off
	global_load_dwordx4 v[152:155], v[114:115], off offset:256
	v_lshl_add_u64 v[114:115], v[112:113], 0, v[216:217]
	v_lshl_add_u64 v[212:213], v[230:231], 0, s[4:5]
	global_load_dwordx4 v[140:143], v[114:115], off
	global_load_dwordx4 v[136:139], v[114:115], off offset:256
	v_lshl_add_u64 v[114:115], v[112:113], 0, v[214:215]
	v_lshl_add_u64 v[112:113], v[112:113], 0, v[212:213]
	global_load_dwordx4 v[124:127], v[114:115], off
	global_load_dwordx4 v[116:119], v[114:115], off offset:256
	global_load_dwordx4 v[120:123], v[112:113], off
	s_nop 0
	global_load_dwordx4 v[112:115], v[112:113], off offset:256
	v_lshl_add_u64 v[230:231], s[28:29], 0, v[230:231]
	v_lshl_add_u64 v[228:229], v[230:231], 0, v[228:229]
	s_waitcnt vmcnt(0)
	v_lshlrev_b32_e32 v248, 16, v244
	v_and_b32_e32 v249, 0xffff0000, v244
	v_lshlrev_b32_e32 v244, 16, v245
	v_and_b32_e32 v245, 0xffff0000, v245
	v_lshlrev_b32_e32 v250, 16, v246
	v_and_b32_e32 v251, 0xffff0000, v246
	v_lshlrev_b32_e32 v246, 16, v247
	v_and_b32_e32 v247, 0xffff0000, v247
	v_pk_add_f32 v[170:171], v[170:171], v[244:245]
	v_pk_add_f32 v[168:169], v[168:169], v[248:249]
	v_pk_add_f32 v[244:245], v[162:163], v[246:247]
	v_pk_add_f32 v[246:247], v[160:161], v[250:251]
	v_cvt_pk_bf16_f32 v160, v168, v169
	v_cvt_pk_bf16_f32 v161, v170, v171
	s_nop 0
	v_cvt_pk_bf16_f32 v162, v246, v247
	v_cvt_pk_bf16_f32 v163, v244, v245
	global_store_dwordx4 v[228:229], v[160:163], off
	s_nop 1
	v_mul_f32_e32 v160, v169, v169
	v_mul_f32_e32 v161, v171, v171
	v_fmac_f32_e32 v160, v168, v168
	v_fmac_f32_e32 v161, v170, v170
	v_add_f32_e32 v160, v160, v161
	v_mul_f32_e32 v161, v247, v247
	v_fmac_f32_e32 v161, v246, v246
	v_add_f32_e32 v160, v161, v160
	v_mul_f32_e32 v161, v245, v245
	v_fmac_f32_e32 v161, v244, v244
	v_add_f32_e32 v196, v161, v160
	v_lshlrev_b32_e32 v160, 16, v192
	v_and_b32_e32 v161, 0xffff0000, v192
	v_lshlrev_b32_e32 v162, 16, v193
	v_and_b32_e32 v163, 0xffff0000, v193
	v_lshlrev_b32_e32 v168, 16, v194
	v_and_b32_e32 v169, 0xffff0000, v194
	v_lshlrev_b32_e32 v170, 16, v195
	v_and_b32_e32 v171, 0xffff0000, v195
	v_pk_add_f32 v[134:135], v[134:135], v[162:163]
	v_pk_add_f32 v[132:133], v[132:133], v[160:161]
	v_pk_add_f32 v[162:163], v[128:129], v[168:169]
	v_cvt_pk_bf16_f32 v128, v132, v133
	v_cvt_pk_bf16_f32 v129, v134, v135
	v_pk_add_f32 v[160:161], v[130:131], v[170:171]
	v_cvt_pk_bf16_f32 v130, v162, v163
	s_nop 0
	v_cvt_pk_bf16_f32 v131, v160, v161
	global_store_dwordx4 v[228:229], v[128:131], off offset:256
	s_nop 1
	v_mul_f32_e32 v128, v133, v133
	v_mul_f32_e32 v129, v135, v135
	v_fmac_f32_e32 v128, v132, v132
	v_fmac_f32_e32 v129, v134, v134
	v_add_f32_e32 v128, v128, v129
	v_mul_f32_e32 v129, v163, v163
	v_fmac_f32_e32 v129, v162, v162
	v_add_f32_e32 v128, v129, v128
	v_mul_f32_e32 v129, v161, v161
	v_fmac_f32_e32 v129, v160, v160
	v_and_b32_e32 v130, 64, v236
	v_add_f32_e32 v128, v129, v128
	v_xor_b32_e32 v129, 16, v236
	v_add_u32_e32 v131, 64, v130
	v_cmp_lt_i32_e32 vcc, v129, v131
	v_add_f32_e32 v128, v196, v128
	s_nop 0
	v_cndmask_b32_e32 v129, v236, v129, vcc
	v_lshlrev_b32_e32 v130, 2, v129
	ds_bpermute_b32 v129, v130, v128
	s_waitcnt lgkmcnt(0)
	v_add_f32_e32 v132, v128, v129
	v_xor_b32_e32 v128, 32, v236
	v_cmp_lt_i32_e32 vcc, v128, v131
	s_nop 1
	v_cndmask_b32_e32 v128, v236, v128, vcc
	v_lshlrev_b32_e32 v131, 2, v128
	ds_bpermute_b32 v133, v131, v132
	v_lshl_add_u64 v[128:129], v[226:227], 3, s[48:49]
	s_and_saveexec_b64 s[26:27], s[40:41]
	s_cbranch_execz .LBB0_179
	s_waitcnt lgkmcnt(0)
	v_add_f32_e32 v132, v132, v133
	v_mul_f32_e32 v132, 0x4b800000, v132
	v_trunc_f32_e32 v132, v132
	v_mul_f32_e32 v133, 0x2f800000, v132
	v_floor_f32_e32 v133, v133
	v_fmac_f32_e32 v132, 0xcf800000, v133
	v_cvt_u32_f32_e32 v132, v132
	v_cvt_u32_f32_e32 v133, v133
	global_atomic_add_x2 v[128:129], v[132:133], off
; __device__ __forceinline__ unsigned long long f2ss(float v) { return (unsigned long long)(v * 16777216.0f); }
; __device__ __forceinline__ u32x4 pack8(f32x4 v0, f32x4 v1) { u32x4 w; w.x = cvt_pk_bf16(v0[0], v0[1]); w.y = cvt_pk_bf16(v0[2], v0[3]); w.z = cvt_pk_bf16(v1[0], v1[1]); w.w = cvt_pk_bf16(v1[2], v1[3]); return w; }
;     __device__ __forceinline__ void operator()(const f32x4 (&acc)[2][2][4][2], const Unit& u, int wr, int wc, int fr, int fq, const Pre&) const {
;     ...
;             for (int m = 0; m < 4; ++m) { const int row = row0 + ai * HALF + m * 16; const size_t off = (size_t)row * 1024 + col0; float sq = 0.f;
; #pragma unroll
;                 for (int bj = 0; bj < 2; ++bj) { const u32x4 bw = bwv[ai][m][bj];
;                     const f32x4 b0 = (f32x4){__uint_as_float(bw.x << 16), __uint_as_float(bw.x & 0xffff0000u), __uint_as_float(bw.y << 16), __uint_as_float(bw.y & 0xffff0000u)};
;                     const f32x4 b1 = (f32x4){__uint_as_float(bw.z << 16), __uint_as_float(bw.z & 0xffff0000u), __uint_as_float(bw.w << 16), __uint_as_float(bw.w & 0xffff0000u)};
;                     const f32x4 v0 = acc[ai][bj][m][0] + b0, v1 = acc[ai][bj][m][1] + b1;
;                     *(gu32x4*)(hb + off + bj * HALF) = pack8(v0, v1);
;                     sq += (v0[0] * v0[0] + v0[1] * v0[1]) + (v0[2] * v0[2] + v0[3] * v0[3]) + (v1[0] * v1[0] + v1[1] * v1[1]) + (v1[2] * v1[2] + v1[3] * v1[3]); }
;                 sq += __shfl_xor(sq, 16); sq += __shfl_xor(sq, 32); if (fq == 0) atomicAdd(ssn + row, f2ss(sq)); }
.LBB0_179:
	s_or_b64 exec, exec, s[26:27]
	v_lshlrev_b32_e32 v132, 16, v188
	s_waitcnt lgkmcnt(0)
	v_and_b32_e32 v133, 0xffff0000, v188
	v_lshlrev_b32_e32 v134, 16, v189
	v_and_b32_e32 v135, 0xffff0000, v189
	v_lshlrev_b32_e32 v160, 16, v190
	v_and_b32_e32 v161, 0xffff0000, v190
	v_pk_add_f32 v[108:109], v[108:109], v[132:133]
	v_pk_add_f32 v[110:111], v[110:111], v[134:135]
	v_pk_add_f32 v[134:135], v[104:105], v[160:161]
	v_cvt_pk_bf16_f32 v104, v108, v109
	v_mul_f32_e32 v109, v109, v109
	v_fmac_f32_e32 v109, v108, v108
	v_mul_f32_e32 v108, v111, v111
	v_fmac_f32_e32 v108, v110, v110
	v_lshlrev_b32_e32 v162, 16, v191
	v_and_b32_e32 v163, 0xffff0000, v191
	v_add_f32_e32 v108, v109, v108
	v_mul_f32_e32 v109, v135, v135
	v_pk_add_f32 v[132:133], v[106:107], v[162:163]
	v_fmac_f32_e32 v109, v134, v134
	v_add_f32_e32 v108, v109, v108
	v_mul_f32_e32 v109, v133, v133
	v_fmac_f32_e32 v109, v132, v132
	v_cvt_pk_bf16_f32 v105, v110, v111
	v_add_f32_e32 v160, v109, v108
	v_lshlrev_b32_e32 v108, 16, v184
	v_and_b32_e32 v109, 0xffff0000, v184
	v_lshlrev_b32_e32 v110, 16, v185
	v_and_b32_e32 v111, 0xffff0000, v185
	v_cvt_pk_bf16_f32 v106, v134, v135
	v_cvt_pk_bf16_f32 v107, v132, v133
	v_lshlrev_b32_e32 v132, 16, v186
	v_and_b32_e32 v133, 0xffff0000, v186
	v_pk_add_f32 v[102:103], v[102:103], v[110:111]
	v_pk_add_f32 v[100:101], v[100:101], v[108:109]
	v_pk_add_f32 v[110:111], v[96:97], v[132:133]
	v_mul_f32_e32 v96, v101, v101
	v_mul_f32_e32 v97, v103, v103
	v_fmac_f32_e32 v96, v100, v100
	v_fmac_f32_e32 v97, v102, v102
	v_lshlrev_b32_e32 v134, 16, v187
	v_and_b32_e32 v135, 0xffff0000, v187
	v_add_f32_e32 v96, v96, v97
	v_mul_f32_e32 v97, v111, v111
	v_pk_add_f32 v[108:109], v[98:99], v[134:135]
	v_fmac_f32_e32 v97, v110, v110
	v_add_f32_e32 v96, v97, v96
	v_mul_f32_e32 v97, v109, v109
	v_fmac_f32_e32 v97, v108, v108
	v_add_f32_e32 v96, v97, v96
	v_add_f32_e32 v99, v160, v96
	ds_bpermute_b32 v134, v130, v99
	v_lshl_add_u64 v[96:97], s[28:29], 0, v[224:225]
	v_lshl_add_u64 v[132:133], v[210:211], 1, v[96:97]
	global_store_dwordx4 v[132:133], v[104:107], off
	v_cvt_pk_bf16_f32 v98, v100, v101
	s_waitcnt lgkmcnt(0)
	v_add_f32_e32 v96, v99, v134
	ds_bpermute_b32 v97, v131, v96
	v_cvt_pk_bf16_f32 v99, v102, v103
	v_cvt_pk_bf16_f32 v100, v110, v111
	v_cvt_pk_bf16_f32 v101, v108, v109
	global_store_dwordx4 v[132:133], v[98:101], off offset:256
	s_and_saveexec_b64 s[26:27], s[40:41]
	s_cbranch_execz .LBB0_181
	s_waitcnt lgkmcnt(0)
	v_add_f32_e32 v96, v96, v97
	v_mul_f32_e32 v96, 0x4b800000, v96
	v_trunc_f32_e32 v96, v96
	v_mul_f32_e32 v97, 0x2f800000, v96
	v_floor_f32_e32 v97, v97
	v_fmac_f32_e32 v96, 0xcf800000, v97
	v_cvt_u32_f32_e32 v96, v96
	v_cvt_u32_f32_e32 v97, v97
	global_atomic_add_x2 v[128:129], v[96:97], off offset:128

; __device__ __forceinline__ unsigned long long f2ss(float v) { return (unsigned long long)(v * 16777216.0f); }
; __device__ __forceinline__ u32x4 pack8(f32x4 v0, f32x4 v1) { u32x4 w; w.x = cvt_pk_bf16(v0[0], v0[1]); w.y = cvt_pk_bf16(v0[2], v0[3]); w.z = cvt_pk_bf16(v1[0], v1[1]); w.w = cvt_pk_bf16(v1[2], v1[3]); return w; }
;     __device__ __forceinline__ void operator()(const f32x4 (&acc)[2][2][4][2], const Unit& u, int wr, int wc, int fr, int fq, const Pre&) const {
;     ...
;             for (int m = 0; m < 4; ++m) { const int row = row0 + ai * HALF + m * 16; const size_t off = (size_t)row * 1024 + col0; float sq = 0.f;
; #pragma unroll
;                 for (int bj = 0; bj < 2; ++bj) { const u32x4 bw = bwv[ai][m][bj];
;                     const f32x4 b0 = (f32x4){__uint_as_float(bw.x << 16), __uint_as_float(bw.x & 0xffff0000u), __uint_as_float(bw.y << 16), __uint_as_float(bw.y & 0xffff0000u)};
;                     const f32x4 b1 = (f32x4){__uint_as_float(bw.z << 16), __uint_as_float(bw.z & 0xffff0000u), __uint_as_float(bw.w << 16), __uint_as_float(bw.w & 0xffff0000u)};
;                     const f32x4 v0 = acc[ai][bj][m][0] + b0, v1 = acc[ai][bj][m][1] + b1;
;                     *(gu32x4*)(hb + off + bj * HALF) = pack8(v0, v1);
;                     sq += (v0[0] * v0[0] + v0[1] * v0[1]) + (v0[2] * v0[2] + v0[3] * v0[3]) + (v1[0] * v1[0] + v1[1] * v1[1]) + (v1[2] * v1[2] + v1[3] * v1[3]); }
;                 sq += __shfl_xor(sq, 16); sq += __shfl_xor(sq, 32); if (fq == 0) atomicAdd(ssn + row, f2ss(sq)); }
.LBB0_187:
	s_or_b64 exec, exec, s[26:27]
	v_lshlrev_b32_e32 v48, 16, v140
	s_waitcnt lgkmcnt(0)
	v_and_b32_e32 v49, 0xffff0000, v140
	v_lshlrev_b32_e32 v50, 16, v141
	v_and_b32_e32 v51, 0xffff0000, v141
	v_lshlrev_b32_e32 v52, 16, v142
	v_and_b32_e32 v53, 0xffff0000, v142
	v_pk_add_f32 v[44:45], v[44:45], v[48:49]
	v_pk_add_f32 v[46:47], v[46:47], v[50:51]
	v_pk_add_f32 v[50:51], v[40:41], v[52:53]
	v_cvt_pk_bf16_f32 v40, v44, v45
	v_mul_f32_e32 v45, v45, v45
	v_fmac_f32_e32 v45, v44, v44
	v_mul_f32_e32 v44, v47, v47
	v_fmac_f32_e32 v44, v46, v46
	v_lshlrev_b32_e32 v54, 16, v143
	v_and_b32_e32 v55, 0xffff0000, v143
	v_add_f32_e32 v44, v45, v44
	v_mul_f32_e32 v45, v51, v51
	v_pk_add_f32 v[48:49], v[42:43], v[54:55]
	v_fmac_f32_e32 v45, v50, v50
	v_add_f32_e32 v44, v45, v44
	v_mul_f32_e32 v45, v49, v49
	v_fmac_f32_e32 v45, v48, v48
	v_cvt_pk_bf16_f32 v41, v46, v47
	v_add_f32_e32 v52, v45, v44
	v_lshlrev_b32_e32 v44, 16, v136
	v_and_b32_e32 v45, 0xffff0000, v136
	v_lshlrev_b32_e32 v46, 16, v137
	v_and_b32_e32 v47, 0xffff0000, v137
	v_cvt_pk_bf16_f32 v42, v50, v51
	v_cvt_pk_bf16_f32 v43, v48, v49
	v_lshlrev_b32_e32 v48, 16, v138
	v_and_b32_e32 v49, 0xffff0000, v138
	v_pk_add_f32 v[38:39], v[38:39], v[46:47]
	v_pk_add_f32 v[36:37], v[36:37], v[44:45]
	v_pk_add_f32 v[46:47], v[32:33], v[48:49]
	v_mul_f32_e32 v32, v37, v37
	v_mul_f32_e32 v33, v39, v39
	v_fmac_f32_e32 v32, v36, v36
	v_fmac_f32_e32 v33, v38, v38
	v_lshlrev_b32_e32 v50, 16, v139
	v_and_b32_e32 v51, 0xffff0000, v139
	v_add_f32_e32 v32, v32, v33
	v_mul_f32_e32 v33, v47, v47
	v_pk_add_f32 v[44:45], v[34:35], v[50:51]
	v_fmac_f32_e32 v33, v46, v46
	v_add_f32_e32 v32, v33, v32
	v_mul_f32_e32 v33, v45, v45
	v_fmac_f32_e32 v33, v44, v44
	v_add_f32_e32 v32, v33, v32
	v_add_f32_e32 v35, v52, v32
	ds_bpermute_b32 v50, v130, v35
	v_lshl_add_u64 v[32:33], s[28:29], 0, v[216:217]
	v_lshl_add_u64 v[48:49], v[210:211], 1, v[32:33]
	global_store_dwordx4 v[48:49], v[40:43], off
	v_cvt_pk_bf16_f32 v34, v36, v37
	s_waitcnt lgkmcnt(0)
	v_add_f32_e32 v32, v35, v50
	ds_bpermute_b32 v33, v131, v32
	v_cvt_pk_bf16_f32 v35, v38, v39
	v_cvt_pk_bf16_f32 v36, v46, v47
	v_cvt_pk_bf16_f32 v37, v44, v45
	global_store_dwordx4 v[48:49], v[34:37], off offset:256
	s_and_saveexec_b64 s[26:27], s[40:41]
	s_cbranch_execz .LBB0_189
	s_waitcnt lgkmcnt(0)
	v_add_f32_e32 v32, v32, v33
	v_mul_f32_e32 v32, 0x4b800000, v32
	v_trunc_f32_e32 v32, v32
	v_mul_f32_e32 v33, 0x2f800000, v32
	v_floor_f32_e32 v33, v33
	v_fmac_f32_e32 v32, 0xcf800000, v33
	v_cvt_u32_f32_e32 v32, v32
	v_cvt_u32_f32_e32 v33, v33
	global_atomic_add_x2 v[128:129], v[32:33], off offset:1152

;     __device__ __forceinline__ void operator()(const f32x4 (&acc)[2][2][4][2], const Unit& u, int wr, int wc, int fr, int fq, const Pre& pre) const {
;     ...
;         if (u.pn == 2 || u.pn == 3) {
;             float mx0 = 0.f, mx1 = 0.f;
; #pragma unroll
;             for (int ai = 0; ai < 2; ++ai)
; #pragma unroll
;                 for (int m = 0; m < 4; ++m) { const float r = rs8[ai * 4 + m];
; #pragma unroll
;                     for (int bj = 0; bj < 2; ++bj) { const f32x4 a = acc[ai][bj][m][0] * r, b = acc[ai][bj][m][1] * r;
;                         float s = (a[0] * a[0] + a[1] * a[1]) + (a[2] * a[2] + a[3] * a[3]) + (b[0] * b[0] + b[1] * b[1]) + (b[2] * b[2] + b[3] * b[3]);
;                         s += __shfl_xor(s, 16); s += __shfl_xor(s, 32);
;                         if (bj == 0) mx0 = fmaxf(mx0, s); else mx1 = fmaxf(mx1, s); } }
.LBB0_419:
	s_andn2_b64 vcc, exec, s[26:27]
	s_cbranch_vccnz .LBB0_423
	s_waitcnt lgkmcnt(7)
	v_pk_mul_f32 v[166:167], v[126:127], v[164:165] op_sel_hi:[1,0]
	v_pk_mul_f32 v[168:169], v[124:125], v[164:165] op_sel_hi:[1,0]
	v_pk_mul_f32 v[170:171], v[122:123], v[164:165] op_sel_hi:[1,0]
	v_pk_mul_f32 v[172:173], v[120:121], v[164:165] op_sel_hi:[1,0]
	v_mul_f32_e32 v165, v169, v169
	v_mul_f32_e32 v167, v167, v167
	v_and_b32_e32 v143, 64, v236
	v_fmac_f32_e32 v165, v168, v168
	v_fmac_f32_e32 v167, v166, v166
	v_mul_f32_e32 v166, v173, v173
	v_xor_b32_e32 v147, 16, v236
	v_add_u32_e32 v143, 64, v143
	v_add_f32_e32 v165, v165, v167
	v_fmac_f32_e32 v166, v172, v172
	v_cmp_lt_i32_e32 vcc, v147, v143
	v_add_f32_e32 v165, v166, v165
	v_mul_f32_e32 v166, v171, v171
	v_cndmask_b32_e32 v147, v236, v147, vcc
	v_fmac_f32_e32 v166, v170, v170
	v_lshlrev_b32_e32 v163, 2, v147
	v_add_f32_e32 v165, v166, v165
	ds_bpermute_b32 v166, v163, v165
	v_xor_b32_e32 v147, 32, v236
	v_cmp_lt_i32_e32 vcc, v147, v143
	s_waitcnt lgkmcnt(0)
	v_add_f32_e32 v165, v165, v166
	v_cndmask_b32_e32 v147, v236, v147, vcc
	v_lshlrev_b32_e32 v147, 2, v147
	ds_bpermute_b32 v166, v147, v165
	s_waitcnt lgkmcnt(0)
	v_add_f32_e32 v165, v165, v166
	v_pk_mul_f32 v[166:167], v[118:119], v[164:165] op_sel_hi:[1,0]
	v_pk_mul_f32 v[168:169], v[116:117], v[164:165] op_sel_hi:[1,0]
	v_mul_f32_e32 v167, v167, v167
	v_mul_f32_e32 v169, v169, v169
	v_pk_mul_f32 v[172:173], v[112:113], v[164:165] op_sel_hi:[1,0]
	v_fmac_f32_e32 v169, v168, v168
	v_fmac_f32_e32 v167, v166, v166
	v_add_f32_e32 v166, v169, v167
	v_mul_f32_e32 v167, v173, v173
	v_pk_mul_f32 v[170:171], v[114:115], v[164:165] op_sel_hi:[1,0]
	v_fmac_f32_e32 v167, v172, v172
	v_add_f32_e32 v166, v167, v166
	v_mul_f32_e32 v167, v171, v171
	v_fmac_f32_e32 v167, v170, v170
	v_add_f32_e32 v166, v167, v166
	ds_bpermute_b32 v167, v163, v166
	v_pk_mul_f32 v[168:169], v[108:109], v[162:163] op_sel_hi:[1,0]
	v_pk_mul_f32 v[172:173], v[104:105], v[162:163] op_sel_hi:[1,0]
	v_mul_f32_e32 v169, v169, v169
	v_fmac_f32_e32 v169, v168, v168
	s_waitcnt lgkmcnt(0)
	v_add_f32_e32 v166, v166, v167
	ds_bpermute_b32 v167, v147, v166
	v_pk_mul_f32 v[170:171], v[106:107], v[162:163] op_sel_hi:[1,0]
	s_waitcnt lgkmcnt(0)
	v_add_f32_e32 v174, v166, v167
	v_pk_mul_f32 v[166:167], v[110:111], v[162:163] op_sel_hi:[1,0]
	s_nop 0
	v_mul_f32_e32 v167, v167, v167
	v_fmac_f32_e32 v167, v166, v166
	v_add_f32_e32 v166, v169, v167
	v_mul_f32_e32 v167, v173, v173
	v_fmac_f32_e32 v167, v172, v172
	v_add_f32_e32 v166, v167, v166
	v_mul_f32_e32 v167, v171, v171
	v_fmac_f32_e32 v167, v170, v170
	v_add_f32_e32 v166, v167, v166
	ds_bpermute_b32 v167, v163, v166
	v_pk_mul_f32 v[168:169], v[100:101], v[162:163] op_sel_hi:[1,0]
	v_pk_mul_f32 v[172:173], v[96:97], v[162:163] op_sel_hi:[1,0]
	v_mul_f32_e32 v169, v169, v169
	v_fmac_f32_e32 v169, v168, v168
	s_waitcnt lgkmcnt(0)
	v_add_f32_e32 v166, v166, v167
	ds_bpermute_b32 v167, v147, v166
	v_pk_mul_f32 v[170:171], v[98:99], v[162:163] op_sel_hi:[1,0]
	s_waitcnt lgkmcnt(0)
	v_add_f32_e32 v166, v166, v167
	v_max3_f32 v165, v165, 0, v166
	v_pk_mul_f32 v[166:167], v[102:103], v[162:163] op_sel_hi:[1,0]
	s_nop 0
	v_mul_f32_e32 v167, v167, v167
	v_fmac_f32_e32 v167, v166, v166
	v_add_f32_e32 v166, v169, v167
	v_mul_f32_e32 v167, v173, v173
	v_fmac_f32_e32 v167, v172, v172
	v_add_f32_e32 v166, v167, v166
	v_mul_f32_e32 v167, v171, v171
	v_fmac_f32_e32 v167, v170, v170
	v_add_f32_e32 v166, v167, v166
	ds_bpermute_b32 v167, v163, v166
	v_pk_mul_f32 v[168:169], v[92:93], v[160:161] op_sel_hi:[1,0]
	v_pk_mul_f32 v[172:173], v[88:89], v[160:161] op_sel_hi:[1,0]
	v_mul_f32_e32 v169, v169, v169
	v_fmac_f32_e32 v169, v168, v168
	s_waitcnt lgkmcnt(0)
	v_add_f32_e32 v166, v166, v167
	ds_bpermute_b32 v167, v147, v166
	v_pk_mul_f32 v[170:171], v[90:91], v[160:161] op_sel_hi:[1,0]
	s_waitcnt lgkmcnt(0)
	v_add_f32_e32 v166, v166, v167
	v_max3_f32 v174, v174, 0, v166
	v_pk_mul_f32 v[166:167], v[94:95], v[160:161] op_sel_hi:[1,0]
	s_nop 0
	v_mul_f32_e32 v167, v167, v167
	v_fmac_f32_e32 v167, v166, v166
	v_add_f32_e32 v166, v169, v167
	v_mul_f32_e32 v167, v173, v173
	v_fmac_f32_e32 v167, v172, v172
	v_add_f32_e32 v166, v167, v166
	v_mul_f32_e32 v167, v171, v171
	v_fmac_f32_e32 v167, v170, v170
	v_add_f32_e32 v166, v167, v166
	ds_bpermute_b32 v167, v163, v166
	v_pk_mul_f32 v[168:169], v[84:85], v[160:161] op_sel_hi:[1,0]
	v_pk_mul_f32 v[172:173], v[80:81], v[160:161] op_sel_hi:[1,0]
	v_mul_f32_e32 v169, v169, v169
	v_fmac_f32_e32 v169, v168, v168
	s_waitcnt lgkmcnt(0)
	v_add_f32_e32 v166, v166, v167
	ds_bpermute_b32 v167, v147, v166
	v_pk_mul_f32 v[170:171], v[82:83], v[160:161] op_sel_hi:[1,0]
	s_waitcnt lgkmcnt(0)
	v_add_f32_e32 v175, v166, v167
	v_pk_mul_f32 v[166:167], v[86:87], v[160:161] op_sel_hi:[1,0]
	s_nop 0
	v_mul_f32_e32 v167, v167, v167
	v_fmac_f32_e32 v167, v166, v166
	v_add_f32_e32 v166, v169, v167
	v_mul_f32_e32 v167, v173, v173
	v_fmac_f32_e32 v167, v172, v172
	v_add_f32_e32 v166, v167, v166
	v_mul_f32_e32 v167, v171, v171
	v_fmac_f32_e32 v167, v170, v170
	v_add_f32_e32 v166, v167, v166
	ds_bpermute_b32 v167, v163, v166
	v_pk_mul_f32 v[168:169], v[76:77], v[158:159] op_sel_hi:[1,0]
	v_pk_mul_f32 v[172:173], v[72:73], v[158:159] op_sel_hi:[1,0]
	v_mul_f32_e32 v169, v169, v169
	v_fmac_f32_e32 v169, v168, v168
	s_waitcnt lgkmcnt(0)
	v_add_f32_e32 v166, v166, v167
	ds_bpermute_b32 v167, v147, v166
	v_pk_mul_f32 v[170:171], v[74:75], v[158:159] op_sel_hi:[1,0]
	s_waitcnt lgkmcnt(0)
;     __device__ __forceinline__ void operator()(const f32x4 (&acc)[2][2][4][2], const Unit& u, int wr, int wc, int fr, int fq, const Pre& pre) const {
;     ...
;             for (int ai = 0; ai < 2; ++ai)
; #pragma unroll
;                 for (int m = 0; m < 4; ++m) { const float r = rs8[ai * 4 + m];
; #pragma unroll
;                     for (int bj = 0; bj < 2; ++bj) { const f32x4 a = acc[ai][bj][m][0] * r, b = acc[ai][bj][m][1] * r;
;                         float s = (a[0] * a[0] + a[1] * a[1]) + (a[2] * a[2] + a[3] * a[3]) + (b[0] * b[0] + b[1] * b[1]) + (b[2] * b[2] + b[3] * b[3]);
;                         s += __shfl_xor(s, 16); s += __shfl_xor(s, 32);
;                         if (bj == 0) mx0 = fmaxf(mx0, s); else mx1 = fmaxf(mx1, s); } }
	v_add_f32_e32 v176, v166, v167
	v_pk_mul_f32 v[166:167], v[78:79], v[158:159] op_sel_hi:[1,0]
	s_nop 0
	v_mul_f32_e32 v167, v167, v167
	v_fmac_f32_e32 v167, v166, v166
	v_add_f32_e32 v166, v169, v167
	v_mul_f32_e32 v167, v173, v173
	v_fmac_f32_e32 v167, v172, v172
	v_add_f32_e32 v166, v167, v166
	v_mul_f32_e32 v167, v171, v171
	v_fmac_f32_e32 v167, v170, v170
	v_add_f32_e32 v166, v167, v166
	ds_bpermute_b32 v167, v163, v166
	v_pk_mul_f32 v[168:169], v[68:69], v[158:159] op_sel_hi:[1,0]
	v_pk_mul_f32 v[172:173], v[64:65], v[158:159] op_sel_hi:[1,0]
	v_mul_f32_e32 v169, v169, v169
	v_fmac_f32_e32 v169, v168, v168
	s_waitcnt lgkmcnt(0)
	v_add_f32_e32 v166, v166, v167
	ds_bpermute_b32 v167, v147, v166
	v_pk_mul_f32 v[170:171], v[66:67], v[158:159] op_sel_hi:[1,0]
	s_waitcnt lgkmcnt(0)
	v_add_f32_e32 v166, v166, v167
	v_max3_f32 v165, v165, v175, v166
	v_pk_mul_f32 v[166:167], v[70:71], v[158:159] op_sel_hi:[1,0]
	s_nop 0
	v_mul_f32_e32 v167, v167, v167
	v_fmac_f32_e32 v167, v166, v166
	v_add_f32_e32 v166, v169, v167
	v_mul_f32_e32 v167, v173, v173
	v_fmac_f32_e32 v167, v172, v172
	v_add_f32_e32 v166, v167, v166
	v_mul_f32_e32 v167, v171, v171
	v_fmac_f32_e32 v167, v170, v170
	v_add_f32_e32 v166, v167, v166
	ds_bpermute_b32 v167, v163, v166
	v_pk_mul_f32 v[168:169], v[60:61], v[156:157] op_sel_hi:[1,0]
	v_pk_mul_f32 v[172:173], v[56:57], v[156:157] op_sel_hi:[1,0]
	v_mul_f32_e32 v169, v169, v169
	v_fmac_f32_e32 v169, v168, v168
	s_waitcnt lgkmcnt(0)
	v_add_f32_e32 v166, v166, v167
	ds_bpermute_b32 v167, v147, v166
	v_pk_mul_f32 v[170:171], v[58:59], v[156:157] op_sel_hi:[1,0]
	s_waitcnt lgkmcnt(0)
	v_add_f32_e32 v166, v166, v167
	v_max3_f32 v174, v174, v176, v166
	v_pk_mul_f32 v[166:167], v[62:63], v[156:157] op_sel_hi:[1,0]
	s_nop 0
	v_mul_f32_e32 v167, v167, v167
	v_fmac_f32_e32 v167, v166, v166
	v_add_f32_e32 v166, v169, v167
	v_mul_f32_e32 v167, v173, v173
	v_fmac_f32_e32 v167, v172, v172
	v_add_f32_e32 v166, v167, v166
	v_mul_f32_e32 v167, v171, v171
	v_fmac_f32_e32 v167, v170, v170
	v_add_f32_e32 v166, v167, v166
	ds_bpermute_b32 v167, v163, v166
	v_pk_mul_f32 v[168:169], v[52:53], v[156:157] op_sel_hi:[1,0]
	v_pk_mul_f32 v[172:173], v[48:49], v[156:157] op_sel_hi:[1,0]
	v_mul_f32_e32 v169, v169, v169
	v_fmac_f32_e32 v169, v168, v168
	s_waitcnt lgkmcnt(0)
	v_add_f32_e32 v166, v166, v167
	ds_bpermute_b32 v167, v147, v166
	v_pk_mul_f32 v[170:171], v[50:51], v[156:157] op_sel_hi:[1,0]
	s_waitcnt lgkmcnt(0)
	v_add_f32_e32 v175, v166, v167
	v_pk_mul_f32 v[166:167], v[54:55], v[156:157] op_sel_hi:[1,0]
	s_nop 0
	v_mul_f32_e32 v167, v167, v167
	v_fmac_f32_e32 v167, v166, v166
	v_add_f32_e32 v166, v169, v167
	v_mul_f32_e32 v167, v173, v173
	v_fmac_f32_e32 v167, v172, v172
	v_add_f32_e32 v166, v167, v166
	v_mul_f32_e32 v167, v171, v171
	v_fmac_f32_e32 v167, v170, v170
	v_add_f32_e32 v166, v167, v166
	ds_bpermute_b32 v167, v163, v166
	v_pk_mul_f32 v[168:169], v[44:45], v[154:155] op_sel_hi:[1,0]
	v_pk_mul_f32 v[172:173], v[40:41], v[154:155] op_sel_hi:[1,0]
	v_mul_f32_e32 v169, v169, v169
	v_fmac_f32_e32 v169, v168, v168
	s_waitcnt lgkmcnt(0)
	v_add_f32_e32 v166, v166, v167
	ds_bpermute_b32 v167, v147, v166
	v_pk_mul_f32 v[170:171], v[42:43], v[154:155] op_sel_hi:[1,0]
	s_waitcnt lgkmcnt(0)
	v_add_f32_e32 v176, v166, v167
	v_pk_mul_f32 v[166:167], v[46:47], v[154:155] op_sel_hi:[1,0]
	s_nop 0
	v_mul_f32_e32 v167, v167, v167
	v_fmac_f32_e32 v167, v166, v166
	v_add_f32_e32 v166, v169, v167
	v_mul_f32_e32 v167, v173, v173
	v_fmac_f32_e32 v167, v172, v172
	v_add_f32_e32 v166, v167, v166
	v_mul_f32_e32 v167, v171, v171
	v_fmac_f32_e32 v167, v170, v170
	v_add_f32_e32 v166, v167, v166
	ds_bpermute_b32 v167, v163, v166
	v_pk_mul_f32 v[168:169], v[36:37], v[154:155] op_sel_hi:[1,0]
	v_pk_mul_f32 v[172:173], v[32:33], v[154:155] op_sel_hi:[1,0]
	v_mul_f32_e32 v169, v169, v169
	v_fmac_f32_e32 v169, v168, v168
	s_waitcnt lgkmcnt(0)
	v_add_f32_e32 v166, v166, v167
	ds_bpermute_b32 v167, v147, v166
	v_pk_mul_f32 v[170:171], v[34:35], v[154:155] op_sel_hi:[1,0]
	s_waitcnt lgkmcnt(0)
	v_add_f32_e32 v166, v166, v167
	v_max3_f32 v165, v165, v175, v166
	v_pk_mul_f32 v[166:167], v[38:39], v[154:155] op_sel_hi:[1,0]
	s_nop 0
	v_mul_f32_e32 v167, v167, v167
	v_fmac_f32_e32 v167, v166, v166
	v_add_f32_e32 v166, v169, v167
	v_mul_f32_e32 v167, v173, v173
	v_fmac_f32_e32 v167, v172, v172
	v_add_f32_e32 v166, v167, v166
	v_mul_f32_e32 v167, v171, v171
	v_fmac_f32_e32 v167, v170, v170
	v_add_f32_e32 v166, v167, v166
	ds_bpermute_b32 v167, v163, v166
	v_pk_mul_f32 v[168:169], v[28:29], v[146:147] op_sel_hi:[1,0]
	v_pk_mul_f32 v[172:173], v[24:25], v[146:147] op_sel_hi:[1,0]
	v_mul_f32_e32 v169, v169, v169
	v_fmac_f32_e32 v169, v168, v168
	s_waitcnt lgkmcnt(0)
	v_add_f32_e32 v166, v166, v167
	ds_bpermute_b32 v167, v147, v166
	v_pk_mul_f32 v[170:171], v[26:27], v[146:147] op_sel_hi:[1,0]
	s_waitcnt lgkmcnt(0)
;     __device__ __forceinline__ void operator()(const f32x4 (&acc)[2][2][4][2], const Unit& u, int wr, int wc, int fr, int fq, const Pre& pre) const {
;     ...
;                     for (int bj = 0; bj < 2; ++bj) { const f32x4 a = acc[ai][bj][m][0] * r, b = acc[ai][bj][m][1] * r;
;                         float s = (a[0] * a[0] + a[1] * a[1]) + (a[2] * a[2] + a[3] * a[3]) + (b[0] * b[0] + b[1] * b[1]) + (b[2] * b[2] + b[3] * b[3]);
;                         s += __shfl_xor(s, 16); s += __shfl_xor(s, 32);
;                         if (bj == 0) mx0 = fmaxf(mx0, s); else mx1 = fmaxf(mx1, s); } }
; #pragma unroll
;             for (int o = 1; o < 16; o <<= 1) { mx0 = fmaxf(mx0, __shfl_xor(mx0, o)); mx1 = fmaxf(mx1, __shfl_xor(mx1, o)); }
;             if (fr == 0 && fq == 0) { unsigned* kp = kmx + (u.pm >> 4) * 8 + (u.pn - 2) * 4 + (wc >> 1);
;                 atomicMax(kp, __float_as_uint(mx0)); atomicMax(kp + 2, __float_as_uint(mx1)); } }
	v_add_f32_e32 v166, v166, v167
	v_max3_f32 v174, v174, v176, v166
	v_pk_mul_f32 v[166:167], v[30:31], v[146:147] op_sel_hi:[1,0]
	s_nop 0
	v_mul_f32_e32 v167, v167, v167
	v_fmac_f32_e32 v167, v166, v166
	v_add_f32_e32 v166, v169, v167
	v_mul_f32_e32 v167, v173, v173
	v_fmac_f32_e32 v167, v172, v172
	v_add_f32_e32 v166, v167, v166
	v_mul_f32_e32 v167, v171, v171
	v_fmac_f32_e32 v167, v170, v170
	v_add_f32_e32 v166, v167, v166
	ds_bpermute_b32 v167, v163, v166
	v_pk_mul_f32 v[168:169], v[20:21], v[146:147] op_sel_hi:[1,0]
	v_pk_mul_f32 v[172:173], v[16:17], v[146:147] op_sel_hi:[1,0]
	v_mul_f32_e32 v169, v169, v169
	v_fmac_f32_e32 v169, v168, v168
	s_waitcnt lgkmcnt(0)
	v_add_f32_e32 v166, v166, v167
	ds_bpermute_b32 v167, v147, v166
	v_pk_mul_f32 v[170:171], v[18:19], v[146:147] op_sel_hi:[1,0]
	s_waitcnt lgkmcnt(0)
	v_add_f32_e32 v175, v166, v167
	v_pk_mul_f32 v[166:167], v[22:23], v[146:147] op_sel_hi:[1,0]
	s_nop 0
	v_mul_f32_e32 v167, v167, v167
	v_fmac_f32_e32 v167, v166, v166
	v_add_f32_e32 v166, v169, v167
	v_mul_f32_e32 v167, v173, v173
	v_fmac_f32_e32 v167, v172, v172
	v_add_f32_e32 v166, v167, v166
	v_mul_f32_e32 v167, v171, v171
	v_fmac_f32_e32 v167, v170, v170
	v_add_f32_e32 v166, v167, v166
	ds_bpermute_b32 v167, v163, v166
	v_pk_mul_f32 v[168:169], v[12:13], v[142:143] op_sel_hi:[1,0]
	v_pk_mul_f32 v[172:173], v[8:9], v[142:143] op_sel_hi:[1,0]
	v_mul_f32_e32 v169, v169, v169
	v_fmac_f32_e32 v169, v168, v168
	s_waitcnt lgkmcnt(0)
	v_add_f32_e32 v166, v166, v167
	ds_bpermute_b32 v167, v147, v166
	v_pk_mul_f32 v[170:171], v[10:11], v[142:143] op_sel_hi:[1,0]
	s_waitcnt lgkmcnt(0)
	v_add_f32_e32 v176, v166, v167
	v_pk_mul_f32 v[166:167], v[14:15], v[142:143] op_sel_hi:[1,0]
	s_nop 0
	v_mul_f32_e32 v167, v167, v167
	v_fmac_f32_e32 v167, v166, v166
	v_add_f32_e32 v166, v169, v167
	v_mul_f32_e32 v167, v173, v173
	v_fmac_f32_e32 v167, v172, v172
	v_add_f32_e32 v166, v167, v166
	v_mul_f32_e32 v167, v171, v171
	v_fmac_f32_e32 v167, v170, v170
	v_add_f32_e32 v166, v167, v166
	ds_bpermute_b32 v167, v163, v166
	v_pk_mul_f32 v[168:169], v[4:5], v[142:143] op_sel_hi:[1,0]
	v_pk_mul_f32 v[172:173], v[0:1], v[142:143] op_sel_hi:[1,0]
	v_mul_f32_e32 v169, v169, v169
	v_fmac_f32_e32 v169, v168, v168
	s_waitcnt lgkmcnt(0)
	v_add_f32_e32 v166, v166, v167
	ds_bpermute_b32 v167, v147, v166
	v_pk_mul_f32 v[170:171], v[2:3], v[142:143] op_sel_hi:[1,0]
	s_waitcnt lgkmcnt(0)
	v_add_f32_e32 v166, v166, v167
	v_max3_f32 v165, v165, v175, v166
	v_pk_mul_f32 v[166:167], v[6:7], v[142:143] op_sel_hi:[1,0]
	s_nop 0
	v_mul_f32_e32 v167, v167, v167
	v_fmac_f32_e32 v167, v166, v166
	v_add_f32_e32 v166, v169, v167
	v_mul_f32_e32 v167, v173, v173
	v_fmac_f32_e32 v167, v172, v172
	v_add_f32_e32 v166, v167, v166
	v_mul_f32_e32 v167, v171, v171
	v_fmac_f32_e32 v167, v170, v170
	v_add_f32_e32 v166, v167, v166
	ds_bpermute_b32 v163, v163, v166
	s_waitcnt lgkmcnt(0)
	v_add_f32_e32 v163, v166, v163
	ds_bpermute_b32 v147, v147, v163
	s_waitcnt lgkmcnt(0)
	v_add_f32_e32 v147, v163, v147
	v_xor_b32_e32 v163, 1, v236
	v_cmp_lt_i32_e32 vcc, v163, v143
	v_max3_f32 v147, v174, v176, v147
	s_nop 0
	v_cndmask_b32_e32 v163, v236, v163, vcc
	v_lshlrev_b32_e32 v163, 2, v163
	ds_bpermute_b32 v166, v163, v165
	ds_bpermute_b32 v163, v163, v147
	s_waitcnt lgkmcnt(1)
	v_max_f32_e32 v166, v166, v166
	s_waitcnt lgkmcnt(0)
	v_max_f32_e32 v163, v163, v163
	v_max_f32_e32 v147, v147, v163
	v_xor_b32_e32 v163, 2, v236
	v_cmp_lt_i32_e32 vcc, v163, v143
	v_max_f32_e32 v165, v165, v166
	s_nop 0
	v_cndmask_b32_e32 v163, v236, v163, vcc
	v_lshlrev_b32_e32 v163, 2, v163
	ds_bpermute_b32 v166, v163, v165
	ds_bpermute_b32 v163, v163, v147
	s_waitcnt lgkmcnt(1)
	v_max_f32_e32 v166, v166, v166
	s_waitcnt lgkmcnt(0)
	v_max_f32_e32 v163, v163, v163
	v_max_f32_e32 v163, v147, v163
	v_xor_b32_e32 v147, 4, v236
	v_cmp_lt_i32_e32 vcc, v147, v143
	v_max_f32_e32 v165, v165, v166
	s_nop 0
	v_cndmask_b32_e32 v147, v236, v147, vcc
	v_lshlrev_b32_e32 v166, 2, v147
	ds_bpermute_b32 v147, v166, v165
	s_waitcnt lgkmcnt(0)
	v_max_f32_e32 v147, v147, v147
	v_max_f32_e32 v147, v165, v147
	ds_bpermute_b32 v165, v166, v163
	s_waitcnt lgkmcnt(0)
	v_max_f32_e32 v165, v165, v165
	v_max_f32_e32 v163, v163, v165
	v_xor_b32_e32 v165, 8, v236
	v_cmp_lt_i32_e32 vcc, v165, v143
	s_nop 1
	v_cndmask_b32_e32 v143, v236, v165, vcc
	v_lshlrev_b32_e32 v165, 2, v143
	ds_bpermute_b32 v143, v165, v147
	ds_bpermute_b32 v165, v165, v163
	s_and_saveexec_b64 s[44:45], s[40:41]
	s_cbranch_execz .LBB0_422
	s_ashr_i32 s2, s2, 1
	s_and_b32 s26, s2, -8
	s_ashr_i32 s27, s26, 31
	s_lshl_b64 s[26:27], s[26:27], 2
	s_add_u32 s4, s62, s26
	s_addc_u32 s8, s63, s27
	s_lshl_b32 s2, s68, 2
	s_lshl_b64 s[26:27], s[2:3], 2
	s_add_u32 s2, s4, s26
	s_addc_u32 s4, s8, s27
	s_waitcnt lgkmcnt(1)
	v_max_f32_e32 v143, v143, v143
	v_max_f32_e32 v147, v147, v147
	s_add_u32 s2, s2, s67
	v_max_f32_e32 v143, v147, v143
	s_addc_u32 s4, s4, 0
	v_mov_b32_e32 v147, s2
	s_add_u32 s26, s2, 0x6fffe0
	v_add_co_u32_e32 v166, vcc, 0x6ff000, v147
	v_mov_b32_e32 v147, s4
	s_waitcnt lgkmcnt(0)
	v_max_f32_e32 v165, v165, v165
	v_max_f32_e32 v163, v163, v163
	s_addc_u32 s27, s4, 0
	v_addc_co_u32_e32 v167, vcc, 0, v147, vcc
	v_max_f32_e32 v163, v163, v165
	global_atomic_umax v[166:167], v143, off offset:4064
	v_mov_b64_e32 v[166:167], s[26:27]
	global_atomic_umax v[166:167], v163, off offset:8

; __device__ __forceinline__ f32x4 silu4(f32x4 v) { return (f32x4){silu1(v[0]), silu1(v[1]), silu1(v[2]), silu1(v[3])}; }
; __device__ __forceinline__ u32x4 pack8(f32x4 v0, f32x4 v1) { u32x4 w; w.x = cvt_pk_bf16(v0[0], v0[1]); w.y = cvt_pk_bf16(v0[2], v0[3]); w.z = cvt_pk_bf16(v1[0], v1[1]); w.w = cvt_pk_bf16(v1[2], v1[3]); return w; }
;     __device__ __forceinline__ void operator()(const f32x4 (&acc)[2][2][4][2], const Unit& u, int wr, int wc, int fr, int fq, const Pre& pre) const {
;     ...
;         const bool act = (u.pn == 6) || (u.pn == 7) || (u.pn == 14) || (u.pn == 15);
;         const float sc = (u.pn < 2) ? 0.125f : 1.0f;
; #pragma unroll
;         for (int ai = 0; ai < 2; ++ai)
; #pragma unroll
;             for (int m = 0; m < 4; ++m) { const int row = row0 + ai * HALF + m * 16; const float r = rs8[ai * 4 + m] * sc;
;                 bf16_t* rowp = O + (size_t)row * 4096 + col0;
; #pragma unroll
;                 for (int bj = 0; bj < 2; ++bj) { f32x4 v0 = acc[ai][bj][m][0] * r, v1 = acc[ai][bj][m][1] * r;
;                     if (act) { v0 = silu4(v0); v1 = silu4(v1); }
;                     *(u32x4*)(rowp + bj * HALF) = pack8(v0, v1); } }
.LBB0_425:
	v_lshl_or_b32 v122, s68, 8, v159
	v_lshlrev_b64 v[120:121], 13, v[152:153]
	v_cvt_pk_bf16_f32 v166, v166, v167
	v_cvt_pk_bf16_f32 v167, v126, v127
	v_cvt_pk_bf16_f32 v168, v168, v169
	v_cvt_pk_bf16_f32 v169, v124, v125
	v_mov_b32_e32 v124, v164
	v_mov_b32_e32 v125, v164
	v_mov_b32_e32 v165, v164
	v_ashrrev_i32_e32 v123, 31, v122
	v_lshl_add_u64 v[120:121], s[30:31], 0, v[120:121]
	v_pk_mul_f32 v[118:119], v[118:119], v[124:125]
	v_pk_mul_f32 v[114:115], v[114:115], v[124:125]
	v_cndmask_b32_e64 v124, 0, 1, s[54:55]
	v_lshl_add_u64 v[120:121], v[122:123], 1, v[120:121]
	v_pk_mul_f32 v[116:117], v[116:117], v[164:165]
	v_cmp_ne_u32_e64 s[44:45], 1, v124
	s_andn2_b64 vcc, exec, s[54:55]
	v_pk_mul_f32 v[112:113], v[112:113], v[164:165]
	global_store_dwordx4 v[120:121], v[166:169], off nt
	s_cbranch_vccnz .LBB0_427
	v_mul_f32_e32 v124, 0xbfb8aa3b, v116
	v_mul_f32_e32 v125, 0xbfb8aa3b, v117
	v_mul_f32_e32 v126, 0xbfb8aa3b, v118
	v_mul_f32_e32 v127, 0xbfb8aa3b, v119
	v_exp_f32_e32 v124, v124
	v_exp_f32_e32 v125, v125
	v_exp_f32_e32 v126, v126
	v_exp_f32_e32 v127, v127
	v_add_f32_e32 v124, 1.0, v124
	v_add_f32_e32 v125, 1.0, v125
	v_add_f32_e32 v126, 1.0, v126
	v_add_f32_e32 v127, 1.0, v127
	v_rcp_f32_e32 v124, v124
	v_rcp_f32_e32 v125, v125
	v_rcp_f32_e32 v126, v126
	v_rcp_f32_e32 v127, v127
	v_pk_mul_f32 v[116:117], v[116:117], v[124:125]
	v_mul_f32_e32 v124, 0xbfb8aa3b, v112
	v_pk_mul_f32 v[118:119], v[118:119], v[126:127]
	v_mul_f32_e32 v125, 0xbfb8aa3b, v113
	v_mul_f32_e32 v126, 0xbfb8aa3b, v114
	v_mul_f32_e32 v127, 0xbfb8aa3b, v115
	v_exp_f32_e32 v124, v124
	v_exp_f32_e32 v125, v125
	v_exp_f32_e32 v126, v126
	v_exp_f32_e32 v127, v127
	v_add_f32_e32 v124, 1.0, v124
	v_add_f32_e32 v125, 1.0, v125
	v_add_f32_e32 v126, 1.0, v126
	v_add_f32_e32 v127, 1.0, v127
	v_rcp_f32_e32 v124, v124
	v_rcp_f32_e32 v125, v125
	v_rcp_f32_e32 v126, v126
	v_rcp_f32_e32 v127, v127
	v_pk_mul_f32 v[112:113], v[112:113], v[124:125]
	v_pk_mul_f32 v[114:115], v[114:115], v[126:127]
.LBB0_427:
	v_cvt_pk_bf16_f32 v116, v116, v117
	v_cvt_pk_bf16_f32 v117, v118, v119
	v_cvt_pk_bf16_f32 v118, v112, v113
	v_mul_f32_e32 v112, v143, v162
	v_cvt_pk_bf16_f32 v119, v114, v115
	v_pk_mul_f32 v[110:111], v[110:111], v[112:113] op_sel_hi:[1,0]
	v_pk_mul_f32 v[108:109], v[108:109], v[112:113] op_sel_hi:[1,0]
	v_pk_mul_f32 v[106:107], v[106:107], v[112:113] op_sel_hi:[1,0]
	s_and_b64 vcc, exec, s[44:45]
	v_pk_mul_f32 v[114:115], v[104:105], v[112:113] op_sel_hi:[1,0]
	global_store_dwordx4 v[120:121], v[116:119], off offset:256 nt
	s_cbranch_vccnz .LBB0_429
	v_mul_f32_e32 v113, 0xbfb8aa3b, v110
	v_exp_f32_e32 v113, v113
	v_mul_f32_e32 v104, 0xbfb8aa3b, v108
	v_mul_f32_e32 v105, 0xbfb8aa3b, v109
	v_exp_f32_e32 v104, v104
	v_add_f32_e32 v113, 1.0, v113
	v_rcp_f32_e32 v116, v113
	v_mul_f32_e32 v113, 0xbfb8aa3b, v111
	v_exp_f32_e32 v113, v113
	v_exp_f32_e32 v105, v105
	v_add_f32_e32 v104, 1.0, v104
	v_rcp_f32_e32 v104, v104
	v_add_f32_e32 v113, 1.0, v113
	v_rcp_f32_e32 v117, v113
	v_mul_f32_e32 v113, 0xbfb8aa3b, v106
	v_add_f32_e32 v105, 1.0, v105
	v_exp_f32_e32 v113, v113
	v_rcp_f32_e32 v105, v105
	v_pk_mul_f32 v[110:111], v[110:111], v[116:117]
	v_add_f32_e32 v113, 1.0, v113
	v_pk_mul_f32 v[108:109], v[108:109], v[104:105]
	v_mul_f32_e32 v104, 0xbfb8aa3b, v114
	v_mul_f32_e32 v105, 0xbfb8aa3b, v115
	v_rcp_f32_e32 v116, v113
	v_mul_f32_e32 v113, 0xbfb8aa3b, v107
	v_exp_f32_e32 v104, v104
	v_exp_f32_e32 v105, v105
	v_exp_f32_e32 v113, v113
	v_add_f32_e32 v104, 1.0, v104
	v_add_f32_e32 v105, 1.0, v105
	v_add_f32_e32 v113, 1.0, v113
	v_rcp_f32_e32 v104, v104
	v_rcp_f32_e32 v105, v105
	v_rcp_f32_e32 v117, v113
	v_pk_mul_f32 v[114:115], v[114:115], v[104:105]
	v_pk_mul_f32 v[106:107], v[106:107], v[116:117]
.LBB0_429:
	v_or_b32_e32 v104, 16, v152
	v_ashrrev_i32_e32 v105, 31, v104
	v_lshlrev_b64 v[104:105], 13, v[104:105]
	v_mov_b32_e32 v113, v112
	v_lshl_add_u64 v[104:105], s[30:31], 0, v[104:105]
	v_cvt_pk_bf16_f32 v108, v108, v109
	v_cvt_pk_bf16_f32 v109, v110, v111
	v_cvt_pk_bf16_f32 v110, v114, v115
	v_cvt_pk_bf16_f32 v111, v106, v107
	v_mov_b32_e32 v106, v112
	v_mov_b32_e32 v107, v112
	v_lshl_add_u64 v[104:105], v[122:123], 1, v[104:105]
	v_pk_mul_f32 v[102:103], v[102:103], v[106:107]
	v_pk_mul_f32 v[100:101], v[100:101], v[112:113]
	v_pk_mul_f32 v[98:99], v[98:99], v[106:107]
	s_and_b64 vcc, exec, s[44:45]
	v_pk_mul_f32 v[96:97], v[96:97], v[112:113]
	global_store_dwordx4 v[104:105], v[108:111], off nt
	s_cbranch_vccnz .LBB0_431
	v_mul_f32_e32 v106, 0xbfb8aa3b, v100
	v_mul_f32_e32 v107, 0xbfb8aa3b, v101
	v_mul_f32_e32 v108, 0xbfb8aa3b, v102
	v_mul_f32_e32 v109, 0xbfb8aa3b, v103
	v_exp_f32_e32 v106, v106
	v_exp_f32_e32 v107, v107
	v_exp_f32_e32 v108, v108
	v_exp_f32_e32 v109, v109
	v_add_f32_e32 v106, 1.0, v106
	v_add_f32_e32 v107, 1.0, v107
	v_add_f32_e32 v108, 1.0, v108
	v_add_f32_e32 v109, 1.0, v109
	v_rcp_f32_e32 v106, v106
	v_rcp_f32_e32 v107, v107
	v_rcp_f32_e32 v108, v108
	v_rcp_f32_e32 v109, v109
	v_pk_mul_f32 v[100:101], v[100:101], v[106:107]
	v_mul_f32_e32 v106, 0xbfb8aa3b, v96
	v_pk_mul_f32 v[102:103], v[102:103], v[108:109]
	v_mul_f32_e32 v107, 0xbfb8aa3b, v97
	v_mul_f32_e32 v108, 0xbfb8aa3b, v98
	v_mul_f32_e32 v109, 0xbfb8aa3b, v99
	v_exp_f32_e32 v106, v106
	v_exp_f32_e32 v107, v107
	v_exp_f32_e32 v108, v108
	v_exp_f32_e32 v109, v109
	v_add_f32_e32 v106, 1.0, v106
	v_add_f32_e32 v107, 1.0, v107
	v_add_f32_e32 v108, 1.0, v108
	v_add_f32_e32 v109, 1.0, v109
	v_rcp_f32_e32 v106, v106
	v_rcp_f32_e32 v107, v107
	v_rcp_f32_e32 v108, v108
	v_rcp_f32_e32 v109, v109
	v_pk_mul_f32 v[96:97], v[96:97], v[106:107]
	v_pk_mul_f32 v[98:99], v[98:99], v[108:109]
; __device__ __forceinline__ f32x4 silu4(f32x4 v) { return (f32x4){silu1(v[0]), silu1(v[1]), silu1(v[2]), silu1(v[3])}; }
; __device__ __forceinline__ u32x4 pack8(f32x4 v0, f32x4 v1) { u32x4 w; w.x = cvt_pk_bf16(v0[0], v0[1]); w.y = cvt_pk_bf16(v0[2], v0[3]); w.z = cvt_pk_bf16(v1[0], v1[1]); w.w = cvt_pk_bf16(v1[2], v1[3]); return w; }
;     __device__ __forceinline__ void operator()(const f32x4 (&acc)[2][2][4][2], const Unit& u, int wr, int wc, int fr, int fq, const Pre& pre) const {
;     ...
; #pragma unroll
;         for (int ai = 0; ai < 2; ++ai)
; #pragma unroll
;             for (int m = 0; m < 4; ++m) { const int row = row0 + ai * HALF + m * 16; const float r = rs8[ai * 4 + m] * sc;
;                 bf16_t* rowp = O + (size_t)row * 4096 + col0;
; #pragma unroll
;                 for (int bj = 0; bj < 2; ++bj) { f32x4 v0 = acc[ai][bj][m][0] * r, v1 = acc[ai][bj][m][1] * r;
;                     if (act) { v0 = silu4(v0); v1 = silu4(v1); }
;                     *(u32x4*)(rowp + bj * HALF) = pack8(v0, v1); } }
.LBB0_431:
	v_cvt_pk_bf16_f32 v100, v100, v101
	v_cvt_pk_bf16_f32 v101, v102, v103
	v_cvt_pk_bf16_f32 v102, v96, v97
	v_mul_f32_e32 v96, v143, v160
	v_cvt_pk_bf16_f32 v103, v98, v99
	v_pk_mul_f32 v[94:95], v[94:95], v[96:97] op_sel_hi:[1,0]
	v_pk_mul_f32 v[92:93], v[92:93], v[96:97] op_sel_hi:[1,0]
	v_pk_mul_f32 v[90:91], v[90:91], v[96:97] op_sel_hi:[1,0]
	s_and_b64 vcc, exec, s[44:45]
	v_pk_mul_f32 v[98:99], v[88:89], v[96:97] op_sel_hi:[1,0]
	global_store_dwordx4 v[104:105], v[100:103], off offset:256 nt
	s_cbranch_vccnz .LBB0_433
	v_mul_f32_e32 v97, 0xbfb8aa3b, v94
	v_exp_f32_e32 v97, v97
	v_mul_f32_e32 v88, 0xbfb8aa3b, v92
	v_mul_f32_e32 v89, 0xbfb8aa3b, v93
	v_exp_f32_e32 v88, v88
	v_add_f32_e32 v97, 1.0, v97
	v_rcp_f32_e32 v100, v97
	v_mul_f32_e32 v97, 0xbfb8aa3b, v95
	v_exp_f32_e32 v97, v97
	v_exp_f32_e32 v89, v89
	v_add_f32_e32 v88, 1.0, v88
	v_rcp_f32_e32 v88, v88
	v_add_f32_e32 v97, 1.0, v97
	v_rcp_f32_e32 v101, v97
	v_mul_f32_e32 v97, 0xbfb8aa3b, v90
	v_add_f32_e32 v89, 1.0, v89
	v_exp_f32_e32 v97, v97
	v_rcp_f32_e32 v89, v89
	v_pk_mul_f32 v[94:95], v[94:95], v[100:101]
	v_add_f32_e32 v97, 1.0, v97
	v_pk_mul_f32 v[92:93], v[92:93], v[88:89]
	v_mul_f32_e32 v88, 0xbfb8aa3b, v98
	v_mul_f32_e32 v89, 0xbfb8aa3b, v99
	v_rcp_f32_e32 v100, v97
	v_mul_f32_e32 v97, 0xbfb8aa3b, v91
	v_exp_f32_e32 v88, v88
	v_exp_f32_e32 v89, v89
	v_exp_f32_e32 v97, v97
	v_add_f32_e32 v88, 1.0, v88
	v_add_f32_e32 v89, 1.0, v89
	v_add_f32_e32 v97, 1.0, v97
	v_rcp_f32_e32 v88, v88
	v_rcp_f32_e32 v89, v89
	v_rcp_f32_e32 v101, v97
	v_pk_mul_f32 v[98:99], v[98:99], v[88:89]
	v_pk_mul_f32 v[90:91], v[90:91], v[100:101]
.LBB0_433:
	v_or_b32_e32 v88, 32, v152
	v_ashrrev_i32_e32 v89, 31, v88
	v_lshlrev_b64 v[88:89], 13, v[88:89]
	v_mov_b32_e32 v97, v96
	v_lshl_add_u64 v[88:89], s[30:31], 0, v[88:89]
	v_cvt_pk_bf16_f32 v92, v92, v93
	v_cvt_pk_bf16_f32 v93, v94, v95
	v_cvt_pk_bf16_f32 v94, v98, v99
	v_cvt_pk_bf16_f32 v95, v90, v91
	v_mov_b32_e32 v90, v96
	v_mov_b32_e32 v91, v96
	v_lshl_add_u64 v[88:89], v[122:123], 1, v[88:89]
	v_pk_mul_f32 v[86:87], v[86:87], v[90:91]
	v_pk_mul_f32 v[84:85], v[84:85], v[96:97]
	v_pk_mul_f32 v[82:83], v[82:83], v[90:91]
	s_and_b64 vcc, exec, s[44:45]
	v_pk_mul_f32 v[80:81], v[80:81], v[96:97]
	global_store_dwordx4 v[88:89], v[92:95], off nt
	s_cbranch_vccnz .LBB0_435
	v_mul_f32_e32 v90, 0xbfb8aa3b, v84
	v_mul_f32_e32 v91, 0xbfb8aa3b, v85
	v_mul_f32_e32 v92, 0xbfb8aa3b, v86
	v_mul_f32_e32 v93, 0xbfb8aa3b, v87
	v_exp_f32_e32 v90, v90
	v_exp_f32_e32 v91, v91
	v_exp_f32_e32 v92, v92
	v_exp_f32_e32 v93, v93
	v_add_f32_e32 v90, 1.0, v90
	v_add_f32_e32 v91, 1.0, v91
	v_add_f32_e32 v92, 1.0, v92
	v_add_f32_e32 v93, 1.0, v93
	v_rcp_f32_e32 v90, v90
	v_rcp_f32_e32 v91, v91
	v_rcp_f32_e32 v92, v92
	v_rcp_f32_e32 v93, v93
	v_pk_mul_f32 v[84:85], v[84:85], v[90:91]
	v_mul_f32_e32 v90, 0xbfb8aa3b, v80
	v_pk_mul_f32 v[86:87], v[86:87], v[92:93]
	v_mul_f32_e32 v91, 0xbfb8aa3b, v81
	v_mul_f32_e32 v92, 0xbfb8aa3b, v82
	v_mul_f32_e32 v93, 0xbfb8aa3b, v83
	v_exp_f32_e32 v90, v90
	v_exp_f32_e32 v91, v91
	v_exp_f32_e32 v92, v92
	v_exp_f32_e32 v93, v93
	v_add_f32_e32 v90, 1.0, v90
	v_add_f32_e32 v91, 1.0, v91
	v_add_f32_e32 v92, 1.0, v92
	v_add_f32_e32 v93, 1.0, v93
	v_rcp_f32_e32 v90, v90
	v_rcp_f32_e32 v91, v91
	v_rcp_f32_e32 v92, v92
	v_rcp_f32_e32 v93, v93
	v_pk_mul_f32 v[80:81], v[80:81], v[90:91]
	v_pk_mul_f32 v[82:83], v[82:83], v[92:93]
.LBB0_435:
	v_cvt_pk_bf16_f32 v84, v84, v85
	v_cvt_pk_bf16_f32 v85, v86, v87
	v_cvt_pk_bf16_f32 v86, v80, v81
	v_mul_f32_e32 v80, v143, v158
	v_cvt_pk_bf16_f32 v87, v82, v83
	v_pk_mul_f32 v[78:79], v[78:79], v[80:81] op_sel_hi:[1,0]
	v_pk_mul_f32 v[76:77], v[76:77], v[80:81] op_sel_hi:[1,0]
	v_pk_mul_f32 v[74:75], v[74:75], v[80:81] op_sel_hi:[1,0]
	s_and_b64 vcc, exec, s[44:45]
	v_pk_mul_f32 v[82:83], v[72:73], v[80:81] op_sel_hi:[1,0]
	global_store_dwordx4 v[88:89], v[84:87], off offset:256 nt
	s_cbranch_vccnz .LBB0_437
	v_mul_f32_e32 v81, 0xbfb8aa3b, v78
	v_exp_f32_e32 v81, v81
	v_mul_f32_e32 v72, 0xbfb8aa3b, v76
	v_mul_f32_e32 v73, 0xbfb8aa3b, v77
	v_exp_f32_e32 v72, v72
	v_add_f32_e32 v81, 1.0, v81
	v_rcp_f32_e32 v84, v81
	v_mul_f32_e32 v81, 0xbfb8aa3b, v79
	v_exp_f32_e32 v81, v81
	v_exp_f32_e32 v73, v73
	v_add_f32_e32 v72, 1.0, v72
	v_rcp_f32_e32 v72, v72
	v_add_f32_e32 v81, 1.0, v81
	v_rcp_f32_e32 v85, v81
	v_mul_f32_e32 v81, 0xbfb8aa3b, v74
	v_add_f32_e32 v73, 1.0, v73
	v_exp_f32_e32 v81, v81
	v_rcp_f32_e32 v73, v73
	v_pk_mul_f32 v[78:79], v[78:79], v[84:85]
	v_add_f32_e32 v81, 1.0, v81
	v_pk_mul_f32 v[76:77], v[76:77], v[72:73]
	v_mul_f32_e32 v72, 0xbfb8aa3b, v82
	v_mul_f32_e32 v73, 0xbfb8aa3b, v83
	v_rcp_f32_e32 v84, v81
	v_mul_f32_e32 v81, 0xbfb8aa3b, v75
	v_exp_f32_e32 v72, v72
	v_exp_f32_e32 v73, v73
	v_exp_f32_e32 v81, v81
	v_add_f32_e32 v72, 1.0, v72
	v_add_f32_e32 v73, 1.0, v73
	v_add_f32_e32 v81, 1.0, v81
	v_rcp_f32_e32 v72, v72
	v_rcp_f32_e32 v73, v73
	v_rcp_f32_e32 v85, v81
	v_pk_mul_f32 v[82:83], v[82:83], v[72:73]
	v_pk_mul_f32 v[74:75], v[74:75], v[84:85]
; __device__ __forceinline__ f32x4 silu4(f32x4 v) { return (f32x4){silu1(v[0]), silu1(v[1]), silu1(v[2]), silu1(v[3])}; }
; __device__ __forceinline__ u32x4 pack8(f32x4 v0, f32x4 v1) { u32x4 w; w.x = cvt_pk_bf16(v0[0], v0[1]); w.y = cvt_pk_bf16(v0[2], v0[3]); w.z = cvt_pk_bf16(v1[0], v1[1]); w.w = cvt_pk_bf16(v1[2], v1[3]); return w; }
;     __device__ __forceinline__ void operator()(const f32x4 (&acc)[2][2][4][2], const Unit& u, int wr, int wc, int fr, int fq, const Pre& pre) const {
;     ...
; #pragma unroll
;         for (int ai = 0; ai < 2; ++ai)
; #pragma unroll
;             for (int m = 0; m < 4; ++m) { const int row = row0 + ai * HALF + m * 16; const float r = rs8[ai * 4 + m] * sc;
;                 bf16_t* rowp = O + (size_t)row * 4096 + col0;
; #pragma unroll
;                 for (int bj = 0; bj < 2; ++bj) { f32x4 v0 = acc[ai][bj][m][0] * r, v1 = acc[ai][bj][m][1] * r;
;                     if (act) { v0 = silu4(v0); v1 = silu4(v1); }
;                     *(u32x4*)(rowp + bj * HALF) = pack8(v0, v1); } }
.LBB0_437:
	v_or_b32_e32 v72, 48, v152
	v_ashrrev_i32_e32 v73, 31, v72
	v_lshlrev_b64 v[72:73], 13, v[72:73]
	v_mov_b32_e32 v81, v80
	v_lshl_add_u64 v[72:73], s[30:31], 0, v[72:73]
	v_cvt_pk_bf16_f32 v76, v76, v77
	v_cvt_pk_bf16_f32 v77, v78, v79
	v_cvt_pk_bf16_f32 v78, v82, v83
	v_cvt_pk_bf16_f32 v79, v74, v75
	v_mov_b32_e32 v74, v80
	v_mov_b32_e32 v75, v80
	v_lshl_add_u64 v[72:73], v[122:123], 1, v[72:73]
	v_pk_mul_f32 v[70:71], v[70:71], v[74:75]
	v_pk_mul_f32 v[68:69], v[68:69], v[80:81]
	v_pk_mul_f32 v[66:67], v[66:67], v[74:75]
	s_and_b64 vcc, exec, s[44:45]
	v_pk_mul_f32 v[64:65], v[64:65], v[80:81]
	global_store_dwordx4 v[72:73], v[76:79], off nt
	s_cbranch_vccnz .LBB0_439
	v_mul_f32_e32 v74, 0xbfb8aa3b, v68
	v_mul_f32_e32 v75, 0xbfb8aa3b, v69
	v_mul_f32_e32 v76, 0xbfb8aa3b, v70
	v_mul_f32_e32 v77, 0xbfb8aa3b, v71
	v_exp_f32_e32 v74, v74
	v_exp_f32_e32 v75, v75
	v_exp_f32_e32 v76, v76
	v_exp_f32_e32 v77, v77
	v_add_f32_e32 v74, 1.0, v74
	v_add_f32_e32 v75, 1.0, v75
	v_add_f32_e32 v76, 1.0, v76
	v_add_f32_e32 v77, 1.0, v77
	v_rcp_f32_e32 v74, v74
	v_rcp_f32_e32 v75, v75
	v_rcp_f32_e32 v76, v76
	v_rcp_f32_e32 v77, v77
	v_pk_mul_f32 v[68:69], v[68:69], v[74:75]
	v_mul_f32_e32 v74, 0xbfb8aa3b, v64
	v_pk_mul_f32 v[70:71], v[70:71], v[76:77]
	v_mul_f32_e32 v75, 0xbfb8aa3b, v65
	v_mul_f32_e32 v76, 0xbfb8aa3b, v66
	v_mul_f32_e32 v77, 0xbfb8aa3b, v67
	v_exp_f32_e32 v74, v74
	v_exp_f32_e32 v75, v75
	v_exp_f32_e32 v76, v76
	v_exp_f32_e32 v77, v77
	v_add_f32_e32 v74, 1.0, v74
	v_add_f32_e32 v75, 1.0, v75
	v_add_f32_e32 v76, 1.0, v76
	v_add_f32_e32 v77, 1.0, v77
	v_rcp_f32_e32 v74, v74
	v_rcp_f32_e32 v75, v75
	v_rcp_f32_e32 v76, v76
	v_rcp_f32_e32 v77, v77
	v_pk_mul_f32 v[64:65], v[64:65], v[74:75]
	v_pk_mul_f32 v[66:67], v[66:67], v[76:77]
.LBB0_439:
	v_cvt_pk_bf16_f32 v68, v68, v69
	v_cvt_pk_bf16_f32 v69, v70, v71
	v_cvt_pk_bf16_f32 v70, v64, v65
	v_mul_f32_e32 v64, v143, v156
	v_pk_mul_f32 v[62:63], v[62:63], v[64:65] op_sel_hi:[1,0]
	v_pk_mul_f32 v[60:61], v[60:61], v[64:65] op_sel_hi:[1,0]
	v_pk_mul_f32 v[58:59], v[58:59], v[64:65] op_sel_hi:[1,0]
	s_and_b64 vcc, exec, s[44:45]
	v_pk_mul_f32 v[56:57], v[56:57], v[64:65] op_sel_hi:[1,0]
	v_cvt_pk_bf16_f32 v71, v66, v67
	global_store_dwordx4 v[72:73], v[68:71], off offset:256 nt
	s_cbranch_vccnz .LBB0_441
	v_mul_f32_e32 v65, 0xbfb8aa3b, v60
	v_exp_f32_e32 v65, v65
	s_nop 0
	v_add_f32_e32 v65, 1.0, v65
	v_rcp_f32_e32 v66, v65
	v_mul_f32_e32 v65, 0xbfb8aa3b, v61
	v_exp_f32_e32 v65, v65
	s_nop 0
	v_add_f32_e32 v65, 1.0, v65
	v_rcp_f32_e32 v67, v65
	v_mul_f32_e32 v65, 0xbfb8aa3b, v62
	v_exp_f32_e32 v65, v65
	v_pk_mul_f32 v[60:61], v[60:61], v[66:67]
	v_add_f32_e32 v65, 1.0, v65
	v_rcp_f32_e32 v68, v65
	v_mul_f32_e32 v65, 0xbfb8aa3b, v63
	v_exp_f32_e32 v65, v65
	s_nop 0
	v_add_f32_e32 v65, 1.0, v65
	v_rcp_f32_e32 v69, v65
	v_mul_f32_e32 v65, 0xbfb8aa3b, v56
	v_exp_f32_e32 v65, v65
	v_pk_mul_f32 v[62:63], v[62:63], v[68:69]
	v_add_f32_e32 v65, 1.0, v65
	v_rcp_f32_e32 v66, v65
	v_mul_f32_e32 v65, 0xbfb8aa3b, v57
	v_exp_f32_e32 v65, v65
	s_nop 0
	v_add_f32_e32 v65, 1.0, v65
	v_rcp_f32_e32 v67, v65
	v_mul_f32_e32 v65, 0xbfb8aa3b, v58
	v_exp_f32_e32 v65, v65
	v_pk_mul_f32 v[56:57], v[56:57], v[66:67]
	v_add_f32_e32 v65, 1.0, v65
	v_rcp_f32_e32 v68, v65
	v_mul_f32_e32 v65, 0xbfb8aa3b, v59
	v_exp_f32_e32 v65, v65
	s_nop 0
	v_add_f32_e32 v65, 1.0, v65
	v_rcp_f32_e32 v69, v65
	s_nop 0
	v_pk_mul_f32 v[58:59], v[58:59], v[68:69]
.LBB0_441:
	s_mov_b32 s2, 0x100000
	v_cvt_pk_bf16_f32 v60, v60, v61
	v_cvt_pk_bf16_f32 v61, v62, v63
	v_cvt_pk_bf16_f32 v62, v56, v57
	v_add_co_u32_e32 v56, vcc, s2, v120
	v_mov_b32_e32 v65, v64
	s_nop 0
	v_addc_co_u32_e32 v57, vcc, 0, v121, vcc
	v_cvt_pk_bf16_f32 v63, v58, v59
	global_store_dwordx4 v[56:57], v[60:63], off nt
	v_mov_b32_e32 v56, v64
	v_mov_b32_e32 v57, v64
	v_pk_mul_f32 v[54:55], v[54:55], v[56:57]
	v_pk_mul_f32 v[52:53], v[52:53], v[64:65]
	v_pk_mul_f32 v[50:51], v[50:51], v[56:57]
	s_and_b64 vcc, exec, s[44:45]
	v_pk_mul_f32 v[48:49], v[48:49], v[64:65]
	s_cbranch_vccnz .LBB0_443
	v_mul_f32_e32 v56, 0xbfb8aa3b, v52
	v_mul_f32_e32 v57, 0xbfb8aa3b, v53
	v_mul_f32_e32 v58, 0xbfb8aa3b, v54
	v_mul_f32_e32 v59, 0xbfb8aa3b, v55
	v_exp_f32_e32 v56, v56
	v_exp_f32_e32 v57, v57
	v_exp_f32_e32 v58, v58
	v_exp_f32_e32 v59, v59
	v_add_f32_e32 v56, 1.0, v56
	v_add_f32_e32 v57, 1.0, v57
	v_add_f32_e32 v58, 1.0, v58
	v_add_f32_e32 v59, 1.0, v59
	v_rcp_f32_e32 v56, v56
	v_rcp_f32_e32 v57, v57
	v_rcp_f32_e32 v58, v58
	v_rcp_f32_e32 v59, v59
	v_pk_mul_f32 v[52:53], v[52:53], v[56:57]
	v_mul_f32_e32 v56, 0xbfb8aa3b, v48
	v_pk_mul_f32 v[54:55], v[54:55], v[58:59]
	v_mul_f32_e32 v57, 0xbfb8aa3b, v49
	v_mul_f32_e32 v58, 0xbfb8aa3b, v50
	v_mul_f32_e32 v59, 0xbfb8aa3b, v51
	v_exp_f32_e32 v56, v56
	v_exp_f32_e32 v57, v57
	v_exp_f32_e32 v58, v58
	v_exp_f32_e32 v59, v59
	v_add_f32_e32 v56, 1.0, v56
	v_add_f32_e32 v57, 1.0, v57
	v_add_f32_e32 v58, 1.0, v58
	v_add_f32_e32 v59, 1.0, v59
	v_rcp_f32_e32 v56, v56
	v_rcp_f32_e32 v57, v57
	v_rcp_f32_e32 v58, v58
	v_rcp_f32_e32 v59, v59
	v_pk_mul_f32 v[48:49], v[48:49], v[56:57]
	v_pk_mul_f32 v[50:51], v[50:51], v[58:59]
; __device__ __forceinline__ f32x4 silu4(f32x4 v) { return (f32x4){silu1(v[0]), silu1(v[1]), silu1(v[2]), silu1(v[3])}; }
; __device__ __forceinline__ u32x4 pack8(f32x4 v0, f32x4 v1) { u32x4 w; w.x = cvt_pk_bf16(v0[0], v0[1]); w.y = cvt_pk_bf16(v0[2], v0[3]); w.z = cvt_pk_bf16(v1[0], v1[1]); w.w = cvt_pk_bf16(v1[2], v1[3]); return w; }
;     __device__ __forceinline__ void operator()(const f32x4 (&acc)[2][2][4][2], const Unit& u, int wr, int wc, int fr, int fq, const Pre& pre) const {
;     ...
; #pragma unroll
;         for (int ai = 0; ai < 2; ++ai)
; #pragma unroll
;             for (int m = 0; m < 4; ++m) { const int row = row0 + ai * HALF + m * 16; const float r = rs8[ai * 4 + m] * sc;
;                 bf16_t* rowp = O + (size_t)row * 4096 + col0;
; #pragma unroll
;                 for (int bj = 0; bj < 2; ++bj) { f32x4 v0 = acc[ai][bj][m][0] * r, v1 = acc[ai][bj][m][1] * r;
;                     if (act) { v0 = silu4(v0); v1 = silu4(v1); }
;                     *(u32x4*)(rowp + bj * HALF) = pack8(v0, v1); } }
.LBB0_443:
	v_cvt_pk_bf16_f32 v52, v52, v53
	v_cvt_pk_bf16_f32 v53, v54, v55
	v_cvt_pk_bf16_f32 v54, v48, v49
	v_mul_f32_e32 v48, v143, v154
	v_lshl_add_u64 v[56:57], v[120:121], 0, s[16:17]
	v_pk_mul_f32 v[46:47], v[46:47], v[48:49] op_sel_hi:[1,0]
	v_pk_mul_f32 v[44:45], v[44:45], v[48:49] op_sel_hi:[1,0]
	v_pk_mul_f32 v[42:43], v[42:43], v[48:49] op_sel_hi:[1,0]
	s_and_b64 vcc, exec, s[44:45]
	v_pk_mul_f32 v[40:41], v[40:41], v[48:49] op_sel_hi:[1,0]
	v_cvt_pk_bf16_f32 v55, v50, v51
	global_store_dwordx4 v[56:57], v[52:55], off offset:256 nt
	s_cbranch_vccnz .LBB0_445
	v_mul_f32_e32 v49, 0xbfb8aa3b, v44
	v_exp_f32_e32 v49, v49
	s_nop 0
	v_add_f32_e32 v49, 1.0, v49
	v_rcp_f32_e32 v50, v49
	v_mul_f32_e32 v49, 0xbfb8aa3b, v45
	v_exp_f32_e32 v49, v49
	s_nop 0
	v_add_f32_e32 v49, 1.0, v49
	v_rcp_f32_e32 v51, v49
	v_mul_f32_e32 v49, 0xbfb8aa3b, v46
	v_exp_f32_e32 v49, v49
	v_pk_mul_f32 v[44:45], v[44:45], v[50:51]
	v_add_f32_e32 v49, 1.0, v49
	v_rcp_f32_e32 v52, v49
	v_mul_f32_e32 v49, 0xbfb8aa3b, v47
	v_exp_f32_e32 v49, v49
	s_nop 0
	v_add_f32_e32 v49, 1.0, v49
	v_rcp_f32_e32 v53, v49
	v_mul_f32_e32 v49, 0xbfb8aa3b, v40
	v_exp_f32_e32 v49, v49
	v_pk_mul_f32 v[46:47], v[46:47], v[52:53]
	v_add_f32_e32 v49, 1.0, v49
	v_rcp_f32_e32 v50, v49
	v_mul_f32_e32 v49, 0xbfb8aa3b, v41
	v_exp_f32_e32 v49, v49
	s_nop 0
	v_add_f32_e32 v49, 1.0, v49
	v_rcp_f32_e32 v51, v49
	v_mul_f32_e32 v49, 0xbfb8aa3b, v42
	v_exp_f32_e32 v49, v49
	v_pk_mul_f32 v[40:41], v[40:41], v[50:51]
	v_add_f32_e32 v49, 1.0, v49
	v_rcp_f32_e32 v52, v49
	v_mul_f32_e32 v49, 0xbfb8aa3b, v43
	v_exp_f32_e32 v49, v49
	s_nop 0
	v_add_f32_e32 v49, 1.0, v49
	v_rcp_f32_e32 v53, v49
	s_nop 0
	v_pk_mul_f32 v[42:43], v[42:43], v[52:53]
.LBB0_445:
	s_mov_b32 s2, 0x120000
	v_cvt_pk_bf16_f32 v44, v44, v45
	v_cvt_pk_bf16_f32 v45, v46, v47
	v_cvt_pk_bf16_f32 v46, v40, v41
	v_add_co_u32_e32 v40, vcc, s2, v120
	v_mov_b32_e32 v49, v48
	s_nop 0
	v_addc_co_u32_e32 v41, vcc, 0, v121, vcc
	v_cvt_pk_bf16_f32 v47, v42, v43
	global_store_dwordx4 v[40:41], v[44:47], off nt
	v_mov_b32_e32 v40, v48
	v_mov_b32_e32 v41, v48
	v_pk_mul_f32 v[38:39], v[38:39], v[40:41]
	v_pk_mul_f32 v[36:37], v[36:37], v[48:49]
	v_pk_mul_f32 v[34:35], v[34:35], v[40:41]
	s_and_b64 vcc, exec, s[44:45]
	v_pk_mul_f32 v[32:33], v[32:33], v[48:49]
	s_cbranch_vccnz .LBB0_447
	v_mul_f32_e32 v40, 0xbfb8aa3b, v36
	v_mul_f32_e32 v41, 0xbfb8aa3b, v37
	v_mul_f32_e32 v42, 0xbfb8aa3b, v38
	v_mul_f32_e32 v43, 0xbfb8aa3b, v39
	v_exp_f32_e32 v40, v40
	v_exp_f32_e32 v41, v41
	v_exp_f32_e32 v42, v42
	v_exp_f32_e32 v43, v43
	v_add_f32_e32 v40, 1.0, v40
	v_add_f32_e32 v41, 1.0, v41
	v_add_f32_e32 v42, 1.0, v42
	v_add_f32_e32 v43, 1.0, v43
	v_rcp_f32_e32 v40, v40
	v_rcp_f32_e32 v41, v41
	v_rcp_f32_e32 v42, v42
	v_rcp_f32_e32 v43, v43
	v_pk_mul_f32 v[36:37], v[36:37], v[40:41]
	v_mul_f32_e32 v40, 0xbfb8aa3b, v32
	v_pk_mul_f32 v[38:39], v[38:39], v[42:43]
	v_mul_f32_e32 v41, 0xbfb8aa3b, v33
	v_mul_f32_e32 v42, 0xbfb8aa3b, v34
	v_mul_f32_e32 v43, 0xbfb8aa3b, v35
	v_exp_f32_e32 v40, v40
	v_exp_f32_e32 v41, v41
	v_exp_f32_e32 v42, v42
	v_exp_f32_e32 v43, v43
	v_add_f32_e32 v40, 1.0, v40
	v_add_f32_e32 v41, 1.0, v41
	v_add_f32_e32 v42, 1.0, v42
	v_add_f32_e32 v43, 1.0, v43
	v_rcp_f32_e32 v40, v40
	v_rcp_f32_e32 v41, v41
	v_rcp_f32_e32 v42, v42
	v_rcp_f32_e32 v43, v43
	v_pk_mul_f32 v[32:33], v[32:33], v[40:41]
	v_pk_mul_f32 v[34:35], v[34:35], v[42:43]
.LBB0_447:
	s_mov_b64 s[26:27], 0x120000
	v_cvt_pk_bf16_f32 v36, v36, v37
	v_cvt_pk_bf16_f32 v37, v38, v39
	v_cvt_pk_bf16_f32 v38, v32, v33
	v_mul_f32_e32 v32, v143, v146
	v_lshl_add_u64 v[40:41], v[120:121], 0, s[26:27]
	v_pk_mul_f32 v[30:31], v[30:31], v[32:33] op_sel_hi:[1,0]
	v_pk_mul_f32 v[28:29], v[28:29], v[32:33] op_sel_hi:[1,0]
	v_pk_mul_f32 v[26:27], v[26:27], v[32:33] op_sel_hi:[1,0]
	s_and_b64 vcc, exec, s[44:45]
	v_pk_mul_f32 v[24:25], v[24:25], v[32:33] op_sel_hi:[1,0]
	v_cvt_pk_bf16_f32 v39, v34, v35
	global_store_dwordx4 v[40:41], v[36:39], off offset:256 nt
	s_cbranch_vccnz .LBB0_449
	v_mul_f32_e32 v33, 0xbfb8aa3b, v28
	v_exp_f32_e32 v33, v33
	s_nop 0
	v_add_f32_e32 v33, 1.0, v33
	v_rcp_f32_e32 v34, v33
	v_mul_f32_e32 v33, 0xbfb8aa3b, v29
	v_exp_f32_e32 v33, v33
	s_nop 0
	v_add_f32_e32 v33, 1.0, v33
	v_rcp_f32_e32 v35, v33
	v_mul_f32_e32 v33, 0xbfb8aa3b, v30
	v_exp_f32_e32 v33, v33
	v_pk_mul_f32 v[28:29], v[28:29], v[34:35]
	v_add_f32_e32 v33, 1.0, v33
	v_rcp_f32_e32 v36, v33
	v_mul_f32_e32 v33, 0xbfb8aa3b, v31
	v_exp_f32_e32 v33, v33
	s_nop 0
	v_add_f32_e32 v33, 1.0, v33
	v_rcp_f32_e32 v37, v33
	v_mul_f32_e32 v33, 0xbfb8aa3b, v24
	v_exp_f32_e32 v33, v33
	v_pk_mul_f32 v[30:31], v[30:31], v[36:37]
	v_add_f32_e32 v33, 1.0, v33
	v_rcp_f32_e32 v34, v33
	v_mul_f32_e32 v33, 0xbfb8aa3b, v25
	v_exp_f32_e32 v33, v33
	s_nop 0
	v_add_f32_e32 v33, 1.0, v33
	v_rcp_f32_e32 v35, v33
	v_mul_f32_e32 v33, 0xbfb8aa3b, v26
	v_exp_f32_e32 v33, v33
	v_pk_mul_f32 v[24:25], v[24:25], v[34:35]
	v_add_f32_e32 v33, 1.0, v33
	v_rcp_f32_e32 v36, v33
	v_mul_f32_e32 v33, 0xbfb8aa3b, v27
	v_exp_f32_e32 v33, v33
	s_nop 0
	v_add_f32_e32 v33, 1.0, v33
	v_rcp_f32_e32 v37, v33
	s_nop 0
	v_pk_mul_f32 v[26:27], v[26:27], v[36:37]
; __device__ __forceinline__ f32x4 silu4(f32x4 v) { return (f32x4){silu1(v[0]), silu1(v[1]), silu1(v[2]), silu1(v[3])}; }
; __device__ __forceinline__ u32x4 pack8(f32x4 v0, f32x4 v1) { u32x4 w; w.x = cvt_pk_bf16(v0[0], v0[1]); w.y = cvt_pk_bf16(v0[2], v0[3]); w.z = cvt_pk_bf16(v1[0], v1[1]); w.w = cvt_pk_bf16(v1[2], v1[3]); return w; }
;     __device__ __forceinline__ void operator()(const f32x4 (&acc)[2][2][4][2], const Unit& u, int wr, int wc, int fr, int fq, const Pre& pre) const {
;     ...
; #pragma unroll
;         for (int ai = 0; ai < 2; ++ai)
; #pragma unroll
;             for (int m = 0; m < 4; ++m) { const int row = row0 + ai * HALF + m * 16; const float r = rs8[ai * 4 + m] * sc;
;                 bf16_t* rowp = O + (size_t)row * 4096 + col0;
; #pragma unroll
;                 for (int bj = 0; bj < 2; ++bj) { f32x4 v0 = acc[ai][bj][m][0] * r, v1 = acc[ai][bj][m][1] * r;
;                     if (act) { v0 = silu4(v0); v1 = silu4(v1); }
;                     *(u32x4*)(rowp + bj * HALF) = pack8(v0, v1); } }
.LBB0_449:
	s_mov_b32 s2, 0x140000
	v_cvt_pk_bf16_f32 v28, v28, v29
	v_cvt_pk_bf16_f32 v29, v30, v31
	v_cvt_pk_bf16_f32 v30, v24, v25
	v_add_co_u32_e32 v24, vcc, s2, v120
	v_mov_b32_e32 v33, v32
	s_nop 0
	v_addc_co_u32_e32 v25, vcc, 0, v121, vcc
	v_cvt_pk_bf16_f32 v31, v26, v27
	global_store_dwordx4 v[24:25], v[28:31], off nt
	v_mov_b32_e32 v24, v32
	v_mov_b32_e32 v25, v32
	v_pk_mul_f32 v[22:23], v[22:23], v[24:25]
	v_pk_mul_f32 v[20:21], v[20:21], v[32:33]
	v_pk_mul_f32 v[18:19], v[18:19], v[24:25]
	s_and_b64 vcc, exec, s[44:45]
	v_pk_mul_f32 v[16:17], v[16:17], v[32:33]
	s_cbranch_vccnz .LBB0_451
	v_mul_f32_e32 v24, 0xbfb8aa3b, v20
	v_mul_f32_e32 v25, 0xbfb8aa3b, v21
	v_mul_f32_e32 v26, 0xbfb8aa3b, v22
	v_mul_f32_e32 v27, 0xbfb8aa3b, v23
	v_exp_f32_e32 v24, v24
	v_exp_f32_e32 v25, v25
	v_exp_f32_e32 v26, v26
	v_exp_f32_e32 v27, v27
	v_add_f32_e32 v24, 1.0, v24
	v_add_f32_e32 v25, 1.0, v25
	v_add_f32_e32 v26, 1.0, v26
	v_add_f32_e32 v27, 1.0, v27
	v_rcp_f32_e32 v24, v24
	v_rcp_f32_e32 v25, v25
	v_rcp_f32_e32 v26, v26
	v_rcp_f32_e32 v27, v27
	v_pk_mul_f32 v[20:21], v[20:21], v[24:25]
	v_mul_f32_e32 v24, 0xbfb8aa3b, v16
	v_pk_mul_f32 v[22:23], v[22:23], v[26:27]
	v_mul_f32_e32 v25, 0xbfb8aa3b, v17
	v_mul_f32_e32 v26, 0xbfb8aa3b, v18
	v_mul_f32_e32 v27, 0xbfb8aa3b, v19
	v_exp_f32_e32 v24, v24
	v_exp_f32_e32 v25, v25
	v_exp_f32_e32 v26, v26
	v_exp_f32_e32 v27, v27
	v_add_f32_e32 v24, 1.0, v24
	v_add_f32_e32 v25, 1.0, v25
	v_add_f32_e32 v26, 1.0, v26
	v_add_f32_e32 v27, 1.0, v27
	v_rcp_f32_e32 v24, v24
	v_rcp_f32_e32 v25, v25
	v_rcp_f32_e32 v26, v26
	v_rcp_f32_e32 v27, v27
	v_pk_mul_f32 v[16:17], v[16:17], v[24:25]
	v_pk_mul_f32 v[18:19], v[18:19], v[26:27]
.LBB0_451:
	s_mov_b64 s[26:27], 0x140000
	v_cvt_pk_bf16_f32 v20, v20, v21
	v_cvt_pk_bf16_f32 v21, v22, v23
	v_cvt_pk_bf16_f32 v22, v16, v17
	v_mul_f32_e32 v16, v143, v142
	v_lshl_add_u64 v[24:25], v[120:121], 0, s[26:27]
	v_pk_mul_f32 v[14:15], v[14:15], v[16:17] op_sel_hi:[1,0]
	v_pk_mul_f32 v[12:13], v[12:13], v[16:17] op_sel_hi:[1,0]
	v_pk_mul_f32 v[10:11], v[10:11], v[16:17] op_sel_hi:[1,0]
	s_and_b64 vcc, exec, s[44:45]
	v_pk_mul_f32 v[8:9], v[8:9], v[16:17] op_sel_hi:[1,0]
	v_cvt_pk_bf16_f32 v23, v18, v19
	global_store_dwordx4 v[24:25], v[20:23], off offset:256 nt
	s_cbranch_vccnz .LBB0_453
	v_mul_f32_e32 v17, 0xbfb8aa3b, v12
	v_exp_f32_e32 v17, v17
	s_nop 0
	v_add_f32_e32 v17, 1.0, v17
	v_rcp_f32_e32 v18, v17
	v_mul_f32_e32 v17, 0xbfb8aa3b, v13
	v_exp_f32_e32 v17, v17
	s_nop 0
	v_add_f32_e32 v17, 1.0, v17
	v_rcp_f32_e32 v19, v17
	v_mul_f32_e32 v17, 0xbfb8aa3b, v14
	v_exp_f32_e32 v17, v17
	v_pk_mul_f32 v[12:13], v[12:13], v[18:19]
	v_add_f32_e32 v17, 1.0, v17
	v_rcp_f32_e32 v20, v17
	v_mul_f32_e32 v17, 0xbfb8aa3b, v15
	v_exp_f32_e32 v17, v17
	s_nop 0
	v_add_f32_e32 v17, 1.0, v17
	v_rcp_f32_e32 v21, v17
	v_mul_f32_e32 v17, 0xbfb8aa3b, v8
	v_exp_f32_e32 v17, v17
	v_pk_mul_f32 v[14:15], v[14:15], v[20:21]
	v_add_f32_e32 v17, 1.0, v17
	v_rcp_f32_e32 v18, v17
	v_mul_f32_e32 v17, 0xbfb8aa3b, v9
	v_exp_f32_e32 v17, v17
	s_nop 0
	v_add_f32_e32 v17, 1.0, v17
	v_rcp_f32_e32 v19, v17
	v_mul_f32_e32 v17, 0xbfb8aa3b, v10
	v_exp_f32_e32 v17, v17
	v_pk_mul_f32 v[8:9], v[8:9], v[18:19]
	v_add_f32_e32 v17, 1.0, v17
	v_rcp_f32_e32 v20, v17
	v_mul_f32_e32 v17, 0xbfb8aa3b, v11
	v_exp_f32_e32 v17, v17
	s_nop 0
	v_add_f32_e32 v17, 1.0, v17
	v_rcp_f32_e32 v21, v17
	s_nop 0
	v_pk_mul_f32 v[10:11], v[10:11], v[20:21]
.LBB0_453:
	s_mov_b32 s2, 0x160000
	v_cvt_pk_bf16_f32 v12, v12, v13
	v_cvt_pk_bf16_f32 v13, v14, v15
	v_cvt_pk_bf16_f32 v14, v8, v9
	v_add_co_u32_e32 v8, vcc, s2, v120
	v_mov_b32_e32 v17, v16
	s_nop 0
	v_addc_co_u32_e32 v9, vcc, 0, v121, vcc
	v_cvt_pk_bf16_f32 v15, v10, v11
	global_store_dwordx4 v[8:9], v[12:15], off nt
	v_mov_b32_e32 v8, v16
	v_mov_b32_e32 v9, v16
	v_pk_mul_f32 v[6:7], v[6:7], v[8:9]
	v_pk_mul_f32 v[4:5], v[4:5], v[16:17]
	v_pk_mul_f32 v[2:3], v[2:3], v[8:9]
	s_and_b64 vcc, exec, s[44:45]
	v_pk_mul_f32 v[0:1], v[0:1], v[16:17]
	s_cbranch_vccnz .LBB0_455
	v_mul_f32_e32 v8, 0xbfb8aa3b, v4
	v_mul_f32_e32 v9, 0xbfb8aa3b, v5
	v_mul_f32_e32 v10, 0xbfb8aa3b, v6
	v_mul_f32_e32 v11, 0xbfb8aa3b, v7
	v_exp_f32_e32 v8, v8
	v_exp_f32_e32 v9, v9
	v_exp_f32_e32 v10, v10
	v_exp_f32_e32 v11, v11
	v_add_f32_e32 v8, 1.0, v8
	v_add_f32_e32 v9, 1.0, v9
	v_add_f32_e32 v10, 1.0, v10
	v_add_f32_e32 v11, 1.0, v11
	v_rcp_f32_e32 v8, v8
	v_rcp_f32_e32 v9, v9
	v_rcp_f32_e32 v10, v10
	v_rcp_f32_e32 v11, v11
	v_pk_mul_f32 v[4:5], v[4:5], v[8:9]
	v_mul_f32_e32 v8, 0xbfb8aa3b, v0
	v_pk_mul_f32 v[6:7], v[6:7], v[10:11]
	v_mul_f32_e32 v9, 0xbfb8aa3b, v1
	v_mul_f32_e32 v10, 0xbfb8aa3b, v2
	v_mul_f32_e32 v11, 0xbfb8aa3b, v3
	v_exp_f32_e32 v8, v8
	v_exp_f32_e32 v9, v9
	v_exp_f32_e32 v10, v10
	v_exp_f32_e32 v11, v11
	v_add_f32_e32 v8, 1.0, v8
	v_add_f32_e32 v9, 1.0, v9
	v_add_f32_e32 v10, 1.0, v10
	v_add_f32_e32 v11, 1.0, v11
	v_rcp_f32_e32 v8, v8
	v_rcp_f32_e32 v9, v9
	v_rcp_f32_e32 v10, v10
	v_rcp_f32_e32 v11, v11
	v_pk_mul_f32 v[0:1], v[0:1], v[8:9]
	v_pk_mul_f32 v[2:3], v[2:3], v[10:11]
.LBB0_455:
	s_mov_b64 s[26:27], 0x160000
	v_lshl_add_u64 v[8:9], v[120:121], 0, s[26:27]
	s_andn2_b64 vcc, exec, s[42:43]
	s_mov_b64 s[26:27], -1
	v_cvt_pk_bf16_f32 v4, v4, v5
	v_cvt_pk_bf16_f32 v5, v6, v7
	v_cvt_pk_bf16_f32 v6, v0, v1
	v_cvt_pk_bf16_f32 v7, v2, v3
	global_store_dwordx4 v[8:9], v[4:7], off offset:256 nt
	s_cbranch_vccnz .LBB0_406
	s_andn2_b64 vcc, exec, s[0:1]
	s_cbranch_vccnz .LBB0_405
	s_barrier
	s_branch .LBB0_405
